# GEMM phases: LDS-DMA of the even half-step issued before the wait for the fragment reads
# speedup vs baseline: 1.2322x; 1.0026x over previous
; template <int NI> ...
;     ...
;   for (int kt = 0; kt < nk; kt += 2) {
;     G_LOAD(a0, b0, min((kt + 2) * 32, klast));
;     G_COMPUTE(0);
;     G_WRITE(a1, b1, 1);
;     __syncthreads();
;     G_LOAD(a1, b1, min((kt + 3) * 32, klast));
;     G_COMPUTE(1);
;     G_WRITE(a0, b0, 0);
;     __syncthreads();
;   }
; __device__ void phase_inproj(CParams& p, int l, int tm, int tn, char* smem) {
;     ...
;   if (tn < 6) {
;     int cb = (tn & 1) * 128;
;     if (lat && (tn == 2 || tn == 3)) {
;       EPI_LOOP({ p.zfnP[(size_t)(tm * 128 + rl) * 256 + cb + cl] = f2bf(acc[mi][ni][j]); })
;     } else {
;       float* dst = tn < 2 ? p.zs5 : (tn < 4 ? p.zfn : p.zpl);
;       EPI_LOOP({ dst[(size_t)(tbase + rl * tstr) * 256 + cb + cl] = acc[mi][ni][j]; })
.Linpj_pair:
	s_cmp_eq_u32 s53, 14
	s_cselect_b64 s[8:9], s[18:19], s[8:9]
	s_cselect_b32 s98, s99, s98
	v_lshl_add_u32 v236, v132, s98, v136
	v_lshl_add_u32 v237, v133, s98, v137
	v_lshl_add_u32 v238, v134, s98, v136
	v_lshl_add_u32 v239, v135, s98, v137
	s_add_u32 s54, s40, s93
	s_add_u32 m0, s54, 0x0
	s_nop 0
	global_load_lds_dwordx4 v236, s[8:9]
	s_add_u32 m0, s54, 0x400
	s_nop 0
	global_load_lds_dwordx4 v237, s[8:9]
	s_add_u32 m0, s54, 0x800
	s_nop 0
	global_load_lds_dwordx4 v238, s[8:9]
	s_add_u32 m0, s54, 0xc00
	s_nop 0
	global_load_lds_dwordx4 v239, s[8:9]
	s_add_u32 s8, s8, 128
	s_addc_u32 s9, s9, 0
	v_add_u32_e32 v129, s59, v249
	v_add_u32_e32 v131, s62, v251
	s_waitcnt lgkmcnt(0)
	v_mfma_f32_16x16x32_bf16 v[0:3], v[184:187], v[168:171], v[0:3]
	ds_read_b128 v[200:203], v129 offset:0
	v_mfma_f32_16x16x32_bf16 v[4:7], v[188:191], v[168:171], v[4:7]
	ds_read_b128 v[216:219], v131 offset:0
	v_mfma_f32_16x16x32_bf16 v[8:11], v[192:195], v[168:171], v[8:11]
	ds_read_b128 v[204:207], v129 offset:2048
	v_mfma_f32_16x16x32_bf16 v[12:15], v[196:199], v[168:171], v[12:15]
	ds_read_b128 v[220:223], v131 offset:2048
	v_mfma_f32_16x16x32_bf16 v[16:19], v[184:187], v[172:175], v[16:19]
	ds_read_b128 v[208:211], v129 offset:4096
	v_mfma_f32_16x16x32_bf16 v[20:23], v[188:191], v[172:175], v[20:23]
	ds_read_b128 v[228:231], v131 offset:4096
	v_mfma_f32_16x16x32_bf16 v[24:27], v[192:195], v[172:175], v[24:27]
	ds_read_b128 v[212:215], v129 offset:6144
	v_mfma_f32_16x16x32_bf16 v[28:31], v[196:199], v[172:175], v[28:31]
	ds_read_b128 v[232:235], v131 offset:6144
	v_mfma_f32_16x16x32_bf16 v[32:35], v[184:187], v[176:179], v[32:35]
	v_mfma_f32_16x16x32_bf16 v[36:39], v[188:191], v[176:179], v[36:39]
	v_mfma_f32_16x16x32_bf16 v[40:43], v[192:195], v[176:179], v[40:43]
	v_mfma_f32_16x16x32_bf16 v[44:47], v[196:199], v[176:179], v[44:47]
	v_mfma_f32_16x16x32_bf16 v[48:51], v[184:187], v[180:183], v[48:51]
	v_mfma_f32_16x16x32_bf16 v[52:55], v[188:191], v[180:183], v[52:55]
	v_mfma_f32_16x16x32_bf16 v[56:59], v[192:195], v[180:183], v[56:59]
	v_mfma_f32_16x16x32_bf16 v[60:63], v[196:199], v[180:183], v[60:63]
	s_waitcnt vmcnt(4) lgkmcnt(0)
	s_barrier
	s_cmp_eq_u32 s53, 14
	s_cselect_b64 s[12:13], s[6:7], s[12:13]
	s_add_u32 s54, s40, s59
	s_add_u32 m0, s54, 0x0
	s_nop 0
	global_load_lds_dwordx4 v240, s[12:13]
	s_add_u32 m0, s54, 0x400
	s_nop 0
	global_load_lds_dwordx4 v241, s[12:13]
	s_add_u32 m0, s54, 0x800
	s_nop 0
	global_load_lds_dwordx4 v242, s[12:13]
	s_add_u32 m0, s54, 0xc00
	s_nop 0
	global_load_lds_dwordx4 v243, s[12:13]
	s_add_u32 s12, s12, 128
	s_addc_u32 s13, s13, 0
	v_add_u32_e32 v128, s63, v248
	v_add_u32_e32 v130, s92, v250
	v_mfma_f32_16x16x32_bf16 v[0:3], v[216:219], v[200:203], v[0:3]
	ds_read_b128 v[168:171], v128 offset:0
	v_mfma_f32_16x16x32_bf16 v[4:7], v[220:223], v[200:203], v[4:7]
	ds_read_b128 v[184:187], v130 offset:0
	v_mfma_f32_16x16x32_bf16 v[8:11], v[228:231], v[200:203], v[8:11]
	ds_read_b128 v[172:175], v128 offset:2048
	v_mfma_f32_16x16x32_bf16 v[12:15], v[232:235], v[200:203], v[12:15]
	ds_read_b128 v[188:191], v130 offset:2048
	v_mfma_f32_16x16x32_bf16 v[16:19], v[216:219], v[204:207], v[16:19]
	ds_read_b128 v[176:179], v128 offset:4096
	v_mfma_f32_16x16x32_bf16 v[20:23], v[220:223], v[204:207], v[20:23]
	ds_read_b128 v[192:195], v130 offset:4096
	v_mfma_f32_16x16x32_bf16 v[24:27], v[228:231], v[204:207], v[24:27]
	ds_read_b128 v[180:183], v128 offset:6144
	v_mfma_f32_16x16x32_bf16 v[28:31], v[232:235], v[204:207], v[28:31]
	ds_read_b128 v[196:199], v130 offset:6144
	v_mfma_f32_16x16x32_bf16 v[32:35], v[216:219], v[208:211], v[32:35]
	v_mfma_f32_16x16x32_bf16 v[36:39], v[220:223], v[208:211], v[36:39]
	v_mfma_f32_16x16x32_bf16 v[40:43], v[228:231], v[208:211], v[40:43]
	v_mfma_f32_16x16x32_bf16 v[44:47], v[232:235], v[208:211], v[44:47]
	v_mfma_f32_16x16x32_bf16 v[48:51], v[216:219], v[212:215], v[48:51]
	v_mfma_f32_16x16x32_bf16 v[52:55], v[220:223], v[212:215], v[52:55]
	v_mfma_f32_16x16x32_bf16 v[56:59], v[228:231], v[212:215], v[56:59]
	v_mfma_f32_16x16x32_bf16 v[60:63], v[232:235], v[212:215], v[60:63]
	s_mov_b32 s55, s59
	s_mov_b32 s56, s62
	s_mov_b32 s59, s63
	s_mov_b32 s62, s92
	s_mov_b32 s63, s93
	s_mov_b32 s92, s55
	s_mov_b32 s93, s56
	s_add_u32 s53, s53, 1
	s_cmp_lt_u32 s53, 16
	s_cbranch_scc1 .Linpj_pair
	s_lshr_b32 s55, s2, 6
	s_lshl_b32 s55, s55, 13
	s_and_b32 s56, s2, 63
	s_or_b32 s55, s55, s56
	s_lshl_b32 s56, s2, 7
	s_cmp_lt_u32 s2, 128
	s_cselect_b32 s55, s55, s56
	s_cselect_b32 s28, 16, 10
	s_cselect_b32 s58, 1, 0
	s_lshl_b32 s55, s55, 10
	s_cmp_ge_u32 s10, 6
	s_cbranch_scc1 .Linpj_egate
	s_lshr_b32 s56, s10, 1
	s_cmp_eq_u32 s56, 1
	s_cselect_b32 s58, s58, 0
	s_lshl_b32 s56, s56, 3
	s_add_u32 s56, s56, 0x190
	s_cmp_eq_u32 s58, 1
	s_cselect_b32 s56, 0x1e8, s56
	s_load_dwordx2 s[24:25], s[20:21], s56
	s_and_b32 s57, s10, 1
	s_cmp_eq_u32 s58, 1
	s_cbranch_scc1 .Linpj_ebf16
	s_lshl_b32 s57, s57, 9
	s_add_u32 s55, s55, s57
	v_lshl_add_u32 v142, v138, s28, v139
	s_lshl_b32 s57, 16, s28
	s_nop 15
	s_nop 7
	s_waitcnt lgkmcnt(0)
	s_add_u32 s22, s24, s55
	s_addc_u32 s23, s25, 0
	global_store_dwordx4 v142, v[0:3], s[22:23] offset:0
	global_store_dwordx4 v142, v[4:7], s[22:23] offset:64
	global_store_dwordx4 v142, v[8:11], s[22:23] offset:128
	global_store_dwordx4 v142, v[12:15], s[22:23] offset:192
	s_add_u32 s22, s22, s57
	s_addc_u32 s23, s23, 0
	global_store_dwordx4 v142, v[16:19], s[22:23] offset:0
	global_store_dwordx4 v142, v[20:23], s[22:23] offset:64
	global_store_dwordx4 v142, v[24:27], s[22:23] offset:128
	global_store_dwordx4 v142, v[28:31], s[22:23] offset:192
	s_add_u32 s22, s22, s57
	s_addc_u32 s23, s23, 0
	global_store_dwordx4 v142, v[32:35], s[22:23] offset:0
	global_store_dwordx4 v142, v[36:39], s[22:23] offset:64
	global_store_dwordx4 v142, v[40:43], s[22:23] offset:128
	global_store_dwordx4 v142, v[44:47], s[22:23] offset:192
	s_add_u32 s22, s22, s57
	s_addc_u32 s23, s23, 0
	global_store_dwordx4 v142, v[48:51], s[22:23] offset:0
	global_store_dwordx4 v142, v[52:55], s[22:23] offset:64
	global_store_dwordx4 v142, v[56:59], s[22:23] offset:128
	global_store_dwordx4 v142, v[60:63], s[22:23] offset:192
	s_branch .Linpj_edone

; __device__ __forceinline__ float bf2f(bf16_t b) { return __uint_as_float(((unsigned)b) << 16); }
; __device__ __forceinline__ float sigmoidf_(float v) { return 1.f / (1.f + __expf(-v)); }
; template <int NI> ...
;     ...
;   for (int kt = 0; kt < nk; kt += 2) {
;     G_LOAD(a0, b0, min((kt + 2) * 32, klast));
;     G_COMPUTE(0);
;     G_WRITE(a1, b1, 1);
;     __syncthreads();
;     G_LOAD(a1, b1, min((kt + 3) * 32, klast));
;     G_COMPUTE(1);
;     G_WRITE(a0, b0, 0);
;     __syncthreads();
;   }
; __device__ void phase_small(CParams& p, int l, int item, char* smem) {
;     ...
;   if (which == 0) {
;     EPI_LOOP({
;       float y = bf2f(p.ys[(size_t)(row0 + rl) * 256 + col0 + cl]);
;       p.br[(size_t)(row0 + rl) * 1024 + col0 + cl] = f2bf(y * sigmoidf_(acc[mi][ni][j]));
;     })
.Lsml_pair:
	s_cmp_eq_u32 s53, 2
	s_cselect_b64 s[12:13], s[22:23], s[12:13]
	s_add_u32 s54, s44, s93
	s_add_u32 m0, s54, 0x0
	s_nop 0
	global_load_lds_dwordx4 v236, s[12:13]
	s_add_u32 m0, s54, 0x400
	s_nop 0
	global_load_lds_dwordx4 v237, s[12:13]
	s_add_u32 m0, s54, 0x800
	s_nop 0
	global_load_lds_dwordx4 v238, s[12:13]
	s_add_u32 m0, s54, 0xc00
	s_nop 0
	global_load_lds_dwordx4 v239, s[12:13]
	s_add_u32 s12, s12, 128
	s_addc_u32 s13, s13, 0
	v_add_u32_e32 v129, s59, v249
	v_add_u32_e32 v131, s62, v251
	s_waitcnt lgkmcnt(0)
	v_mfma_f32_16x16x32_bf16 v[0:3], v[184:187], v[168:171], v[0:3]
	ds_read_b128 v[200:203], v129 offset:0
	v_mfma_f32_16x16x32_bf16 v[4:7], v[188:191], v[168:171], v[4:7]
	ds_read_b128 v[216:219], v131 offset:0
	v_mfma_f32_16x16x32_bf16 v[8:11], v[192:195], v[168:171], v[8:11]
	ds_read_b128 v[204:207], v129 offset:2048
	v_mfma_f32_16x16x32_bf16 v[12:15], v[196:199], v[168:171], v[12:15]
	ds_read_b128 v[220:223], v131 offset:512
	v_mfma_f32_16x16x32_bf16 v[16:19], v[184:187], v[172:175], v[16:19]
	ds_read_b128 v[208:211], v129 offset:4096
	v_mfma_f32_16x16x32_bf16 v[20:23], v[188:191], v[172:175], v[20:23]
	ds_read_b128 v[228:231], v131 offset:1024
	v_mfma_f32_16x16x32_bf16 v[24:27], v[192:195], v[172:175], v[24:27]
	ds_read_b128 v[212:215], v129 offset:6144
	v_mfma_f32_16x16x32_bf16 v[28:31], v[196:199], v[172:175], v[28:31]
	ds_read_b128 v[232:235], v131 offset:1536
	v_mfma_f32_16x16x32_bf16 v[32:35], v[184:187], v[176:179], v[32:35]
	v_mfma_f32_16x16x32_bf16 v[36:39], v[188:191], v[176:179], v[36:39]
	v_mfma_f32_16x16x32_bf16 v[40:43], v[192:195], v[176:179], v[40:43]
	v_mfma_f32_16x16x32_bf16 v[44:47], v[196:199], v[176:179], v[44:47]
	v_mfma_f32_16x16x32_bf16 v[48:51], v[184:187], v[180:183], v[48:51]
	v_mfma_f32_16x16x32_bf16 v[52:55], v[188:191], v[180:183], v[52:55]
	v_mfma_f32_16x16x32_bf16 v[56:59], v[192:195], v[180:183], v[56:59]
	v_mfma_f32_16x16x32_bf16 v[60:63], v[196:199], v[180:183], v[60:63]
	s_waitcnt vmcnt(4) lgkmcnt(0)
	s_barrier
	s_cmp_eq_u32 s53, 2
	s_cselect_b64 s[18:19], s[24:25], s[18:19]
	s_add_u32 s54, s44, s59
	s_add_u32 m0, s54, 0x0
	s_nop 0
	global_load_lds_dwordx4 v240, s[18:19]
	s_add_u32 m0, s54, 0x400
	s_nop 0
	global_load_lds_dwordx4 v241, s[18:19]
	s_add_u32 m0, s54, 0x800
	s_nop 0
	global_load_lds_dwordx4 v242, s[18:19]
	s_add_u32 m0, s54, 0xc00
	s_nop 0
	global_load_lds_dwordx4 v243, s[18:19]
	s_add_u32 s18, s18, 128
	s_addc_u32 s19, s19, 0
	v_add_u32_e32 v128, s63, v248
	v_add_u32_e32 v130, s92, v250
	v_mfma_f32_16x16x32_bf16 v[0:3], v[216:219], v[200:203], v[0:3]
	ds_read_b128 v[168:171], v128 offset:0
	v_mfma_f32_16x16x32_bf16 v[4:7], v[220:223], v[200:203], v[4:7]
	ds_read_b128 v[184:187], v130 offset:0
	v_mfma_f32_16x16x32_bf16 v[8:11], v[228:231], v[200:203], v[8:11]
	ds_read_b128 v[172:175], v128 offset:2048
	v_mfma_f32_16x16x32_bf16 v[12:15], v[232:235], v[200:203], v[12:15]
	ds_read_b128 v[188:191], v130 offset:512
	v_mfma_f32_16x16x32_bf16 v[16:19], v[216:219], v[204:207], v[16:19]
	ds_read_b128 v[176:179], v128 offset:4096
	v_mfma_f32_16x16x32_bf16 v[20:23], v[220:223], v[204:207], v[20:23]
	ds_read_b128 v[192:195], v130 offset:1024
	v_mfma_f32_16x16x32_bf16 v[24:27], v[228:231], v[204:207], v[24:27]
	ds_read_b128 v[180:183], v128 offset:6144
	v_mfma_f32_16x16x32_bf16 v[28:31], v[232:235], v[204:207], v[28:31]
	ds_read_b128 v[196:199], v130 offset:1536
	v_mfma_f32_16x16x32_bf16 v[32:35], v[216:219], v[208:211], v[32:35]
	v_mfma_f32_16x16x32_bf16 v[36:39], v[220:223], v[208:211], v[36:39]
	v_mfma_f32_16x16x32_bf16 v[40:43], v[228:231], v[208:211], v[40:43]
	v_mfma_f32_16x16x32_bf16 v[44:47], v[232:235], v[208:211], v[44:47]
	v_mfma_f32_16x16x32_bf16 v[48:51], v[216:219], v[212:215], v[48:51]
	v_mfma_f32_16x16x32_bf16 v[52:55], v[220:223], v[212:215], v[52:55]
	v_mfma_f32_16x16x32_bf16 v[56:59], v[228:231], v[212:215], v[56:59]
	v_mfma_f32_16x16x32_bf16 v[60:63], v[232:235], v[212:215], v[60:63]
	s_mov_b32 s55, s59
	s_mov_b32 s56, s62
	s_mov_b32 s59, s63
	s_mov_b32 s62, s92
	s_mov_b32 s63, s93
	s_mov_b32 s92, s55
	s_mov_b32 s93, s56
	s_add_u32 s53, s53, 1
	s_cmp_lt_u32 s53, 4
	s_cbranch_scc1 .Lsml_pair
	s_cmp_lg_u32 s1, 0
	s_cbranch_scc1 .Lsml_eplain
	s_nop 7
	v_mul_f32_e32 v96, 0xbfb8aa3b, v0
	v_mul_f32_e32 v97, 0xbfb8aa3b, v1
	v_mul_f32_e32 v98, 0xbfb8aa3b, v2
	v_mul_f32_e32 v99, 0xbfb8aa3b, v3
	v_mul_f32_e32 v100, 0xbfb8aa3b, v4
	v_mul_f32_e32 v101, 0xbfb8aa3b, v5
	v_mul_f32_e32 v102, 0xbfb8aa3b, v6
	v_mul_f32_e32 v103, 0xbfb8aa3b, v7
	v_mul_f32_e32 v104, 0xbfb8aa3b, v8
	v_mul_f32_e32 v105, 0xbfb8aa3b, v9
	v_mul_f32_e32 v106, 0xbfb8aa3b, v10
	v_mul_f32_e32 v107, 0xbfb8aa3b, v11
	v_mul_f32_e32 v108, 0xbfb8aa3b, v12
	v_mul_f32_e32 v109, 0xbfb8aa3b, v13
	v_mul_f32_e32 v110, 0xbfb8aa3b, v14
	v_mul_f32_e32 v111, 0xbfb8aa3b, v15
	v_exp_f32_e32 v96, v96
	v_exp_f32_e32 v97, v97
	v_exp_f32_e32 v98, v98
	v_exp_f32_e32 v99, v99
	v_exp_f32_e32 v100, v100
	v_exp_f32_e32 v101, v101
	v_exp_f32_e32 v102, v102
	v_exp_f32_e32 v103, v103
	v_exp_f32_e32 v104, v104
	v_exp_f32_e32 v105, v105
	v_exp_f32_e32 v106, v106
	v_exp_f32_e32 v107, v107
	v_exp_f32_e32 v108, v108
	v_exp_f32_e32 v109, v109
	v_exp_f32_e32 v110, v110
	v_exp_f32_e32 v111, v111
	v_add_f32_e32 v96, 1.0, v96
	v_add_f32_e32 v97, 1.0, v97
	v_add_f32_e32 v98, 1.0, v98
	v_add_f32_e32 v99, 1.0, v99
	v_add_f32_e32 v100, 1.0, v100
	v_add_f32_e32 v101, 1.0, v101
	v_add_f32_e32 v102, 1.0, v102
	v_add_f32_e32 v103, 1.0, v103
	v_add_f32_e32 v104, 1.0, v104
	v_add_f32_e32 v105, 1.0, v105
	v_add_f32_e32 v106, 1.0, v106
	v_add_f32_e32 v107, 1.0, v107
	v_add_f32_e32 v108, 1.0, v108
	v_add_f32_e32 v109, 1.0, v109
	v_add_f32_e32 v110, 1.0, v110
	v_add_f32_e32 v111, 1.0, v111
	v_rcp_f32_e32 v96, v96
	v_rcp_f32_e32 v97, v97
	v_rcp_f32_e32 v98, v98
	v_rcp_f32_e32 v99, v99
	v_rcp_f32_e32 v100, v100
	v_rcp_f32_e32 v101, v101
	v_rcp_f32_e32 v102, v102
	v_rcp_f32_e32 v103, v103
	v_rcp_f32_e32 v104, v104
	v_rcp_f32_e32 v105, v105
	v_rcp_f32_e32 v106, v106
	v_rcp_f32_e32 v107, v107
	v_rcp_f32_e32 v108, v108
	v_rcp_f32_e32 v109, v109
	v_rcp_f32_e32 v110, v110
	v_rcp_f32_e32 v111, v111
	s_waitcnt vmcnt(8)
; __device__ __forceinline__ float bf2f(bf16_t b) { return __uint_as_float(((unsigned)b) << 16); }
; __device__ __forceinline__ float sigmoidf_(float v) { return 1.f / (1.f + __expf(-v)); }
; __device__ void phase_small(CParams& p, int l, int item, char* smem) {
;     ...
;   if (which == 0) {
;     EPI_LOOP({
;       float y = bf2f(p.ys[(size_t)(row0 + rl) * 256 + col0 + cl]);
;       p.br[(size_t)(row0 + rl) * 1024 + col0 + cl] = f2bf(y * sigmoidf_(acc[mi][ni][j]));
;     })
	v_lshlrev_b32_e32 v112, 16, v64
	v_and_b32_e32 v113, 0xffff0000, v64
	v_lshlrev_b32_e32 v114, 16, v65
	v_and_b32_e32 v115, 0xffff0000, v65
	v_lshlrev_b32_e32 v116, 16, v66
	v_and_b32_e32 v117, 0xffff0000, v66
	v_lshlrev_b32_e32 v118, 16, v67
	v_and_b32_e32 v119, 0xffff0000, v67
	v_lshlrev_b32_e32 v120, 16, v68
	v_and_b32_e32 v121, 0xffff0000, v68
	v_lshlrev_b32_e32 v122, 16, v69
	v_and_b32_e32 v123, 0xffff0000, v69
	v_lshlrev_b32_e32 v124, 16, v70
	v_and_b32_e32 v125, 0xffff0000, v70
	v_lshlrev_b32_e32 v126, 16, v71
	v_and_b32_e32 v127, 0xffff0000, v71
	v_mul_f32_e32 v96, v96, v112
	v_mul_f32_e32 v97, v97, v113
	v_mul_f32_e32 v98, v98, v114
	v_mul_f32_e32 v99, v99, v115
	v_mul_f32_e32 v100, v100, v116
	v_mul_f32_e32 v101, v101, v117
	v_mul_f32_e32 v102, v102, v118
	v_mul_f32_e32 v103, v103, v119
	v_mul_f32_e32 v104, v104, v120
	v_mul_f32_e32 v105, v105, v121
	v_mul_f32_e32 v106, v106, v122
	v_mul_f32_e32 v107, v107, v123
	v_mul_f32_e32 v108, v108, v124
	v_mul_f32_e32 v109, v109, v125
	v_mul_f32_e32 v110, v110, v126
	v_mul_f32_e32 v111, v111, v127
	v_cvt_pk_bf16_f32 v200, v96, v97
	v_cvt_pk_bf16_f32 v201, v98, v99
	v_cvt_pk_bf16_f32 v202, v100, v101
	v_cvt_pk_bf16_f32 v203, v102, v103
	v_cvt_pk_bf16_f32 v204, v104, v105
	v_cvt_pk_bf16_f32 v205, v106, v107
	v_cvt_pk_bf16_f32 v206, v108, v109
	v_cvt_pk_bf16_f32 v207, v110, v111
	v_mul_f32_e32 v96, 0xbfb8aa3b, v16
	v_mul_f32_e32 v97, 0xbfb8aa3b, v17
	v_mul_f32_e32 v98, 0xbfb8aa3b, v18
	v_mul_f32_e32 v99, 0xbfb8aa3b, v19
	v_mul_f32_e32 v100, 0xbfb8aa3b, v20
	v_mul_f32_e32 v101, 0xbfb8aa3b, v21
	v_mul_f32_e32 v102, 0xbfb8aa3b, v22
	v_mul_f32_e32 v103, 0xbfb8aa3b, v23
	v_mul_f32_e32 v104, 0xbfb8aa3b, v24
	v_mul_f32_e32 v105, 0xbfb8aa3b, v25
	v_mul_f32_e32 v106, 0xbfb8aa3b, v26
	v_mul_f32_e32 v107, 0xbfb8aa3b, v27
	v_mul_f32_e32 v108, 0xbfb8aa3b, v28
	v_mul_f32_e32 v109, 0xbfb8aa3b, v29
	v_mul_f32_e32 v110, 0xbfb8aa3b, v30
	v_mul_f32_e32 v111, 0xbfb8aa3b, v31
	v_exp_f32_e32 v96, v96
	v_exp_f32_e32 v97, v97
	v_exp_f32_e32 v98, v98
	v_exp_f32_e32 v99, v99
	v_exp_f32_e32 v100, v100
	v_exp_f32_e32 v101, v101
	v_exp_f32_e32 v102, v102
	v_exp_f32_e32 v103, v103
	v_exp_f32_e32 v104, v104
	v_exp_f32_e32 v105, v105
	v_exp_f32_e32 v106, v106
	v_exp_f32_e32 v107, v107
	v_exp_f32_e32 v108, v108
	v_exp_f32_e32 v109, v109
	v_exp_f32_e32 v110, v110
	v_exp_f32_e32 v111, v111
	v_add_f32_e32 v96, 1.0, v96
	v_add_f32_e32 v97, 1.0, v97
	v_add_f32_e32 v98, 1.0, v98
	v_add_f32_e32 v99, 1.0, v99
	v_add_f32_e32 v100, 1.0, v100
	v_add_f32_e32 v101, 1.0, v101
	v_add_f32_e32 v102, 1.0, v102
	v_add_f32_e32 v103, 1.0, v103
	v_add_f32_e32 v104, 1.0, v104
	v_add_f32_e32 v105, 1.0, v105
	v_add_f32_e32 v106, 1.0, v106
	v_add_f32_e32 v107, 1.0, v107
	v_add_f32_e32 v108, 1.0, v108
	v_add_f32_e32 v109, 1.0, v109
	v_add_f32_e32 v110, 1.0, v110
	v_add_f32_e32 v111, 1.0, v111
	v_rcp_f32_e32 v96, v96
	v_rcp_f32_e32 v97, v97
	v_rcp_f32_e32 v98, v98
	v_rcp_f32_e32 v99, v99
	v_rcp_f32_e32 v100, v100
	v_rcp_f32_e32 v101, v101
	v_rcp_f32_e32 v102, v102
	v_rcp_f32_e32 v103, v103
	v_rcp_f32_e32 v104, v104
	v_rcp_f32_e32 v105, v105
	v_rcp_f32_e32 v106, v106
	v_rcp_f32_e32 v107, v107
	v_rcp_f32_e32 v108, v108
	v_rcp_f32_e32 v109, v109
	v_rcp_f32_e32 v110, v110
	v_rcp_f32_e32 v111, v111
	v_lshlrev_b32_e32 v112, 16, v72
	v_and_b32_e32 v113, 0xffff0000, v72
	v_lshlrev_b32_e32 v114, 16, v73
	v_and_b32_e32 v115, 0xffff0000, v73
	v_lshlrev_b32_e32 v116, 16, v74
	v_and_b32_e32 v117, 0xffff0000, v74
	v_lshlrev_b32_e32 v118, 16, v75
	v_and_b32_e32 v119, 0xffff0000, v75
	v_lshlrev_b32_e32 v120, 16, v76
	v_and_b32_e32 v121, 0xffff0000, v76
	v_lshlrev_b32_e32 v122, 16, v77
	v_and_b32_e32 v123, 0xffff0000, v77
	v_lshlrev_b32_e32 v124, 16, v78
	v_and_b32_e32 v125, 0xffff0000, v78
	v_lshlrev_b32_e32 v126, 16, v79
	v_and_b32_e32 v127, 0xffff0000, v79
	v_mul_f32_e32 v96, v96, v112
	v_mul_f32_e32 v97, v97, v113
	v_mul_f32_e32 v98, v98, v114
	v_mul_f32_e32 v99, v99, v115
	v_mul_f32_e32 v100, v100, v116
	v_mul_f32_e32 v101, v101, v117
	v_mul_f32_e32 v102, v102, v118
	v_mul_f32_e32 v103, v103, v119
	v_mul_f32_e32 v104, v104, v120
	v_mul_f32_e32 v105, v105, v121
	v_mul_f32_e32 v106, v106, v122
	v_mul_f32_e32 v107, v107, v123
	v_mul_f32_e32 v108, v108, v124
	v_mul_f32_e32 v109, v109, v125
	v_mul_f32_e32 v110, v110, v126
	v_mul_f32_e32 v111, v111, v127
	v_cvt_pk_bf16_f32 v208, v96, v97
	v_cvt_pk_bf16_f32 v209, v98, v99
	v_cvt_pk_bf16_f32 v210, v100, v101
	v_cvt_pk_bf16_f32 v211, v102, v103
	v_cvt_pk_bf16_f32 v212, v104, v105
	v_cvt_pk_bf16_f32 v213, v106, v107
	v_cvt_pk_bf16_f32 v214, v108, v109
	v_cvt_pk_bf16_f32 v215, v110, v111
	v_mul_f32_e32 v96, 0xbfb8aa3b, v32
	v_mul_f32_e32 v97, 0xbfb8aa3b, v33
	v_mul_f32_e32 v98, 0xbfb8aa3b, v34
	v_mul_f32_e32 v99, 0xbfb8aa3b, v35
	v_mul_f32_e32 v100, 0xbfb8aa3b, v36
	v_mul_f32_e32 v101, 0xbfb8aa3b, v37
	v_mul_f32_e32 v102, 0xbfb8aa3b, v38
	v_mul_f32_e32 v103, 0xbfb8aa3b, v39
	v_mul_f32_e32 v104, 0xbfb8aa3b, v40
	v_mul_f32_e32 v105, 0xbfb8aa3b, v41
	v_mul_f32_e32 v106, 0xbfb8aa3b, v42
	v_mul_f32_e32 v107, 0xbfb8aa3b, v43
	v_mul_f32_e32 v108, 0xbfb8aa3b, v44
	v_mul_f32_e32 v109, 0xbfb8aa3b, v45
	v_mul_f32_e32 v110, 0xbfb8aa3b, v46
	v_mul_f32_e32 v111, 0xbfb8aa3b, v47
	v_exp_f32_e32 v96, v96
	v_exp_f32_e32 v97, v97
	v_exp_f32_e32 v98, v98
	v_exp_f32_e32 v99, v99
	v_exp_f32_e32 v100, v100
	v_exp_f32_e32 v101, v101
	v_exp_f32_e32 v102, v102
	v_exp_f32_e32 v103, v103
	v_exp_f32_e32 v104, v104
	v_exp_f32_e32 v105, v105
	v_exp_f32_e32 v106, v106
	v_exp_f32_e32 v107, v107
	v_exp_f32_e32 v108, v108
	v_exp_f32_e32 v109, v109
	v_exp_f32_e32 v110, v110
	v_exp_f32_e32 v111, v111
	v_add_f32_e32 v96, 1.0, v96
	v_add_f32_e32 v97, 1.0, v97
; __device__ __forceinline__ float bf2f(bf16_t b) { return __uint_as_float(((unsigned)b) << 16); }
; __device__ __forceinline__ float sigmoidf_(float v) { return 1.f / (1.f + __expf(-v)); }
; __device__ void phase_small(CParams& p, int l, int item, char* smem) {
;     ...
;   if (which == 0) {
;     EPI_LOOP({
;       float y = bf2f(p.ys[(size_t)(row0 + rl) * 256 + col0 + cl]);
;       p.br[(size_t)(row0 + rl) * 1024 + col0 + cl] = f2bf(y * sigmoidf_(acc[mi][ni][j]));
;     })
	v_add_f32_e32 v98, 1.0, v98
	v_add_f32_e32 v99, 1.0, v99
	v_add_f32_e32 v100, 1.0, v100
	v_add_f32_e32 v101, 1.0, v101
	v_add_f32_e32 v102, 1.0, v102
	v_add_f32_e32 v103, 1.0, v103
	v_add_f32_e32 v104, 1.0, v104
	v_add_f32_e32 v105, 1.0, v105
	v_add_f32_e32 v106, 1.0, v106
	v_add_f32_e32 v107, 1.0, v107
	v_add_f32_e32 v108, 1.0, v108
	v_add_f32_e32 v109, 1.0, v109
	v_add_f32_e32 v110, 1.0, v110
	v_add_f32_e32 v111, 1.0, v111
	v_rcp_f32_e32 v96, v96
	v_rcp_f32_e32 v97, v97
	v_rcp_f32_e32 v98, v98
	v_rcp_f32_e32 v99, v99
	v_rcp_f32_e32 v100, v100
	v_rcp_f32_e32 v101, v101
	v_rcp_f32_e32 v102, v102
	v_rcp_f32_e32 v103, v103
	v_rcp_f32_e32 v104, v104
	v_rcp_f32_e32 v105, v105
	v_rcp_f32_e32 v106, v106
	v_rcp_f32_e32 v107, v107
	v_rcp_f32_e32 v108, v108
	v_rcp_f32_e32 v109, v109
	v_rcp_f32_e32 v110, v110
	v_rcp_f32_e32 v111, v111
	v_lshlrev_b32_e32 v112, 16, v80
	v_and_b32_e32 v113, 0xffff0000, v80
	v_lshlrev_b32_e32 v114, 16, v81
	v_and_b32_e32 v115, 0xffff0000, v81
	v_lshlrev_b32_e32 v116, 16, v82
	v_and_b32_e32 v117, 0xffff0000, v82
	v_lshlrev_b32_e32 v118, 16, v83
	v_and_b32_e32 v119, 0xffff0000, v83
	v_lshlrev_b32_e32 v120, 16, v84
	v_and_b32_e32 v121, 0xffff0000, v84
	v_lshlrev_b32_e32 v122, 16, v85
	v_and_b32_e32 v123, 0xffff0000, v85
	v_lshlrev_b32_e32 v124, 16, v86
	v_and_b32_e32 v125, 0xffff0000, v86
	v_lshlrev_b32_e32 v126, 16, v87
	v_and_b32_e32 v127, 0xffff0000, v87
	v_mul_f32_e32 v96, v96, v112
	v_mul_f32_e32 v97, v97, v113
	v_mul_f32_e32 v98, v98, v114
	v_mul_f32_e32 v99, v99, v115
	v_mul_f32_e32 v100, v100, v116
	v_mul_f32_e32 v101, v101, v117
	v_mul_f32_e32 v102, v102, v118
	v_mul_f32_e32 v103, v103, v119
	v_mul_f32_e32 v104, v104, v120
	v_mul_f32_e32 v105, v105, v121
	v_mul_f32_e32 v106, v106, v122
	v_mul_f32_e32 v107, v107, v123
	v_mul_f32_e32 v108, v108, v124
	v_mul_f32_e32 v109, v109, v125
	v_mul_f32_e32 v110, v110, v126
	v_mul_f32_e32 v111, v111, v127
	v_cvt_pk_bf16_f32 v216, v96, v97
	v_cvt_pk_bf16_f32 v217, v98, v99
	v_cvt_pk_bf16_f32 v218, v100, v101
	v_cvt_pk_bf16_f32 v219, v102, v103
	v_cvt_pk_bf16_f32 v220, v104, v105
	v_cvt_pk_bf16_f32 v221, v106, v107
	v_cvt_pk_bf16_f32 v222, v108, v109
	v_cvt_pk_bf16_f32 v223, v110, v111
	v_mul_f32_e32 v96, 0xbfb8aa3b, v48
	v_mul_f32_e32 v97, 0xbfb8aa3b, v49
	v_mul_f32_e32 v98, 0xbfb8aa3b, v50
	v_mul_f32_e32 v99, 0xbfb8aa3b, v51
	v_mul_f32_e32 v100, 0xbfb8aa3b, v52
	v_mul_f32_e32 v101, 0xbfb8aa3b, v53
	v_mul_f32_e32 v102, 0xbfb8aa3b, v54
	v_mul_f32_e32 v103, 0xbfb8aa3b, v55
	v_mul_f32_e32 v104, 0xbfb8aa3b, v56
	v_mul_f32_e32 v105, 0xbfb8aa3b, v57
	v_mul_f32_e32 v106, 0xbfb8aa3b, v58
	v_mul_f32_e32 v107, 0xbfb8aa3b, v59
	v_mul_f32_e32 v108, 0xbfb8aa3b, v60
	v_mul_f32_e32 v109, 0xbfb8aa3b, v61
	v_mul_f32_e32 v110, 0xbfb8aa3b, v62
	v_mul_f32_e32 v111, 0xbfb8aa3b, v63
	v_exp_f32_e32 v96, v96
	v_exp_f32_e32 v97, v97
	v_exp_f32_e32 v98, v98
	v_exp_f32_e32 v99, v99
	v_exp_f32_e32 v100, v100
	v_exp_f32_e32 v101, v101
	v_exp_f32_e32 v102, v102
	v_exp_f32_e32 v103, v103
	v_exp_f32_e32 v104, v104
	v_exp_f32_e32 v105, v105
	v_exp_f32_e32 v106, v106
	v_exp_f32_e32 v107, v107
	v_exp_f32_e32 v108, v108
	v_exp_f32_e32 v109, v109
	v_exp_f32_e32 v110, v110
	v_exp_f32_e32 v111, v111
	v_add_f32_e32 v96, 1.0, v96
	v_add_f32_e32 v97, 1.0, v97
	v_add_f32_e32 v98, 1.0, v98
	v_add_f32_e32 v99, 1.0, v99
	v_add_f32_e32 v100, 1.0, v100
	v_add_f32_e32 v101, 1.0, v101
	v_add_f32_e32 v102, 1.0, v102
	v_add_f32_e32 v103, 1.0, v103
	v_add_f32_e32 v104, 1.0, v104
	v_add_f32_e32 v105, 1.0, v105
	v_add_f32_e32 v106, 1.0, v106
	v_add_f32_e32 v107, 1.0, v107
	v_add_f32_e32 v108, 1.0, v108
	v_add_f32_e32 v109, 1.0, v109
	v_add_f32_e32 v110, 1.0, v110
	v_add_f32_e32 v111, 1.0, v111
	v_rcp_f32_e32 v96, v96
	v_rcp_f32_e32 v97, v97
	v_rcp_f32_e32 v98, v98
	v_rcp_f32_e32 v99, v99
	v_rcp_f32_e32 v100, v100
	v_rcp_f32_e32 v101, v101
	v_rcp_f32_e32 v102, v102
	v_rcp_f32_e32 v103, v103
	v_rcp_f32_e32 v104, v104
	v_rcp_f32_e32 v105, v105
	v_rcp_f32_e32 v106, v106
	v_rcp_f32_e32 v107, v107
	v_rcp_f32_e32 v108, v108
	v_rcp_f32_e32 v109, v109
	v_rcp_f32_e32 v110, v110
	v_rcp_f32_e32 v111, v111
	v_lshlrev_b32_e32 v112, 16, v88
	v_and_b32_e32 v113, 0xffff0000, v88
	v_lshlrev_b32_e32 v114, 16, v89
	v_and_b32_e32 v115, 0xffff0000, v89
	v_lshlrev_b32_e32 v116, 16, v90
	v_and_b32_e32 v117, 0xffff0000, v90
	v_lshlrev_b32_e32 v118, 16, v91
	v_and_b32_e32 v119, 0xffff0000, v91
	v_lshlrev_b32_e32 v120, 16, v92
	v_and_b32_e32 v121, 0xffff0000, v92
	v_lshlrev_b32_e32 v122, 16, v93
	v_and_b32_e32 v123, 0xffff0000, v93
	v_lshlrev_b32_e32 v124, 16, v94
	v_and_b32_e32 v125, 0xffff0000, v94
	v_lshlrev_b32_e32 v126, 16, v95
	v_and_b32_e32 v127, 0xffff0000, v95
	v_mul_f32_e32 v96, v96, v112
	v_mul_f32_e32 v97, v97, v113
	v_mul_f32_e32 v98, v98, v114
	v_mul_f32_e32 v99, v99, v115
	v_mul_f32_e32 v100, v100, v116
	v_mul_f32_e32 v101, v101, v117
	v_mul_f32_e32 v102, v102, v118
	v_mul_f32_e32 v103, v103, v119
	v_mul_f32_e32 v104, v104, v120
	v_mul_f32_e32 v105, v105, v121
	v_mul_f32_e32 v106, v106, v122
	v_mul_f32_e32 v107, v107, v123
	v_mul_f32_e32 v108, v108, v124
	v_mul_f32_e32 v109, v109, v125
	v_mul_f32_e32 v110, v110, v126
	v_mul_f32_e32 v111, v111, v127
	v_cvt_pk_bf16_f32 v228, v96, v97
	v_cvt_pk_bf16_f32 v229, v98, v99
	v_cvt_pk_bf16_f32 v230, v100, v101
	v_cvt_pk_bf16_f32 v231, v102, v103
	v_cvt_pk_bf16_f32 v232, v104, v105
	v_cvt_pk_bf16_f32 v233, v106, v107
	v_cvt_pk_bf16_f32 v234, v108, v109
	v_cvt_pk_bf16_f32 v235, v110, v111
	global_store_dwordx4 v144, v[200:203], s[26:27] offset:0
	global_store_dwordx4 v144, v[204:207], s[26:27] offset:16
	s_add_u32 s26, s26, 0x8000
	s_addc_u32 s27, s27, 0
	global_store_dwordx4 v144, v[208:211], s[26:27] offset:0
	global_store_dwordx4 v144, v[212:215], s[26:27] offset:16
	s_add_u32 s26, s26, 0x8000
	s_addc_u32 s27, s27, 0
	global_store_dwordx4 v144, v[216:219], s[26:27] offset:0
	global_store_dwordx4 v144, v[220:223], s[26:27] offset:16
	s_add_u32 s26, s26, 0x8000
	s_addc_u32 s27, s27, 0
	global_store_dwordx4 v144, v[228:231], s[26:27] offset:0
	global_store_dwordx4 v144, v[232:235], s[26:27] offset:16
	s_branch .Lsml_edone

; template <int NI> ...
;     ...
;   G_LOAD(a0, b0, 0);
;   G_LOAD(a1, b1, 32);
;   __syncthreads();
;   G_WRITE(a0, b0, 0);
;   __syncthreads();
;   for (int kt = 0; kt < nk; kt += 2) {
;     G_LOAD(a0, b0, min((kt + 2) * 32, klast));
;     G_COMPUTE(0);
;     G_WRITE(a1, b1, 1);
;     __syncthreads();
;     G_LOAD(a1, b1, min((kt + 3) * 32, klast));
;     G_COMPUTE(1);
;     G_WRITE(a0, b0, 0);
;     __syncthreads();
;   }
; __device__ void phase_merge4(CParams& p, int l, int tm, int tn, char* smem) {
;     ...
;       gemm_mainloop<4>(p.br + (size_t)row0 * 1024 + kb * 256, 1024,
;                        p.WbT + (((size_t)l * 4 + kb) * 1024 + col0) * 256, 256, 256, sA, sB, acc, tid2);
.Lmg4_nozero:
	s_add_u32 m0, s56, 0x10000
	s_nop 0
	global_load_lds_dwordx4 v236, s[24:25]
	s_add_u32 m0, s56, 0x10400
	s_nop 0
	global_load_lds_dwordx4 v237, s[24:25]
	s_add_u32 m0, s56, 0x10800
	s_nop 0
	global_load_lds_dwordx4 v238, s[24:25]
	s_add_u32 m0, s56, 0x10c00
	s_nop 0
	global_load_lds_dwordx4 v239, s[24:25]
	s_add_u32 s24, s24, 128
	s_addc_u32 s25, s25, 0
	s_waitcnt lgkmcnt(0)
	v_mfma_f32_16x16x32_bf16 v[0:3], v[184:187], v[168:171], 0
	ds_read_b128 v[200:203], v249 offset:0
	v_mfma_f32_16x16x32_bf16 v[4:7], v[188:191], v[168:171], 0
	ds_read_b128 v[216:219], v251 offset:16384
	v_mfma_f32_16x16x32_bf16 v[8:11], v[192:195], v[168:171], 0
	ds_read_b128 v[204:207], v249 offset:2048
	v_mfma_f32_16x16x32_bf16 v[12:15], v[196:199], v[168:171], 0
	ds_read_b128 v[220:223], v251 offset:16896
	v_mfma_f32_16x16x32_bf16 v[16:19], v[184:187], v[172:175], 0
	ds_read_b128 v[208:211], v249 offset:4096
	v_mfma_f32_16x16x32_bf16 v[20:23], v[188:191], v[172:175], 0
	ds_read_b128 v[228:231], v251 offset:17408
	v_mfma_f32_16x16x32_bf16 v[24:27], v[192:195], v[172:175], 0
	ds_read_b128 v[212:215], v249 offset:6144
	v_mfma_f32_16x16x32_bf16 v[28:31], v[196:199], v[172:175], 0
	ds_read_b128 v[232:235], v251 offset:17920
	v_mfma_f32_16x16x32_bf16 v[32:35], v[184:187], v[176:179], 0
	v_mfma_f32_16x16x32_bf16 v[36:39], v[188:191], v[176:179], 0
	v_mfma_f32_16x16x32_bf16 v[40:43], v[192:195], v[176:179], 0
	v_mfma_f32_16x16x32_bf16 v[44:47], v[196:199], v[176:179], 0
	v_mfma_f32_16x16x32_bf16 v[48:51], v[184:187], v[180:183], 0
	v_mfma_f32_16x16x32_bf16 v[52:55], v[188:191], v[180:183], 0
	v_mfma_f32_16x16x32_bf16 v[56:59], v[192:195], v[180:183], 0
	v_mfma_f32_16x16x32_bf16 v[60:63], v[196:199], v[180:183], 0
	s_waitcnt vmcnt(4) lgkmcnt(0)
	s_barrier
	s_add_u32 m0, s56, 0x0
	s_nop 0
	global_load_lds_dwordx4 v240, s[26:27]
	s_add_u32 m0, s56, 0x400
	s_nop 0
	global_load_lds_dwordx4 v241, s[26:27]
	s_add_u32 m0, s56, 0x800
	s_nop 0
	global_load_lds_dwordx4 v242, s[26:27]
	s_add_u32 m0, s56, 0xc00
	s_nop 0
	global_load_lds_dwordx4 v243, s[26:27]
	s_add_u32 s26, s26, 128
	s_addc_u32 s27, s27, 0
	v_mfma_f32_16x16x32_bf16 v[0:3], v[216:219], v[200:203], v[0:3]
	ds_read_b128 v[168:171], v248 offset:32768
	v_mfma_f32_16x16x32_bf16 v[4:7], v[220:223], v[200:203], v[4:7]
	ds_read_b128 v[184:187], v250 offset:49152
	v_mfma_f32_16x16x32_bf16 v[8:11], v[228:231], v[200:203], v[8:11]
	ds_read_b128 v[172:175], v248 offset:34816
	v_mfma_f32_16x16x32_bf16 v[12:15], v[232:235], v[200:203], v[12:15]
	ds_read_b128 v[188:191], v250 offset:49664
	v_mfma_f32_16x16x32_bf16 v[16:19], v[216:219], v[204:207], v[16:19]
	ds_read_b128 v[176:179], v248 offset:36864
	v_mfma_f32_16x16x32_bf16 v[20:23], v[220:223], v[204:207], v[20:23]
	ds_read_b128 v[192:195], v250 offset:50176
	v_mfma_f32_16x16x32_bf16 v[24:27], v[228:231], v[204:207], v[24:27]
	ds_read_b128 v[180:183], v248 offset:38912
	v_mfma_f32_16x16x32_bf16 v[28:31], v[232:235], v[204:207], v[28:31]
	ds_read_b128 v[196:199], v250 offset:50688
	v_mfma_f32_16x16x32_bf16 v[32:35], v[216:219], v[208:211], v[32:35]
	v_mfma_f32_16x16x32_bf16 v[36:39], v[220:223], v[208:211], v[36:39]
	v_mfma_f32_16x16x32_bf16 v[40:43], v[228:231], v[208:211], v[40:43]
	v_mfma_f32_16x16x32_bf16 v[44:47], v[232:235], v[208:211], v[44:47]
	v_mfma_f32_16x16x32_bf16 v[48:51], v[216:219], v[212:215], v[48:51]
	v_mfma_f32_16x16x32_bf16 v[52:55], v[220:223], v[212:215], v[52:55]
	v_mfma_f32_16x16x32_bf16 v[56:59], v[228:231], v[212:215], v[56:59]
	v_mfma_f32_16x16x32_bf16 v[60:63], v[232:235], v[212:215], v[60:63]
	s_add_u32 m0, s56, 0x4000
	s_nop 0
	global_load_lds_dwordx4 v236, s[24:25]
	s_add_u32 m0, s56, 0x4400
	s_nop 0
	global_load_lds_dwordx4 v237, s[24:25]
	s_add_u32 m0, s56, 0x4800
	s_nop 0
	global_load_lds_dwordx4 v238, s[24:25]
	s_add_u32 m0, s56, 0x4c00
	s_nop 0
	global_load_lds_dwordx4 v239, s[24:25]
	s_add_u32 s24, s24, 128
	s_addc_u32 s25, s25, 0
	s_waitcnt lgkmcnt(0)
	v_mfma_f32_16x16x32_bf16 v[0:3], v[184:187], v[168:171], v[0:3]
	ds_read_b128 v[200:203], v249 offset:32768
	v_mfma_f32_16x16x32_bf16 v[4:7], v[188:191], v[168:171], v[4:7]
	ds_read_b128 v[216:219], v251 offset:49152
	v_mfma_f32_16x16x32_bf16 v[8:11], v[192:195], v[168:171], v[8:11]
	ds_read_b128 v[204:207], v249 offset:34816
	v_mfma_f32_16x16x32_bf16 v[12:15], v[196:199], v[168:171], v[12:15]
	ds_read_b128 v[220:223], v251 offset:49664
	v_mfma_f32_16x16x32_bf16 v[16:19], v[184:187], v[172:175], v[16:19]
	ds_read_b128 v[208:211], v249 offset:36864
	v_mfma_f32_16x16x32_bf16 v[20:23], v[188:191], v[172:175], v[20:23]
	ds_read_b128 v[228:231], v251 offset:50176
	v_mfma_f32_16x16x32_bf16 v[24:27], v[192:195], v[172:175], v[24:27]
	ds_read_b128 v[212:215], v249 offset:38912
	v_mfma_f32_16x16x32_bf16 v[28:31], v[196:199], v[172:175], v[28:31]
	ds_read_b128 v[232:235], v251 offset:50688
	v_mfma_f32_16x16x32_bf16 v[32:35], v[184:187], v[176:179], v[32:35]
	v_mfma_f32_16x16x32_bf16 v[36:39], v[188:191], v[176:179], v[36:39]
	v_mfma_f32_16x16x32_bf16 v[40:43], v[192:195], v[176:179], v[40:43]
	v_mfma_f32_16x16x32_bf16 v[44:47], v[196:199], v[176:179], v[44:47]
	v_mfma_f32_16x16x32_bf16 v[48:51], v[184:187], v[180:183], v[48:51]
	v_mfma_f32_16x16x32_bf16 v[52:55], v[188:191], v[180:183], v[52:55]
	v_mfma_f32_16x16x32_bf16 v[56:59], v[192:195], v[180:183], v[56:59]
	v_mfma_f32_16x16x32_bf16 v[60:63], v[196:199], v[180:183], v[60:63]
	s_waitcnt vmcnt(4) lgkmcnt(0)
	s_barrier
; template <int NI> ...
;     ...
;   G_LOAD(a0, b0, 0);
;   G_LOAD(a1, b1, 32);
;   __syncthreads();
;   G_WRITE(a0, b0, 0);
;   __syncthreads();
;   for (int kt = 0; kt < nk; kt += 2) {
;     G_LOAD(a0, b0, min((kt + 2) * 32, klast));
;     G_COMPUTE(0);
;     G_WRITE(a1, b1, 1);
;     __syncthreads();
;     G_LOAD(a1, b1, min((kt + 3) * 32, klast));
;     G_COMPUTE(1);
;     G_WRITE(a0, b0, 0);
;     __syncthreads();
;   }
; __device__ void phase_merge4(CParams& p, int l, int tm, int tn, char* smem) {
;     ...
;       gemm_mainloop<4>(p.br + (size_t)row0 * 1024 + kb * 256, 1024,
;                        p.WbT + (((size_t)l * 4 + kb) * 1024 + col0) * 256, 256, 256, sA, sB, acc, tid2);
	s_add_u32 m0, s56, 0x8000
	s_nop 0
	global_load_lds_dwordx4 v240, s[26:27]
	s_add_u32 m0, s56, 0x8400
	s_nop 0
	global_load_lds_dwordx4 v241, s[26:27]
	s_add_u32 m0, s56, 0x8800
	s_nop 0
	global_load_lds_dwordx4 v242, s[26:27]
	s_add_u32 m0, s56, 0x8c00
	s_nop 0
	global_load_lds_dwordx4 v243, s[26:27]
	s_add_u32 s26, s26, 128
	s_addc_u32 s27, s27, 0
	v_mfma_f32_16x16x32_bf16 v[0:3], v[216:219], v[200:203], v[0:3]
	ds_read_b128 v[168:171], v166 offset:49152
	v_mfma_f32_16x16x32_bf16 v[4:7], v[220:223], v[200:203], v[4:7]
	ds_read_b128 v[184:187], v250 offset:0
	v_mfma_f32_16x16x32_bf16 v[8:11], v[228:231], v[200:203], v[8:11]
	ds_read_b128 v[172:175], v166 offset:51200
	v_mfma_f32_16x16x32_bf16 v[12:15], v[232:235], v[200:203], v[12:15]
	ds_read_b128 v[188:191], v250 offset:512
	v_mfma_f32_16x16x32_bf16 v[16:19], v[216:219], v[204:207], v[16:19]
	ds_read_b128 v[176:179], v166 offset:53248
	v_mfma_f32_16x16x32_bf16 v[20:23], v[220:223], v[204:207], v[20:23]
	ds_read_b128 v[192:195], v250 offset:1024
	v_mfma_f32_16x16x32_bf16 v[24:27], v[228:231], v[204:207], v[24:27]
	ds_read_b128 v[180:183], v166 offset:55296
	v_mfma_f32_16x16x32_bf16 v[28:31], v[232:235], v[204:207], v[28:31]
	ds_read_b128 v[196:199], v250 offset:1536
	v_mfma_f32_16x16x32_bf16 v[32:35], v[216:219], v[208:211], v[32:35]
	v_mfma_f32_16x16x32_bf16 v[36:39], v[220:223], v[208:211], v[36:39]
	v_mfma_f32_16x16x32_bf16 v[40:43], v[228:231], v[208:211], v[40:43]
	v_mfma_f32_16x16x32_bf16 v[44:47], v[232:235], v[208:211], v[44:47]
	v_mfma_f32_16x16x32_bf16 v[48:51], v[216:219], v[212:215], v[48:51]
	v_mfma_f32_16x16x32_bf16 v[52:55], v[220:223], v[212:215], v[52:55]
	v_mfma_f32_16x16x32_bf16 v[56:59], v[228:231], v[212:215], v[56:59]
	v_mfma_f32_16x16x32_bf16 v[60:63], v[232:235], v[212:215], v[60:63]
	s_mov_b64 s[24:25], s[50:51]
	s_add_u32 m0, s56, 0xc000
	s_nop 0
	global_load_lds_dwordx4 v236, s[24:25]
	s_add_u32 m0, s56, 0xc400
	s_nop 0
	global_load_lds_dwordx4 v237, s[24:25]
	s_add_u32 m0, s56, 0xc800
	s_nop 0
	global_load_lds_dwordx4 v238, s[24:25]
	s_add_u32 m0, s56, 0xcc00
	s_nop 0
	global_load_lds_dwordx4 v239, s[24:25]
	s_add_u32 s24, s24, 128
	s_addc_u32 s25, s25, 0
	s_waitcnt lgkmcnt(0)
	v_mfma_f32_16x16x32_bf16 v[0:3], v[184:187], v[168:171], v[0:3]
	ds_read_b128 v[200:203], v167 offset:49152
	v_mfma_f32_16x16x32_bf16 v[4:7], v[188:191], v[168:171], v[4:7]
	ds_read_b128 v[216:219], v251 offset:0
	v_mfma_f32_16x16x32_bf16 v[8:11], v[192:195], v[168:171], v[8:11]
	ds_read_b128 v[204:207], v167 offset:51200
	v_mfma_f32_16x16x32_bf16 v[12:15], v[196:199], v[168:171], v[12:15]
	ds_read_b128 v[220:223], v251 offset:512
	v_mfma_f32_16x16x32_bf16 v[16:19], v[184:187], v[172:175], v[16:19]
	ds_read_b128 v[208:211], v167 offset:53248
	v_mfma_f32_16x16x32_bf16 v[20:23], v[188:191], v[172:175], v[20:23]
	ds_read_b128 v[228:231], v251 offset:1024
	v_mfma_f32_16x16x32_bf16 v[24:27], v[192:195], v[172:175], v[24:27]
	ds_read_b128 v[212:215], v167 offset:55296
	v_mfma_f32_16x16x32_bf16 v[28:31], v[196:199], v[172:175], v[28:31]
	ds_read_b128 v[232:235], v251 offset:1536
	v_mfma_f32_16x16x32_bf16 v[32:35], v[184:187], v[176:179], v[32:35]
	v_mfma_f32_16x16x32_bf16 v[36:39], v[188:191], v[176:179], v[36:39]
	v_mfma_f32_16x16x32_bf16 v[40:43], v[192:195], v[176:179], v[40:43]
	v_mfma_f32_16x16x32_bf16 v[44:47], v[196:199], v[176:179], v[44:47]
	v_mfma_f32_16x16x32_bf16 v[48:51], v[184:187], v[180:183], v[48:51]
	v_mfma_f32_16x16x32_bf16 v[52:55], v[188:191], v[180:183], v[52:55]
	v_mfma_f32_16x16x32_bf16 v[56:59], v[192:195], v[180:183], v[56:59]
	v_mfma_f32_16x16x32_bf16 v[60:63], v[196:199], v[180:183], v[60:63]
	s_waitcnt vmcnt(4) lgkmcnt(0)
	s_barrier
	s_mov_b64 s[26:27], s[54:55]
	s_add_u32 m0, s56, 0x10000
	s_nop 0
	global_load_lds_dwordx4 v244, s[26:27]
	s_add_u32 m0, s56, 0x10400
	s_nop 0
	global_load_lds_dwordx4 v245, s[26:27]
	s_add_u32 m0, s56, 0x10800
	s_nop 0
	global_load_lds_dwordx4 v246, s[26:27]
	s_add_u32 m0, s56, 0x10c00
	s_nop 0
	global_load_lds_dwordx4 v247, s[26:27]
	s_add_u32 s26, s26, 128
	s_addc_u32 s27, s27, 0
	v_mfma_f32_16x16x32_bf16 v[0:3], v[216:219], v[200:203], v[0:3]
	ds_read_b128 v[168:171], v248 offset:16384
	v_mfma_f32_16x16x32_bf16 v[4:7], v[220:223], v[200:203], v[4:7]
	ds_read_b128 v[184:187], v250 offset:32768
	v_mfma_f32_16x16x32_bf16 v[8:11], v[228:231], v[200:203], v[8:11]
	ds_read_b128 v[172:175], v248 offset:18432
	v_mfma_f32_16x16x32_bf16 v[12:15], v[232:235], v[200:203], v[12:15]
	ds_read_b128 v[188:191], v250 offset:33280
	v_mfma_f32_16x16x32_bf16 v[16:19], v[216:219], v[204:207], v[16:19]
	ds_read_b128 v[176:179], v248 offset:20480
	v_mfma_f32_16x16x32_bf16 v[20:23], v[220:223], v[204:207], v[20:23]
	ds_read_b128 v[192:195], v250 offset:33792
	v_mfma_f32_16x16x32_bf16 v[24:27], v[228:231], v[204:207], v[24:27]
	ds_read_b128 v[180:183], v248 offset:22528
	v_mfma_f32_16x16x32_bf16 v[28:31], v[232:235], v[204:207], v[28:31]
	ds_read_b128 v[196:199], v250 offset:34304
	v_mfma_f32_16x16x32_bf16 v[32:35], v[216:219], v[208:211], v[32:35]
	v_mfma_f32_16x16x32_bf16 v[36:39], v[220:223], v[208:211], v[36:39]
	v_mfma_f32_16x16x32_bf16 v[40:43], v[228:231], v[208:211], v[40:43]
	v_mfma_f32_16x16x32_bf16 v[44:47], v[232:235], v[208:211], v[44:47]
	v_mfma_f32_16x16x32_bf16 v[48:51], v[216:219], v[212:215], v[48:51]
	v_mfma_f32_16x16x32_bf16 v[52:55], v[220:223], v[212:215], v[52:55]
	v_mfma_f32_16x16x32_bf16 v[56:59], v[228:231], v[212:215], v[56:59]
	v_mfma_f32_16x16x32_bf16 v[60:63], v[232:235], v[212:215], v[60:63]
	s_add_u32 m0, s56, 0x0
	s_nop 0
	global_load_lds_dwordx4 v236, s[24:25]
	s_add_u32 m0, s56, 0x400
	s_nop 0
	global_load_lds_dwordx4 v237, s[24:25]
	s_add_u32 m0, s56, 0x800
	s_nop 0
	global_load_lds_dwordx4 v238, s[24:25]
	s_add_u32 m0, s56, 0xc00
	s_nop 0
	global_load_lds_dwordx4 v239, s[24:25]
	s_add_u32 s24, s24, 128
	s_addc_u32 s25, s25, 0
	s_waitcnt lgkmcnt(0)
; template <int NI> ...
;     ...
;   G_LOAD(a0, b0, 0);
;   G_LOAD(a1, b1, 32);
;   __syncthreads();
;   G_WRITE(a0, b0, 0);
;   __syncthreads();
;   for (int kt = 0; kt < nk; kt += 2) {
;     G_LOAD(a0, b0, min((kt + 2) * 32, klast));
;     G_COMPUTE(0);
;     G_WRITE(a1, b1, 1);
;     __syncthreads();
;     G_LOAD(a1, b1, min((kt + 3) * 32, klast));
;     G_COMPUTE(1);
;     G_WRITE(a0, b0, 0);
;     __syncthreads();
;   }
; __device__ void phase_merge4(CParams& p, int l, int tm, int tn, char* smem) {
;     ...
; #pragma unroll
;       for (int mi = 0; mi < 4; mi++)
; #pragma unroll
;         for (int ni = 0; ni < 4; ni++) {
;           pk[mi][ni][0] = (unsigned)f2bf(acc[mi][ni][0]) | ((unsigned)f2bf(acc[mi][ni][1]) << 16);
;           pk[mi][ni][1] = (unsigned)f2bf(acc[mi][ni][2]) | ((unsigned)f2bf(acc[mi][ni][3]) << 16);
;         }
	v_mfma_f32_16x16x32_bf16 v[0:3], v[184:187], v[168:171], v[0:3]
	ds_read_b128 v[200:203], v249 offset:16384
	v_mfma_f32_16x16x32_bf16 v[4:7], v[188:191], v[168:171], v[4:7]
	ds_read_b128 v[216:219], v251 offset:32768
	v_mfma_f32_16x16x32_bf16 v[8:11], v[192:195], v[168:171], v[8:11]
	ds_read_b128 v[204:207], v249 offset:18432
	v_mfma_f32_16x16x32_bf16 v[12:15], v[196:199], v[168:171], v[12:15]
	ds_read_b128 v[220:223], v251 offset:33280
	v_mfma_f32_16x16x32_bf16 v[16:19], v[184:187], v[172:175], v[16:19]
	ds_read_b128 v[208:211], v249 offset:20480
	v_mfma_f32_16x16x32_bf16 v[20:23], v[188:191], v[172:175], v[20:23]
	ds_read_b128 v[228:231], v251 offset:33792
	v_mfma_f32_16x16x32_bf16 v[24:27], v[192:195], v[172:175], v[24:27]
	ds_read_b128 v[212:215], v249 offset:22528
	v_mfma_f32_16x16x32_bf16 v[28:31], v[196:199], v[172:175], v[28:31]
	ds_read_b128 v[232:235], v251 offset:34304
	v_mfma_f32_16x16x32_bf16 v[32:35], v[184:187], v[176:179], v[32:35]
	v_mfma_f32_16x16x32_bf16 v[36:39], v[188:191], v[176:179], v[36:39]
	v_mfma_f32_16x16x32_bf16 v[40:43], v[192:195], v[176:179], v[40:43]
	v_mfma_f32_16x16x32_bf16 v[44:47], v[196:199], v[176:179], v[44:47]
	v_mfma_f32_16x16x32_bf16 v[48:51], v[184:187], v[180:183], v[48:51]
	v_mfma_f32_16x16x32_bf16 v[52:55], v[188:191], v[180:183], v[52:55]
	v_mfma_f32_16x16x32_bf16 v[56:59], v[192:195], v[180:183], v[56:59]
	v_mfma_f32_16x16x32_bf16 v[60:63], v[196:199], v[180:183], v[60:63]
	s_waitcnt vmcnt(4) lgkmcnt(0)
	s_barrier
	s_add_u32 m0, s56, 0x4000
	s_nop 0
	global_load_lds_dwordx4 v244, s[26:27]
	s_add_u32 m0, s56, 0x4400
	s_nop 0
	global_load_lds_dwordx4 v245, s[26:27]
	s_add_u32 m0, s56, 0x4800
	s_nop 0
	global_load_lds_dwordx4 v246, s[26:27]
	s_add_u32 m0, s56, 0x4c00
	s_nop 0
	global_load_lds_dwordx4 v247, s[26:27]
	s_add_u32 s26, s26, 128
	s_addc_u32 s27, s27, 0
	v_mfma_f32_16x16x32_bf16 v[0:3], v[216:219], v[200:203], v[0:3]
	ds_read_b128 v[168:171], v248 offset:49152
	v_mfma_f32_16x16x32_bf16 v[4:7], v[220:223], v[200:203], v[4:7]
	ds_read_b128 v[184:187], v226 offset:49152
	v_mfma_f32_16x16x32_bf16 v[8:11], v[228:231], v[200:203], v[8:11]
	ds_read_b128 v[172:175], v248 offset:51200
	v_mfma_f32_16x16x32_bf16 v[12:15], v[232:235], v[200:203], v[12:15]
	ds_read_b128 v[188:191], v226 offset:49664
	v_mfma_f32_16x16x32_bf16 v[16:19], v[216:219], v[204:207], v[16:19]
	ds_read_b128 v[176:179], v248 offset:53248
	v_mfma_f32_16x16x32_bf16 v[20:23], v[220:223], v[204:207], v[20:23]
	ds_read_b128 v[192:195], v226 offset:50176
	v_mfma_f32_16x16x32_bf16 v[24:27], v[228:231], v[204:207], v[24:27]
	ds_read_b128 v[180:183], v248 offset:55296
	v_mfma_f32_16x16x32_bf16 v[28:31], v[232:235], v[204:207], v[28:31]
	ds_read_b128 v[196:199], v226 offset:50688
	v_mfma_f32_16x16x32_bf16 v[32:35], v[216:219], v[208:211], v[32:35]
	v_mfma_f32_16x16x32_bf16 v[36:39], v[220:223], v[208:211], v[36:39]
	v_mfma_f32_16x16x32_bf16 v[40:43], v[228:231], v[208:211], v[40:43]
	v_mfma_f32_16x16x32_bf16 v[44:47], v[232:235], v[208:211], v[44:47]
	v_mfma_f32_16x16x32_bf16 v[48:51], v[216:219], v[212:215], v[48:51]
	v_mfma_f32_16x16x32_bf16 v[52:55], v[220:223], v[212:215], v[52:55]
	v_mfma_f32_16x16x32_bf16 v[56:59], v[228:231], v[212:215], v[56:59]
	v_mfma_f32_16x16x32_bf16 v[60:63], v[232:235], v[212:215], v[60:63]
	s_nop 15
	s_nop 7
	v_cvt_pk_bf16_f32 v128, v0, v1
	v_cvt_pk_bf16_f32 v129, v2, v3
	v_cvt_pk_bf16_f32 v130, v4, v5
	v_cvt_pk_bf16_f32 v131, v6, v7
	v_cvt_pk_bf16_f32 v132, v8, v9
	v_cvt_pk_bf16_f32 v133, v10, v11
	v_cvt_pk_bf16_f32 v134, v12, v13
	v_cvt_pk_bf16_f32 v135, v14, v15
	v_cvt_pk_bf16_f32 v136, v16, v17
	v_cvt_pk_bf16_f32 v137, v18, v19
	v_cvt_pk_bf16_f32 v138, v20, v21
	v_cvt_pk_bf16_f32 v139, v22, v23
	v_cvt_pk_bf16_f32 v140, v24, v25
	v_cvt_pk_bf16_f32 v141, v26, v27
	v_cvt_pk_bf16_f32 v142, v28, v29
	v_cvt_pk_bf16_f32 v143, v30, v31
	v_cvt_pk_bf16_f32 v148, v32, v33
	v_cvt_pk_bf16_f32 v149, v34, v35
	v_cvt_pk_bf16_f32 v150, v36, v37
	v_cvt_pk_bf16_f32 v151, v38, v39
	v_cvt_pk_bf16_f32 v152, v40, v41
	v_cvt_pk_bf16_f32 v153, v42, v43
	v_cvt_pk_bf16_f32 v154, v44, v45
	v_cvt_pk_bf16_f32 v155, v46, v47
	v_cvt_pk_bf16_f32 v156, v48, v49
	v_cvt_pk_bf16_f32 v157, v50, v51
	v_cvt_pk_bf16_f32 v158, v52, v53
	v_cvt_pk_bf16_f32 v159, v54, v55
	v_cvt_pk_bf16_f32 v160, v56, v57
	v_cvt_pk_bf16_f32 v161, v58, v59
	v_cvt_pk_bf16_f32 v162, v60, v61
	v_cvt_pk_bf16_f32 v163, v62, v63
	s_add_u32 m0, s56, 0x8000
	s_nop 0
	global_load_lds_dwordx4 v236, s[24:25]
	s_add_u32 m0, s56, 0x8400
	s_nop 0
	global_load_lds_dwordx4 v237, s[24:25]
	s_add_u32 m0, s56, 0x8800
	s_nop 0
	global_load_lds_dwordx4 v238, s[24:25]
	s_add_u32 m0, s56, 0x8c00
	s_nop 0
	global_load_lds_dwordx4 v239, s[24:25]
	s_add_u32 s24, s24, 128
	s_addc_u32 s25, s25, 0
	s_waitcnt lgkmcnt(0)
	v_mfma_f32_16x16x32_bf16 v[0:3], v[184:187], v[168:171], 0
	ds_read_b128 v[200:203], v249 offset:49152
	v_mfma_f32_16x16x32_bf16 v[4:7], v[188:191], v[168:171], 0
	ds_read_b128 v[216:219], v227 offset:49152
	v_mfma_f32_16x16x32_bf16 v[8:11], v[192:195], v[168:171], 0
	ds_read_b128 v[204:207], v249 offset:51200
	v_mfma_f32_16x16x32_bf16 v[12:15], v[196:199], v[168:171], 0
	ds_read_b128 v[220:223], v227 offset:49664
	v_mfma_f32_16x16x32_bf16 v[16:19], v[184:187], v[172:175], 0
	ds_read_b128 v[208:211], v249 offset:53248
	v_mfma_f32_16x16x32_bf16 v[20:23], v[188:191], v[172:175], 0
	ds_read_b128 v[228:231], v227 offset:50176
	v_mfma_f32_16x16x32_bf16 v[24:27], v[192:195], v[172:175], 0
	ds_read_b128 v[212:215], v249 offset:55296
	v_mfma_f32_16x16x32_bf16 v[28:31], v[196:199], v[172:175], 0
	ds_read_b128 v[232:235], v227 offset:50688
	v_mfma_f32_16x16x32_bf16 v[32:35], v[184:187], v[176:179], 0
	v_mfma_f32_16x16x32_bf16 v[36:39], v[188:191], v[176:179], 0
	v_mfma_f32_16x16x32_bf16 v[40:43], v[192:195], v[176:179], 0
	v_mfma_f32_16x16x32_bf16 v[44:47], v[196:199], v[176:179], 0
	v_mfma_f32_16x16x32_bf16 v[48:51], v[184:187], v[180:183], 0
	v_mfma_f32_16x16x32_bf16 v[52:55], v[188:191], v[180:183], 0
	v_mfma_f32_16x16x32_bf16 v[56:59], v[192:195], v[180:183], 0
	v_mfma_f32_16x16x32_bf16 v[60:63], v[196:199], v[180:183], 0
	s_waitcnt vmcnt(4) lgkmcnt(0)
	s_barrier
; template <int NI> ...
;     ...
;   G_LOAD(a0, b0, 0);
;   G_LOAD(a1, b1, 32);
;   __syncthreads();
;   G_WRITE(a0, b0, 0);
;   __syncthreads();
;   for (int kt = 0; kt < nk; kt += 2) {
;     G_LOAD(a0, b0, min((kt + 2) * 32, klast));
;     G_COMPUTE(0);
;     G_WRITE(a1, b1, 1);
;     __syncthreads();
;     G_LOAD(a1, b1, min((kt + 3) * 32, klast));
;     G_COMPUTE(1);
;     G_WRITE(a0, b0, 0);
;     __syncthreads();
;   }
; __device__ void phase_merge4(CParams& p, int l, int tm, int tn, char* smem) {
;     ...
;     gemm_mainloop<4>(p.hbuf + (size_t)row0 * DM, DM,
;                      p.WgT + (((size_t)l * 4 + kb) * 1024 + col0) * 1024, 1024, 1024, sA, sB, acc, tid2);
	s_add_u32 m0, s56, 0xc000
	s_nop 0
	global_load_lds_dwordx4 v244, s[26:27]
	s_add_u32 m0, s56, 0xc400
	s_nop 0
	global_load_lds_dwordx4 v245, s[26:27]
	s_add_u32 m0, s56, 0xc800
	s_nop 0
	global_load_lds_dwordx4 v246, s[26:27]
	s_add_u32 m0, s56, 0xcc00
	s_nop 0
	global_load_lds_dwordx4 v247, s[26:27]
	s_add_u32 s26, s26, 128
	s_addc_u32 s27, s27, 0
	v_mfma_f32_16x16x32_bf16 v[0:3], v[216:219], v[200:203], v[0:3]
	ds_read_b128 v[168:171], v248 offset:0
	v_mfma_f32_16x16x32_bf16 v[4:7], v[220:223], v[200:203], v[4:7]
	ds_read_b128 v[184:187], v250 offset:16384
	v_mfma_f32_16x16x32_bf16 v[8:11], v[228:231], v[200:203], v[8:11]
	ds_read_b128 v[172:175], v248 offset:2048
	v_mfma_f32_16x16x32_bf16 v[12:15], v[232:235], v[200:203], v[12:15]
	ds_read_b128 v[188:191], v250 offset:16896
	v_mfma_f32_16x16x32_bf16 v[16:19], v[216:219], v[204:207], v[16:19]
	ds_read_b128 v[176:179], v248 offset:4096
	v_mfma_f32_16x16x32_bf16 v[20:23], v[220:223], v[204:207], v[20:23]
	ds_read_b128 v[192:195], v250 offset:17408
	v_mfma_f32_16x16x32_bf16 v[24:27], v[228:231], v[204:207], v[24:27]
	ds_read_b128 v[180:183], v248 offset:6144
	v_mfma_f32_16x16x32_bf16 v[28:31], v[232:235], v[204:207], v[28:31]
	ds_read_b128 v[196:199], v250 offset:17920
	v_mfma_f32_16x16x32_bf16 v[32:35], v[216:219], v[208:211], v[32:35]
	v_mfma_f32_16x16x32_bf16 v[36:39], v[220:223], v[208:211], v[36:39]
	v_mfma_f32_16x16x32_bf16 v[40:43], v[228:231], v[208:211], v[40:43]
	v_mfma_f32_16x16x32_bf16 v[44:47], v[232:235], v[208:211], v[44:47]
	v_mfma_f32_16x16x32_bf16 v[48:51], v[216:219], v[212:215], v[48:51]
	v_mfma_f32_16x16x32_bf16 v[52:55], v[220:223], v[212:215], v[52:55]
	v_mfma_f32_16x16x32_bf16 v[56:59], v[228:231], v[212:215], v[56:59]
	v_mfma_f32_16x16x32_bf16 v[60:63], v[232:235], v[212:215], v[60:63]
	s_add_u32 m0, s56, 0x10000
	s_nop 0
	global_load_lds_dwordx4 v236, s[24:25]
	s_add_u32 m0, s56, 0x10400
	s_nop 0
	global_load_lds_dwordx4 v237, s[24:25]
	s_add_u32 m0, s56, 0x10800
	s_nop 0
	global_load_lds_dwordx4 v238, s[24:25]
	s_add_u32 m0, s56, 0x10c00
	s_nop 0
	global_load_lds_dwordx4 v239, s[24:25]
	s_add_u32 s24, s24, 128
	s_addc_u32 s25, s25, 0
	s_waitcnt lgkmcnt(0)
	v_mfma_f32_16x16x32_bf16 v[0:3], v[184:187], v[168:171], v[0:3]
	ds_read_b128 v[200:203], v249 offset:0
	v_mfma_f32_16x16x32_bf16 v[4:7], v[188:191], v[168:171], v[4:7]
	ds_read_b128 v[216:219], v251 offset:16384
	v_mfma_f32_16x16x32_bf16 v[8:11], v[192:195], v[168:171], v[8:11]
	ds_read_b128 v[204:207], v249 offset:2048
	v_mfma_f32_16x16x32_bf16 v[12:15], v[196:199], v[168:171], v[12:15]
	ds_read_b128 v[220:223], v251 offset:16896
	v_mfma_f32_16x16x32_bf16 v[16:19], v[184:187], v[172:175], v[16:19]
	ds_read_b128 v[208:211], v249 offset:4096
	v_mfma_f32_16x16x32_bf16 v[20:23], v[188:191], v[172:175], v[20:23]
	ds_read_b128 v[228:231], v251 offset:17408
	v_mfma_f32_16x16x32_bf16 v[24:27], v[192:195], v[172:175], v[24:27]
	ds_read_b128 v[212:215], v249 offset:6144
	v_mfma_f32_16x16x32_bf16 v[28:31], v[196:199], v[172:175], v[28:31]
	ds_read_b128 v[232:235], v251 offset:17920
	v_mfma_f32_16x16x32_bf16 v[32:35], v[184:187], v[176:179], v[32:35]
	v_mfma_f32_16x16x32_bf16 v[36:39], v[188:191], v[176:179], v[36:39]
	v_mfma_f32_16x16x32_bf16 v[40:43], v[192:195], v[176:179], v[40:43]
	v_mfma_f32_16x16x32_bf16 v[44:47], v[196:199], v[176:179], v[44:47]
	v_mfma_f32_16x16x32_bf16 v[48:51], v[184:187], v[180:183], v[48:51]
	v_mfma_f32_16x16x32_bf16 v[52:55], v[188:191], v[180:183], v[52:55]
	v_mfma_f32_16x16x32_bf16 v[56:59], v[192:195], v[180:183], v[56:59]
	v_mfma_f32_16x16x32_bf16 v[60:63], v[196:199], v[180:183], v[60:63]
	s_waitcnt vmcnt(4) lgkmcnt(0)
	s_barrier
	s_add_u32 m0, s56, 0x0
	s_nop 0
	global_load_lds_dwordx4 v244, s[26:27]
	s_add_u32 m0, s56, 0x400
	s_nop 0
	global_load_lds_dwordx4 v245, s[26:27]
	s_add_u32 m0, s56, 0x800
	s_nop 0
	global_load_lds_dwordx4 v246, s[26:27]
	s_add_u32 m0, s56, 0xc00
	s_nop 0
	global_load_lds_dwordx4 v247, s[26:27]
	s_add_u32 s26, s26, 128
	s_addc_u32 s27, s27, 0
	v_mfma_f32_16x16x32_bf16 v[0:3], v[216:219], v[200:203], v[0:3]
	ds_read_b128 v[168:171], v248 offset:32768
	v_mfma_f32_16x16x32_bf16 v[4:7], v[220:223], v[200:203], v[4:7]
	ds_read_b128 v[184:187], v250 offset:49152
	v_mfma_f32_16x16x32_bf16 v[8:11], v[228:231], v[200:203], v[8:11]
	ds_read_b128 v[172:175], v248 offset:34816
	v_mfma_f32_16x16x32_bf16 v[12:15], v[232:235], v[200:203], v[12:15]
	ds_read_b128 v[188:191], v250 offset:49664
	v_mfma_f32_16x16x32_bf16 v[16:19], v[216:219], v[204:207], v[16:19]
	ds_read_b128 v[176:179], v248 offset:36864
	v_mfma_f32_16x16x32_bf16 v[20:23], v[220:223], v[204:207], v[20:23]
	ds_read_b128 v[192:195], v250 offset:50176
	v_mfma_f32_16x16x32_bf16 v[24:27], v[228:231], v[204:207], v[24:27]
	ds_read_b128 v[180:183], v248 offset:38912
	v_mfma_f32_16x16x32_bf16 v[28:31], v[232:235], v[204:207], v[28:31]
	ds_read_b128 v[196:199], v250 offset:50688
	v_mfma_f32_16x16x32_bf16 v[32:35], v[216:219], v[208:211], v[32:35]
	v_mfma_f32_16x16x32_bf16 v[36:39], v[220:223], v[208:211], v[36:39]
	v_mfma_f32_16x16x32_bf16 v[40:43], v[228:231], v[208:211], v[40:43]
	v_mfma_f32_16x16x32_bf16 v[44:47], v[232:235], v[208:211], v[44:47]
	v_mfma_f32_16x16x32_bf16 v[48:51], v[216:219], v[212:215], v[48:51]
	v_mfma_f32_16x16x32_bf16 v[52:55], v[220:223], v[212:215], v[52:55]
	v_mfma_f32_16x16x32_bf16 v[56:59], v[228:231], v[212:215], v[56:59]
	v_mfma_f32_16x16x32_bf16 v[60:63], v[232:235], v[212:215], v[60:63]
	s_add_u32 m0, s56, 0x4000
	s_nop 0
	global_load_lds_dwordx4 v236, s[24:25]
	s_add_u32 m0, s56, 0x4400
	s_nop 0
	global_load_lds_dwordx4 v237, s[24:25]
	s_add_u32 m0, s56, 0x4800
	s_nop 0
	global_load_lds_dwordx4 v238, s[24:25]
	s_add_u32 m0, s56, 0x4c00
	s_nop 0
	global_load_lds_dwordx4 v239, s[24:25]
	s_add_u32 s24, s24, 128
	s_addc_u32 s25, s25, 0
	s_waitcnt lgkmcnt(0)
; template <int NI> ...
;     ...
;   G_LOAD(a0, b0, 0);
;   G_LOAD(a1, b1, 32);
;   __syncthreads();
;   G_WRITE(a0, b0, 0);
;   __syncthreads();
;   for (int kt = 0; kt < nk; kt += 2) {
;     G_LOAD(a0, b0, min((kt + 2) * 32, klast));
;     G_COMPUTE(0);
;     G_WRITE(a1, b1, 1);
;     __syncthreads();
;     G_LOAD(a1, b1, min((kt + 3) * 32, klast));
;     G_COMPUTE(1);
;     G_WRITE(a0, b0, 0);
;     __syncthreads();
;   }
; __device__ void phase_merge4(CParams& p, int l, int tm, int tn, char* smem) {
;     ...
;     gemm_mainloop<4>(p.hbuf + (size_t)row0 * DM, DM,
;                      p.WgT + (((size_t)l * 4 + kb) * 1024 + col0) * 1024, 1024, 1024, sA, sB, acc, tid2);
	v_mfma_f32_16x16x32_bf16 v[0:3], v[184:187], v[168:171], v[0:3]
	ds_read_b128 v[200:203], v249 offset:32768
	v_mfma_f32_16x16x32_bf16 v[4:7], v[188:191], v[168:171], v[4:7]
	ds_read_b128 v[216:219], v251 offset:49152
	v_mfma_f32_16x16x32_bf16 v[8:11], v[192:195], v[168:171], v[8:11]
	ds_read_b128 v[204:207], v249 offset:34816
	v_mfma_f32_16x16x32_bf16 v[12:15], v[196:199], v[168:171], v[12:15]
	ds_read_b128 v[220:223], v251 offset:49664
	v_mfma_f32_16x16x32_bf16 v[16:19], v[184:187], v[172:175], v[16:19]
	ds_read_b128 v[208:211], v249 offset:36864
	v_mfma_f32_16x16x32_bf16 v[20:23], v[188:191], v[172:175], v[20:23]
	ds_read_b128 v[228:231], v251 offset:50176
	v_mfma_f32_16x16x32_bf16 v[24:27], v[192:195], v[172:175], v[24:27]
	ds_read_b128 v[212:215], v249 offset:38912
	v_mfma_f32_16x16x32_bf16 v[28:31], v[196:199], v[172:175], v[28:31]
	ds_read_b128 v[232:235], v251 offset:50688
	v_mfma_f32_16x16x32_bf16 v[32:35], v[184:187], v[176:179], v[32:35]
	v_mfma_f32_16x16x32_bf16 v[36:39], v[188:191], v[176:179], v[36:39]
	v_mfma_f32_16x16x32_bf16 v[40:43], v[192:195], v[176:179], v[40:43]
	v_mfma_f32_16x16x32_bf16 v[44:47], v[196:199], v[176:179], v[44:47]
	v_mfma_f32_16x16x32_bf16 v[48:51], v[184:187], v[180:183], v[48:51]
	v_mfma_f32_16x16x32_bf16 v[52:55], v[188:191], v[180:183], v[52:55]
	v_mfma_f32_16x16x32_bf16 v[56:59], v[192:195], v[180:183], v[56:59]
	v_mfma_f32_16x16x32_bf16 v[60:63], v[196:199], v[180:183], v[60:63]
	s_waitcnt vmcnt(4) lgkmcnt(0)
	s_barrier
	s_add_u32 m0, s56, 0x8000
	s_nop 0
	global_load_lds_dwordx4 v244, s[26:27]
	s_add_u32 m0, s56, 0x8400
	s_nop 0
	global_load_lds_dwordx4 v245, s[26:27]
	s_add_u32 m0, s56, 0x8800
	s_nop 0
	global_load_lds_dwordx4 v246, s[26:27]
	s_add_u32 m0, s56, 0x8c00
	s_nop 0
	global_load_lds_dwordx4 v247, s[26:27]
	s_add_u32 s26, s26, 128
	s_addc_u32 s27, s27, 0
	v_mfma_f32_16x16x32_bf16 v[0:3], v[216:219], v[200:203], v[0:3]
	ds_read_b128 v[168:171], v166 offset:49152
	v_mfma_f32_16x16x32_bf16 v[4:7], v[220:223], v[200:203], v[4:7]
	ds_read_b128 v[184:187], v250 offset:0
	v_mfma_f32_16x16x32_bf16 v[8:11], v[228:231], v[200:203], v[8:11]
	ds_read_b128 v[172:175], v166 offset:51200
	v_mfma_f32_16x16x32_bf16 v[12:15], v[232:235], v[200:203], v[12:15]
	ds_read_b128 v[188:191], v250 offset:512
	v_mfma_f32_16x16x32_bf16 v[16:19], v[216:219], v[204:207], v[16:19]
	ds_read_b128 v[176:179], v166 offset:53248
	v_mfma_f32_16x16x32_bf16 v[20:23], v[220:223], v[204:207], v[20:23]
	ds_read_b128 v[192:195], v250 offset:1024
	v_mfma_f32_16x16x32_bf16 v[24:27], v[228:231], v[204:207], v[24:27]
	ds_read_b128 v[180:183], v166 offset:55296
	v_mfma_f32_16x16x32_bf16 v[28:31], v[232:235], v[204:207], v[28:31]
	ds_read_b128 v[196:199], v250 offset:1536
	v_mfma_f32_16x16x32_bf16 v[32:35], v[216:219], v[208:211], v[32:35]
	v_mfma_f32_16x16x32_bf16 v[36:39], v[220:223], v[208:211], v[36:39]
	v_mfma_f32_16x16x32_bf16 v[40:43], v[228:231], v[208:211], v[40:43]
	v_mfma_f32_16x16x32_bf16 v[44:47], v[232:235], v[208:211], v[44:47]
	v_mfma_f32_16x16x32_bf16 v[48:51], v[216:219], v[212:215], v[48:51]
	v_mfma_f32_16x16x32_bf16 v[52:55], v[220:223], v[212:215], v[52:55]
	v_mfma_f32_16x16x32_bf16 v[56:59], v[228:231], v[212:215], v[56:59]
	v_mfma_f32_16x16x32_bf16 v[60:63], v[232:235], v[212:215], v[60:63]
	s_add_u32 m0, s56, 0xc000
	s_nop 0
	global_load_lds_dwordx4 v236, s[24:25]
	s_add_u32 m0, s56, 0xc400
	s_nop 0
	global_load_lds_dwordx4 v237, s[24:25]
	s_add_u32 m0, s56, 0xc800
	s_nop 0
	global_load_lds_dwordx4 v238, s[24:25]
	s_add_u32 m0, s56, 0xcc00
	s_nop 0
	global_load_lds_dwordx4 v239, s[24:25]
	s_add_u32 s24, s24, 128
	s_addc_u32 s25, s25, 0
	s_waitcnt lgkmcnt(0)
	v_mfma_f32_16x16x32_bf16 v[0:3], v[184:187], v[168:171], v[0:3]
	ds_read_b128 v[200:203], v167 offset:49152
	v_mfma_f32_16x16x32_bf16 v[4:7], v[188:191], v[168:171], v[4:7]
	ds_read_b128 v[216:219], v251 offset:0
	v_mfma_f32_16x16x32_bf16 v[8:11], v[192:195], v[168:171], v[8:11]
	ds_read_b128 v[204:207], v167 offset:51200
	v_mfma_f32_16x16x32_bf16 v[12:15], v[196:199], v[168:171], v[12:15]
	ds_read_b128 v[220:223], v251 offset:512
	v_mfma_f32_16x16x32_bf16 v[16:19], v[184:187], v[172:175], v[16:19]
	ds_read_b128 v[208:211], v167 offset:53248
	v_mfma_f32_16x16x32_bf16 v[20:23], v[188:191], v[172:175], v[20:23]
	ds_read_b128 v[228:231], v251 offset:1024
	v_mfma_f32_16x16x32_bf16 v[24:27], v[192:195], v[172:175], v[24:27]
	ds_read_b128 v[212:215], v167 offset:55296
	v_mfma_f32_16x16x32_bf16 v[28:31], v[196:199], v[172:175], v[28:31]
	ds_read_b128 v[232:235], v251 offset:1536
	v_mfma_f32_16x16x32_bf16 v[32:35], v[184:187], v[176:179], v[32:35]
	v_mfma_f32_16x16x32_bf16 v[36:39], v[188:191], v[176:179], v[36:39]
	v_mfma_f32_16x16x32_bf16 v[40:43], v[192:195], v[176:179], v[40:43]
	v_mfma_f32_16x16x32_bf16 v[44:47], v[196:199], v[176:179], v[44:47]
	v_mfma_f32_16x16x32_bf16 v[48:51], v[184:187], v[180:183], v[48:51]
	v_mfma_f32_16x16x32_bf16 v[52:55], v[188:191], v[180:183], v[52:55]
	v_mfma_f32_16x16x32_bf16 v[56:59], v[192:195], v[180:183], v[56:59]
	v_mfma_f32_16x16x32_bf16 v[60:63], v[196:199], v[180:183], v[60:63]
	s_waitcnt vmcnt(4) lgkmcnt(0)
	s_barrier
; template <int NI> ...
;     ...
;   G_LOAD(a0, b0, 0);
;   G_LOAD(a1, b1, 32);
;   __syncthreads();
;   G_WRITE(a0, b0, 0);
;   __syncthreads();
;   for (int kt = 0; kt < nk; kt += 2) {
;     G_LOAD(a0, b0, min((kt + 2) * 32, klast));
;     G_COMPUTE(0);
;     G_WRITE(a1, b1, 1);
;     __syncthreads();
;     G_LOAD(a1, b1, min((kt + 3) * 32, klast));
;     G_COMPUTE(1);
;     G_WRITE(a0, b0, 0);
;     __syncthreads();
;   }
; __device__ void phase_merge4(CParams& p, int l, int tm, int tn, char* smem) {
;     ...
;     gemm_mainloop<4>(p.hbuf + (size_t)row0 * DM, DM,
;                      p.WgT + (((size_t)l * 4 + kb) * 1024 + col0) * 1024, 1024, 1024, sA, sB, acc, tid2);
	s_add_u32 m0, s56, 0x10000
	s_nop 0
	global_load_lds_dwordx4 v244, s[26:27]
	s_add_u32 m0, s56, 0x10400
	s_nop 0
	global_load_lds_dwordx4 v245, s[26:27]
	s_add_u32 m0, s56, 0x10800
	s_nop 0
	global_load_lds_dwordx4 v246, s[26:27]
	s_add_u32 m0, s56, 0x10c00
	s_nop 0
	global_load_lds_dwordx4 v247, s[26:27]
	s_add_u32 s26, s26, 128
	s_addc_u32 s27, s27, 0
	v_mfma_f32_16x16x32_bf16 v[0:3], v[216:219], v[200:203], v[0:3]
	ds_read_b128 v[168:171], v248 offset:16384
	v_mfma_f32_16x16x32_bf16 v[4:7], v[220:223], v[200:203], v[4:7]
	ds_read_b128 v[184:187], v250 offset:32768
	v_mfma_f32_16x16x32_bf16 v[8:11], v[228:231], v[200:203], v[8:11]
	ds_read_b128 v[172:175], v248 offset:18432
	v_mfma_f32_16x16x32_bf16 v[12:15], v[232:235], v[200:203], v[12:15]
	ds_read_b128 v[188:191], v250 offset:33280
	v_mfma_f32_16x16x32_bf16 v[16:19], v[216:219], v[204:207], v[16:19]
	ds_read_b128 v[176:179], v248 offset:20480
	v_mfma_f32_16x16x32_bf16 v[20:23], v[220:223], v[204:207], v[20:23]
	ds_read_b128 v[192:195], v250 offset:33792
	v_mfma_f32_16x16x32_bf16 v[24:27], v[228:231], v[204:207], v[24:27]
	ds_read_b128 v[180:183], v248 offset:22528
	v_mfma_f32_16x16x32_bf16 v[28:31], v[232:235], v[204:207], v[28:31]
	ds_read_b128 v[196:199], v250 offset:34304
	v_mfma_f32_16x16x32_bf16 v[32:35], v[216:219], v[208:211], v[32:35]
	v_mfma_f32_16x16x32_bf16 v[36:39], v[220:223], v[208:211], v[36:39]
	v_mfma_f32_16x16x32_bf16 v[40:43], v[228:231], v[208:211], v[40:43]
	v_mfma_f32_16x16x32_bf16 v[44:47], v[232:235], v[208:211], v[44:47]
	v_mfma_f32_16x16x32_bf16 v[48:51], v[216:219], v[212:215], v[48:51]
	v_mfma_f32_16x16x32_bf16 v[52:55], v[220:223], v[212:215], v[52:55]
	v_mfma_f32_16x16x32_bf16 v[56:59], v[228:231], v[212:215], v[56:59]
	v_mfma_f32_16x16x32_bf16 v[60:63], v[232:235], v[212:215], v[60:63]
	s_add_u32 m0, s56, 0x0
	s_nop 0
	global_load_lds_dwordx4 v236, s[24:25]
	s_add_u32 m0, s56, 0x400
	s_nop 0
	global_load_lds_dwordx4 v237, s[24:25]
	s_add_u32 m0, s56, 0x800
	s_nop 0
	global_load_lds_dwordx4 v238, s[24:25]
	s_add_u32 m0, s56, 0xc00
	s_nop 0
	global_load_lds_dwordx4 v239, s[24:25]
	s_add_u32 s24, s24, 128
	s_addc_u32 s25, s25, 0
	s_waitcnt lgkmcnt(0)
	v_mfma_f32_16x16x32_bf16 v[0:3], v[184:187], v[168:171], v[0:3]
	ds_read_b128 v[200:203], v249 offset:16384
	v_mfma_f32_16x16x32_bf16 v[4:7], v[188:191], v[168:171], v[4:7]
	ds_read_b128 v[216:219], v251 offset:32768
	v_mfma_f32_16x16x32_bf16 v[8:11], v[192:195], v[168:171], v[8:11]
	ds_read_b128 v[204:207], v249 offset:18432
	v_mfma_f32_16x16x32_bf16 v[12:15], v[196:199], v[168:171], v[12:15]
	ds_read_b128 v[220:223], v251 offset:33280
	v_mfma_f32_16x16x32_bf16 v[16:19], v[184:187], v[172:175], v[16:19]
	ds_read_b128 v[208:211], v249 offset:20480
	v_mfma_f32_16x16x32_bf16 v[20:23], v[188:191], v[172:175], v[20:23]
	ds_read_b128 v[228:231], v251 offset:33792
	v_mfma_f32_16x16x32_bf16 v[24:27], v[192:195], v[172:175], v[24:27]
	ds_read_b128 v[212:215], v249 offset:22528
	v_mfma_f32_16x16x32_bf16 v[28:31], v[196:199], v[172:175], v[28:31]
	ds_read_b128 v[232:235], v251 offset:34304
	v_mfma_f32_16x16x32_bf16 v[32:35], v[184:187], v[176:179], v[32:35]
	v_mfma_f32_16x16x32_bf16 v[36:39], v[188:191], v[176:179], v[36:39]
	v_mfma_f32_16x16x32_bf16 v[40:43], v[192:195], v[176:179], v[40:43]
	v_mfma_f32_16x16x32_bf16 v[44:47], v[196:199], v[176:179], v[44:47]
	v_mfma_f32_16x16x32_bf16 v[48:51], v[184:187], v[180:183], v[48:51]
	v_mfma_f32_16x16x32_bf16 v[52:55], v[188:191], v[180:183], v[52:55]
	v_mfma_f32_16x16x32_bf16 v[56:59], v[192:195], v[180:183], v[56:59]
	v_mfma_f32_16x16x32_bf16 v[60:63], v[196:199], v[180:183], v[60:63]
	s_waitcnt vmcnt(4) lgkmcnt(0)
	s_barrier
	s_add_u32 m0, s56, 0x4000
	s_nop 0
	global_load_lds_dwordx4 v244, s[26:27]
	s_add_u32 m0, s56, 0x4400
	s_nop 0
	global_load_lds_dwordx4 v245, s[26:27]
	s_add_u32 m0, s56, 0x4800
	s_nop 0
	global_load_lds_dwordx4 v246, s[26:27]
	s_add_u32 m0, s56, 0x4c00
	s_nop 0
	global_load_lds_dwordx4 v247, s[26:27]
	s_add_u32 s26, s26, 128
	s_addc_u32 s27, s27, 0
	v_mfma_f32_16x16x32_bf16 v[0:3], v[216:219], v[200:203], v[0:3]
	ds_read_b128 v[168:171], v248 offset:49152
	v_mfma_f32_16x16x32_bf16 v[4:7], v[220:223], v[200:203], v[4:7]
	ds_read_b128 v[184:187], v226 offset:49152
	v_mfma_f32_16x16x32_bf16 v[8:11], v[228:231], v[200:203], v[8:11]
	ds_read_b128 v[172:175], v248 offset:51200
	v_mfma_f32_16x16x32_bf16 v[12:15], v[232:235], v[200:203], v[12:15]
	ds_read_b128 v[188:191], v226 offset:49664
	v_mfma_f32_16x16x32_bf16 v[16:19], v[216:219], v[204:207], v[16:19]
	ds_read_b128 v[176:179], v248 offset:53248
	v_mfma_f32_16x16x32_bf16 v[20:23], v[220:223], v[204:207], v[20:23]
	ds_read_b128 v[192:195], v226 offset:50176
	v_mfma_f32_16x16x32_bf16 v[24:27], v[228:231], v[204:207], v[24:27]
	ds_read_b128 v[180:183], v248 offset:55296
	v_mfma_f32_16x16x32_bf16 v[28:31], v[232:235], v[204:207], v[28:31]
	ds_read_b128 v[196:199], v226 offset:50688
	v_mfma_f32_16x16x32_bf16 v[32:35], v[216:219], v[208:211], v[32:35]
	v_mfma_f32_16x16x32_bf16 v[36:39], v[220:223], v[208:211], v[36:39]
	v_mfma_f32_16x16x32_bf16 v[40:43], v[228:231], v[208:211], v[40:43]
	v_mfma_f32_16x16x32_bf16 v[44:47], v[232:235], v[208:211], v[44:47]
	v_mfma_f32_16x16x32_bf16 v[48:51], v[216:219], v[212:215], v[48:51]
	v_mfma_f32_16x16x32_bf16 v[52:55], v[220:223], v[212:215], v[52:55]
	v_mfma_f32_16x16x32_bf16 v[56:59], v[228:231], v[212:215], v[56:59]
	v_mfma_f32_16x16x32_bf16 v[60:63], v[232:235], v[212:215], v[60:63]
	s_add_u32 m0, s56, 0x8000
	s_nop 0
	global_load_lds_dwordx4 v236, s[24:25]
	s_add_u32 m0, s56, 0x8400
	s_nop 0
	global_load_lds_dwordx4 v237, s[24:25]
	s_add_u32 m0, s56, 0x8800
	s_nop 0
	global_load_lds_dwordx4 v238, s[24:25]
	s_add_u32 m0, s56, 0x8c00
	s_nop 0
	global_load_lds_dwordx4 v239, s[24:25]
	s_add_u32 s24, s24, 128
	s_addc_u32 s25, s25, 0
	s_waitcnt lgkmcnt(0)
; template <int NI> ...
;     ...
;   G_LOAD(a0, b0, 0);
;   G_LOAD(a1, b1, 32);
;   __syncthreads();
;   G_WRITE(a0, b0, 0);
;   __syncthreads();
;   for (int kt = 0; kt < nk; kt += 2) {
;     G_LOAD(a0, b0, min((kt + 2) * 32, klast));
;     G_COMPUTE(0);
;     G_WRITE(a1, b1, 1);
;     __syncthreads();
;     G_LOAD(a1, b1, min((kt + 3) * 32, klast));
;     G_COMPUTE(1);
;     G_WRITE(a0, b0, 0);
;     __syncthreads();
;   }
; __device__ void phase_merge4(CParams& p, int l, int tm, int tn, char* smem) {
;     ...
;     gemm_mainloop<4>(p.hbuf + (size_t)row0 * DM, DM,
;                      p.WgT + (((size_t)l * 4 + kb) * 1024 + col0) * 1024, 1024, 1024, sA, sB, acc, tid2);
	v_mfma_f32_16x16x32_bf16 v[0:3], v[184:187], v[168:171], v[0:3]
	ds_read_b128 v[200:203], v249 offset:49152
	v_mfma_f32_16x16x32_bf16 v[4:7], v[188:191], v[168:171], v[4:7]
	ds_read_b128 v[216:219], v227 offset:49152
	v_mfma_f32_16x16x32_bf16 v[8:11], v[192:195], v[168:171], v[8:11]
	ds_read_b128 v[204:207], v249 offset:51200
	v_mfma_f32_16x16x32_bf16 v[12:15], v[196:199], v[168:171], v[12:15]
	ds_read_b128 v[220:223], v227 offset:49664
	v_mfma_f32_16x16x32_bf16 v[16:19], v[184:187], v[172:175], v[16:19]
	ds_read_b128 v[208:211], v249 offset:53248
	v_mfma_f32_16x16x32_bf16 v[20:23], v[188:191], v[172:175], v[20:23]
	ds_read_b128 v[228:231], v227 offset:50176
	v_mfma_f32_16x16x32_bf16 v[24:27], v[192:195], v[172:175], v[24:27]
	ds_read_b128 v[212:215], v249 offset:55296
	v_mfma_f32_16x16x32_bf16 v[28:31], v[196:199], v[172:175], v[28:31]
	ds_read_b128 v[232:235], v227 offset:50688
	v_mfma_f32_16x16x32_bf16 v[32:35], v[184:187], v[176:179], v[32:35]
	v_mfma_f32_16x16x32_bf16 v[36:39], v[188:191], v[176:179], v[36:39]
	v_mfma_f32_16x16x32_bf16 v[40:43], v[192:195], v[176:179], v[40:43]
	v_mfma_f32_16x16x32_bf16 v[44:47], v[196:199], v[176:179], v[44:47]
	v_mfma_f32_16x16x32_bf16 v[48:51], v[184:187], v[180:183], v[48:51]
	v_mfma_f32_16x16x32_bf16 v[52:55], v[188:191], v[180:183], v[52:55]
	v_mfma_f32_16x16x32_bf16 v[56:59], v[192:195], v[180:183], v[56:59]
	v_mfma_f32_16x16x32_bf16 v[60:63], v[196:199], v[180:183], v[60:63]
	s_waitcnt vmcnt(4) lgkmcnt(0)
	s_barrier
	s_add_u32 m0, s56, 0xc000
	s_nop 0
	global_load_lds_dwordx4 v244, s[26:27]
	s_add_u32 m0, s56, 0xc400
	s_nop 0
	global_load_lds_dwordx4 v245, s[26:27]
	s_add_u32 m0, s56, 0xc800
	s_nop 0
	global_load_lds_dwordx4 v246, s[26:27]
	s_add_u32 m0, s56, 0xcc00
	s_nop 0
	global_load_lds_dwordx4 v247, s[26:27]
	s_add_u32 s26, s26, 128
	s_addc_u32 s27, s27, 0
	v_mfma_f32_16x16x32_bf16 v[0:3], v[216:219], v[200:203], v[0:3]
	ds_read_b128 v[168:171], v248 offset:0
	v_mfma_f32_16x16x32_bf16 v[4:7], v[220:223], v[200:203], v[4:7]
	ds_read_b128 v[184:187], v250 offset:16384
	v_mfma_f32_16x16x32_bf16 v[8:11], v[228:231], v[200:203], v[8:11]
	ds_read_b128 v[172:175], v248 offset:2048
	v_mfma_f32_16x16x32_bf16 v[12:15], v[232:235], v[200:203], v[12:15]
	ds_read_b128 v[188:191], v250 offset:16896
	v_mfma_f32_16x16x32_bf16 v[16:19], v[216:219], v[204:207], v[16:19]
	ds_read_b128 v[176:179], v248 offset:4096
	v_mfma_f32_16x16x32_bf16 v[20:23], v[220:223], v[204:207], v[20:23]
	ds_read_b128 v[192:195], v250 offset:17408
	v_mfma_f32_16x16x32_bf16 v[24:27], v[228:231], v[204:207], v[24:27]
	ds_read_b128 v[180:183], v248 offset:6144
	v_mfma_f32_16x16x32_bf16 v[28:31], v[232:235], v[204:207], v[28:31]
	ds_read_b128 v[196:199], v250 offset:17920
	v_mfma_f32_16x16x32_bf16 v[32:35], v[216:219], v[208:211], v[32:35]
	v_mfma_f32_16x16x32_bf16 v[36:39], v[220:223], v[208:211], v[36:39]
	v_mfma_f32_16x16x32_bf16 v[40:43], v[228:231], v[208:211], v[40:43]
	v_mfma_f32_16x16x32_bf16 v[44:47], v[232:235], v[208:211], v[44:47]
	v_mfma_f32_16x16x32_bf16 v[48:51], v[216:219], v[212:215], v[48:51]
	v_mfma_f32_16x16x32_bf16 v[52:55], v[220:223], v[212:215], v[52:55]
	v_mfma_f32_16x16x32_bf16 v[56:59], v[228:231], v[212:215], v[56:59]
	v_mfma_f32_16x16x32_bf16 v[60:63], v[232:235], v[212:215], v[60:63]
	s_add_u32 m0, s56, 0x10000
	s_nop 0
	global_load_lds_dwordx4 v236, s[24:25]
	s_add_u32 m0, s56, 0x10400
	s_nop 0
	global_load_lds_dwordx4 v237, s[24:25]
	s_add_u32 m0, s56, 0x10800
	s_nop 0
	global_load_lds_dwordx4 v238, s[24:25]
	s_add_u32 m0, s56, 0x10c00
	s_nop 0
	global_load_lds_dwordx4 v239, s[24:25]
	s_add_u32 s24, s24, 128
	s_addc_u32 s25, s25, 0
	s_waitcnt lgkmcnt(0)
	v_mfma_f32_16x16x32_bf16 v[0:3], v[184:187], v[168:171], v[0:3]
	ds_read_b128 v[200:203], v249 offset:0
	v_mfma_f32_16x16x32_bf16 v[4:7], v[188:191], v[168:171], v[4:7]
	ds_read_b128 v[216:219], v251 offset:16384
	v_mfma_f32_16x16x32_bf16 v[8:11], v[192:195], v[168:171], v[8:11]
	ds_read_b128 v[204:207], v249 offset:2048
	v_mfma_f32_16x16x32_bf16 v[12:15], v[196:199], v[168:171], v[12:15]
	ds_read_b128 v[220:223], v251 offset:16896
	v_mfma_f32_16x16x32_bf16 v[16:19], v[184:187], v[172:175], v[16:19]
	ds_read_b128 v[208:211], v249 offset:4096
	v_mfma_f32_16x16x32_bf16 v[20:23], v[188:191], v[172:175], v[20:23]
	ds_read_b128 v[228:231], v251 offset:17408
	v_mfma_f32_16x16x32_bf16 v[24:27], v[192:195], v[172:175], v[24:27]
	ds_read_b128 v[212:215], v249 offset:6144
	v_mfma_f32_16x16x32_bf16 v[28:31], v[196:199], v[172:175], v[28:31]
	ds_read_b128 v[232:235], v251 offset:17920
	v_mfma_f32_16x16x32_bf16 v[32:35], v[184:187], v[176:179], v[32:35]
	v_mfma_f32_16x16x32_bf16 v[36:39], v[188:191], v[176:179], v[36:39]
	v_mfma_f32_16x16x32_bf16 v[40:43], v[192:195], v[176:179], v[40:43]
	v_mfma_f32_16x16x32_bf16 v[44:47], v[196:199], v[176:179], v[44:47]
	v_mfma_f32_16x16x32_bf16 v[48:51], v[184:187], v[180:183], v[48:51]
	v_mfma_f32_16x16x32_bf16 v[52:55], v[188:191], v[180:183], v[52:55]
	v_mfma_f32_16x16x32_bf16 v[56:59], v[192:195], v[180:183], v[56:59]
	v_mfma_f32_16x16x32_bf16 v[60:63], v[196:199], v[180:183], v[60:63]
	s_waitcnt vmcnt(4) lgkmcnt(0)
	s_barrier
; template <int NI> ...
;     ...
;   G_LOAD(a0, b0, 0);
;   G_LOAD(a1, b1, 32);
;   __syncthreads();
;   G_WRITE(a0, b0, 0);
;   __syncthreads();
;   for (int kt = 0; kt < nk; kt += 2) {
;     G_LOAD(a0, b0, min((kt + 2) * 32, klast));
;     G_COMPUTE(0);
;     G_WRITE(a1, b1, 1);
;     __syncthreads();
;     G_LOAD(a1, b1, min((kt + 3) * 32, klast));
;     G_COMPUTE(1);
;     G_WRITE(a0, b0, 0);
;     __syncthreads();
;   }
; __device__ void phase_merge4(CParams& p, int l, int tm, int tn, char* smem) {
;     ...
;     gemm_mainloop<4>(p.hbuf + (size_t)row0 * DM, DM,
;                      p.WgT + (((size_t)l * 4 + kb) * 1024 + col0) * 1024, 1024, 1024, sA, sB, acc, tid2);
	s_add_u32 m0, s56, 0x0
	s_nop 0
	global_load_lds_dwordx4 v244, s[26:27]
	s_add_u32 m0, s56, 0x400
	s_nop 0
	global_load_lds_dwordx4 v245, s[26:27]
	s_add_u32 m0, s56, 0x800
	s_nop 0
	global_load_lds_dwordx4 v246, s[26:27]
	s_add_u32 m0, s56, 0xc00
	s_nop 0
	global_load_lds_dwordx4 v247, s[26:27]
	s_add_u32 s26, s26, 128
	s_addc_u32 s27, s27, 0
	v_mfma_f32_16x16x32_bf16 v[0:3], v[216:219], v[200:203], v[0:3]
	ds_read_b128 v[168:171], v248 offset:32768
	v_mfma_f32_16x16x32_bf16 v[4:7], v[220:223], v[200:203], v[4:7]
	ds_read_b128 v[184:187], v250 offset:49152
	v_mfma_f32_16x16x32_bf16 v[8:11], v[228:231], v[200:203], v[8:11]
	ds_read_b128 v[172:175], v248 offset:34816
	v_mfma_f32_16x16x32_bf16 v[12:15], v[232:235], v[200:203], v[12:15]
	ds_read_b128 v[188:191], v250 offset:49664
	v_mfma_f32_16x16x32_bf16 v[16:19], v[216:219], v[204:207], v[16:19]
	ds_read_b128 v[176:179], v248 offset:36864
	v_mfma_f32_16x16x32_bf16 v[20:23], v[220:223], v[204:207], v[20:23]
	ds_read_b128 v[192:195], v250 offset:50176
	v_mfma_f32_16x16x32_bf16 v[24:27], v[228:231], v[204:207], v[24:27]
	ds_read_b128 v[180:183], v248 offset:38912
	v_mfma_f32_16x16x32_bf16 v[28:31], v[232:235], v[204:207], v[28:31]
	ds_read_b128 v[196:199], v250 offset:50688
	v_mfma_f32_16x16x32_bf16 v[32:35], v[216:219], v[208:211], v[32:35]
	v_mfma_f32_16x16x32_bf16 v[36:39], v[220:223], v[208:211], v[36:39]
	v_mfma_f32_16x16x32_bf16 v[40:43], v[228:231], v[208:211], v[40:43]
	v_mfma_f32_16x16x32_bf16 v[44:47], v[232:235], v[208:211], v[44:47]
	v_mfma_f32_16x16x32_bf16 v[48:51], v[216:219], v[212:215], v[48:51]
	v_mfma_f32_16x16x32_bf16 v[52:55], v[220:223], v[212:215], v[52:55]
	v_mfma_f32_16x16x32_bf16 v[56:59], v[228:231], v[212:215], v[56:59]
	v_mfma_f32_16x16x32_bf16 v[60:63], v[232:235], v[212:215], v[60:63]
	s_add_u32 m0, s56, 0x4000
	s_nop 0
	global_load_lds_dwordx4 v236, s[24:25]
	s_add_u32 m0, s56, 0x4400
	s_nop 0
	global_load_lds_dwordx4 v237, s[24:25]
	s_add_u32 m0, s56, 0x4800
	s_nop 0
	global_load_lds_dwordx4 v238, s[24:25]
	s_add_u32 m0, s56, 0x4c00
	s_nop 0
	global_load_lds_dwordx4 v239, s[24:25]
	s_add_u32 s24, s24, 128
	s_addc_u32 s25, s25, 0
	s_waitcnt lgkmcnt(0)
	v_mfma_f32_16x16x32_bf16 v[0:3], v[184:187], v[168:171], v[0:3]
	ds_read_b128 v[200:203], v249 offset:32768
	v_mfma_f32_16x16x32_bf16 v[4:7], v[188:191], v[168:171], v[4:7]
	ds_read_b128 v[216:219], v251 offset:49152
	v_mfma_f32_16x16x32_bf16 v[8:11], v[192:195], v[168:171], v[8:11]
	ds_read_b128 v[204:207], v249 offset:34816
	v_mfma_f32_16x16x32_bf16 v[12:15], v[196:199], v[168:171], v[12:15]
	ds_read_b128 v[220:223], v251 offset:49664
	v_mfma_f32_16x16x32_bf16 v[16:19], v[184:187], v[172:175], v[16:19]
	ds_read_b128 v[208:211], v249 offset:36864
	v_mfma_f32_16x16x32_bf16 v[20:23], v[188:191], v[172:175], v[20:23]
	ds_read_b128 v[228:231], v251 offset:50176
	v_mfma_f32_16x16x32_bf16 v[24:27], v[192:195], v[172:175], v[24:27]
	ds_read_b128 v[212:215], v249 offset:38912
	v_mfma_f32_16x16x32_bf16 v[28:31], v[196:199], v[172:175], v[28:31]
	ds_read_b128 v[232:235], v251 offset:50688
	v_mfma_f32_16x16x32_bf16 v[32:35], v[184:187], v[176:179], v[32:35]
	v_mfma_f32_16x16x32_bf16 v[36:39], v[188:191], v[176:179], v[36:39]
	v_mfma_f32_16x16x32_bf16 v[40:43], v[192:195], v[176:179], v[40:43]
	v_mfma_f32_16x16x32_bf16 v[44:47], v[196:199], v[176:179], v[44:47]
	v_mfma_f32_16x16x32_bf16 v[48:51], v[184:187], v[180:183], v[48:51]
	v_mfma_f32_16x16x32_bf16 v[52:55], v[188:191], v[180:183], v[52:55]
	v_mfma_f32_16x16x32_bf16 v[56:59], v[192:195], v[180:183], v[56:59]
	v_mfma_f32_16x16x32_bf16 v[60:63], v[196:199], v[180:183], v[60:63]
	s_waitcnt vmcnt(4) lgkmcnt(0)
	s_barrier
	s_add_u32 m0, s56, 0x8000
	s_nop 0
	global_load_lds_dwordx4 v244, s[26:27]
	s_add_u32 m0, s56, 0x8400
	s_nop 0
	global_load_lds_dwordx4 v245, s[26:27]
	s_add_u32 m0, s56, 0x8800
	s_nop 0
	global_load_lds_dwordx4 v246, s[26:27]
	s_add_u32 m0, s56, 0x8c00
	s_nop 0
	global_load_lds_dwordx4 v247, s[26:27]
	s_add_u32 s26, s26, 128
	s_addc_u32 s27, s27, 0
	v_mfma_f32_16x16x32_bf16 v[0:3], v[216:219], v[200:203], v[0:3]
	ds_read_b128 v[168:171], v166 offset:49152
	v_mfma_f32_16x16x32_bf16 v[4:7], v[220:223], v[200:203], v[4:7]
	ds_read_b128 v[184:187], v250 offset:0
	v_mfma_f32_16x16x32_bf16 v[8:11], v[228:231], v[200:203], v[8:11]
	ds_read_b128 v[172:175], v166 offset:51200
	v_mfma_f32_16x16x32_bf16 v[12:15], v[232:235], v[200:203], v[12:15]
	ds_read_b128 v[188:191], v250 offset:512
	v_mfma_f32_16x16x32_bf16 v[16:19], v[216:219], v[204:207], v[16:19]
	ds_read_b128 v[176:179], v166 offset:53248
	v_mfma_f32_16x16x32_bf16 v[20:23], v[220:223], v[204:207], v[20:23]
	ds_read_b128 v[192:195], v250 offset:1024
	v_mfma_f32_16x16x32_bf16 v[24:27], v[228:231], v[204:207], v[24:27]
	ds_read_b128 v[180:183], v166 offset:55296
	v_mfma_f32_16x16x32_bf16 v[28:31], v[232:235], v[204:207], v[28:31]
	ds_read_b128 v[196:199], v250 offset:1536
	v_mfma_f32_16x16x32_bf16 v[32:35], v[216:219], v[208:211], v[32:35]
	v_mfma_f32_16x16x32_bf16 v[36:39], v[220:223], v[208:211], v[36:39]
	v_mfma_f32_16x16x32_bf16 v[40:43], v[228:231], v[208:211], v[40:43]
	v_mfma_f32_16x16x32_bf16 v[44:47], v[232:235], v[208:211], v[44:47]
	v_mfma_f32_16x16x32_bf16 v[48:51], v[216:219], v[212:215], v[48:51]
	v_mfma_f32_16x16x32_bf16 v[52:55], v[220:223], v[212:215], v[52:55]
	v_mfma_f32_16x16x32_bf16 v[56:59], v[228:231], v[212:215], v[56:59]
	v_mfma_f32_16x16x32_bf16 v[60:63], v[232:235], v[212:215], v[60:63]
	s_add_u32 m0, s56, 0xc000
	s_nop 0
	global_load_lds_dwordx4 v236, s[24:25]
	s_add_u32 m0, s56, 0xc400
	s_nop 0
	global_load_lds_dwordx4 v237, s[24:25]
	s_add_u32 m0, s56, 0xc800
	s_nop 0
	global_load_lds_dwordx4 v238, s[24:25]
	s_add_u32 m0, s56, 0xcc00
	s_nop 0
	global_load_lds_dwordx4 v239, s[24:25]
	s_add_u32 s24, s24, 128
	s_addc_u32 s25, s25, 0
	s_waitcnt lgkmcnt(0)
; template <int NI> ...
;     ...
;   G_LOAD(a0, b0, 0);
;   G_LOAD(a1, b1, 32);
;   __syncthreads();
;   G_WRITE(a0, b0, 0);
;   __syncthreads();
;   for (int kt = 0; kt < nk; kt += 2) {
;     G_LOAD(a0, b0, min((kt + 2) * 32, klast));
;     G_COMPUTE(0);
;     G_WRITE(a1, b1, 1);
;     __syncthreads();
;     G_LOAD(a1, b1, min((kt + 3) * 32, klast));
;     G_COMPUTE(1);
;     G_WRITE(a0, b0, 0);
;     __syncthreads();
;   }
; __device__ void phase_merge4(CParams& p, int l, int tm, int tn, char* smem) {
;     ...
;     gemm_mainloop<4>(p.hbuf + (size_t)row0 * DM, DM,
;                      p.WgT + (((size_t)l * 4 + kb) * 1024 + col0) * 1024, 1024, 1024, sA, sB, acc, tid2);
	v_mfma_f32_16x16x32_bf16 v[0:3], v[184:187], v[168:171], v[0:3]
	ds_read_b128 v[200:203], v167 offset:49152
	v_mfma_f32_16x16x32_bf16 v[4:7], v[188:191], v[168:171], v[4:7]
	ds_read_b128 v[216:219], v251 offset:0
	v_mfma_f32_16x16x32_bf16 v[8:11], v[192:195], v[168:171], v[8:11]
	ds_read_b128 v[204:207], v167 offset:51200
	v_mfma_f32_16x16x32_bf16 v[12:15], v[196:199], v[168:171], v[12:15]
	ds_read_b128 v[220:223], v251 offset:512
	v_mfma_f32_16x16x32_bf16 v[16:19], v[184:187], v[172:175], v[16:19]
	ds_read_b128 v[208:211], v167 offset:53248
	v_mfma_f32_16x16x32_bf16 v[20:23], v[188:191], v[172:175], v[20:23]
	ds_read_b128 v[228:231], v251 offset:1024
	v_mfma_f32_16x16x32_bf16 v[24:27], v[192:195], v[172:175], v[24:27]
	ds_read_b128 v[212:215], v167 offset:55296
	v_mfma_f32_16x16x32_bf16 v[28:31], v[196:199], v[172:175], v[28:31]
	ds_read_b128 v[232:235], v251 offset:1536
	v_mfma_f32_16x16x32_bf16 v[32:35], v[184:187], v[176:179], v[32:35]
	v_mfma_f32_16x16x32_bf16 v[36:39], v[188:191], v[176:179], v[36:39]
	v_mfma_f32_16x16x32_bf16 v[40:43], v[192:195], v[176:179], v[40:43]
	v_mfma_f32_16x16x32_bf16 v[44:47], v[196:199], v[176:179], v[44:47]
	v_mfma_f32_16x16x32_bf16 v[48:51], v[184:187], v[180:183], v[48:51]
	v_mfma_f32_16x16x32_bf16 v[52:55], v[188:191], v[180:183], v[52:55]
	v_mfma_f32_16x16x32_bf16 v[56:59], v[192:195], v[180:183], v[56:59]
	v_mfma_f32_16x16x32_bf16 v[60:63], v[196:199], v[180:183], v[60:63]
	s_waitcnt vmcnt(4) lgkmcnt(0)
	s_barrier
	s_add_u32 m0, s56, 0x10000
	s_nop 0
	global_load_lds_dwordx4 v244, s[26:27]
	s_add_u32 m0, s56, 0x10400
	s_nop 0
	global_load_lds_dwordx4 v245, s[26:27]
	s_add_u32 m0, s56, 0x10800
	s_nop 0
	global_load_lds_dwordx4 v246, s[26:27]
	s_add_u32 m0, s56, 0x10c00
	s_nop 0
	global_load_lds_dwordx4 v247, s[26:27]
	s_add_u32 s26, s26, 128
	s_addc_u32 s27, s27, 0
	v_mfma_f32_16x16x32_bf16 v[0:3], v[216:219], v[200:203], v[0:3]
	ds_read_b128 v[168:171], v248 offset:16384
	v_mfma_f32_16x16x32_bf16 v[4:7], v[220:223], v[200:203], v[4:7]
	ds_read_b128 v[184:187], v250 offset:32768
	v_mfma_f32_16x16x32_bf16 v[8:11], v[228:231], v[200:203], v[8:11]
	ds_read_b128 v[172:175], v248 offset:18432
	v_mfma_f32_16x16x32_bf16 v[12:15], v[232:235], v[200:203], v[12:15]
	ds_read_b128 v[188:191], v250 offset:33280
	v_mfma_f32_16x16x32_bf16 v[16:19], v[216:219], v[204:207], v[16:19]
	ds_read_b128 v[176:179], v248 offset:20480
	v_mfma_f32_16x16x32_bf16 v[20:23], v[220:223], v[204:207], v[20:23]
	ds_read_b128 v[192:195], v250 offset:33792
	v_mfma_f32_16x16x32_bf16 v[24:27], v[228:231], v[204:207], v[24:27]
	ds_read_b128 v[180:183], v248 offset:22528
	v_mfma_f32_16x16x32_bf16 v[28:31], v[232:235], v[204:207], v[28:31]
	ds_read_b128 v[196:199], v250 offset:34304
	v_mfma_f32_16x16x32_bf16 v[32:35], v[216:219], v[208:211], v[32:35]
	v_mfma_f32_16x16x32_bf16 v[36:39], v[220:223], v[208:211], v[36:39]
	v_mfma_f32_16x16x32_bf16 v[40:43], v[228:231], v[208:211], v[40:43]
	v_mfma_f32_16x16x32_bf16 v[44:47], v[232:235], v[208:211], v[44:47]
	v_mfma_f32_16x16x32_bf16 v[48:51], v[216:219], v[212:215], v[48:51]
	v_mfma_f32_16x16x32_bf16 v[52:55], v[220:223], v[212:215], v[52:55]
	v_mfma_f32_16x16x32_bf16 v[56:59], v[228:231], v[212:215], v[56:59]
	v_mfma_f32_16x16x32_bf16 v[60:63], v[232:235], v[212:215], v[60:63]
	s_add_u32 m0, s56, 0x0
	s_nop 0
	global_load_lds_dwordx4 v236, s[24:25]
	s_add_u32 m0, s56, 0x400
	s_nop 0
	global_load_lds_dwordx4 v237, s[24:25]
	s_add_u32 m0, s56, 0x800
	s_nop 0
	global_load_lds_dwordx4 v238, s[24:25]
	s_add_u32 m0, s56, 0xc00
	s_nop 0
	global_load_lds_dwordx4 v239, s[24:25]
	s_add_u32 s24, s24, 128
	s_addc_u32 s25, s25, 0
	s_waitcnt lgkmcnt(0)
	v_mfma_f32_16x16x32_bf16 v[0:3], v[184:187], v[168:171], v[0:3]
	ds_read_b128 v[200:203], v249 offset:16384
	v_mfma_f32_16x16x32_bf16 v[4:7], v[188:191], v[168:171], v[4:7]
	ds_read_b128 v[216:219], v251 offset:32768
	v_mfma_f32_16x16x32_bf16 v[8:11], v[192:195], v[168:171], v[8:11]
	ds_read_b128 v[204:207], v249 offset:18432
	v_mfma_f32_16x16x32_bf16 v[12:15], v[196:199], v[168:171], v[12:15]
	ds_read_b128 v[220:223], v251 offset:33280
	v_mfma_f32_16x16x32_bf16 v[16:19], v[184:187], v[172:175], v[16:19]
	ds_read_b128 v[208:211], v249 offset:20480
	v_mfma_f32_16x16x32_bf16 v[20:23], v[188:191], v[172:175], v[20:23]
	ds_read_b128 v[228:231], v251 offset:33792
	v_mfma_f32_16x16x32_bf16 v[24:27], v[192:195], v[172:175], v[24:27]
	ds_read_b128 v[212:215], v249 offset:22528
	v_mfma_f32_16x16x32_bf16 v[28:31], v[196:199], v[172:175], v[28:31]
	ds_read_b128 v[232:235], v251 offset:34304
	v_mfma_f32_16x16x32_bf16 v[32:35], v[184:187], v[176:179], v[32:35]
	v_mfma_f32_16x16x32_bf16 v[36:39], v[188:191], v[176:179], v[36:39]
	v_mfma_f32_16x16x32_bf16 v[40:43], v[192:195], v[176:179], v[40:43]
	v_mfma_f32_16x16x32_bf16 v[44:47], v[196:199], v[176:179], v[44:47]
	v_mfma_f32_16x16x32_bf16 v[48:51], v[184:187], v[180:183], v[48:51]
	v_mfma_f32_16x16x32_bf16 v[52:55], v[188:191], v[180:183], v[52:55]
	v_mfma_f32_16x16x32_bf16 v[56:59], v[192:195], v[180:183], v[56:59]
	v_mfma_f32_16x16x32_bf16 v[60:63], v[196:199], v[180:183], v[60:63]
	s_waitcnt vmcnt(4) lgkmcnt(0)
	s_barrier
; template <int NI> ...
;     ...
;   G_LOAD(a0, b0, 0);
;   G_LOAD(a1, b1, 32);
;   __syncthreads();
;   G_WRITE(a0, b0, 0);
;   __syncthreads();
;   for (int kt = 0; kt < nk; kt += 2) {
;     G_LOAD(a0, b0, min((kt + 2) * 32, klast));
;     G_COMPUTE(0);
;     G_WRITE(a1, b1, 1);
;     __syncthreads();
;     G_LOAD(a1, b1, min((kt + 3) * 32, klast));
;     G_COMPUTE(1);
;     G_WRITE(a0, b0, 0);
;     __syncthreads();
;   }
; __device__ void phase_merge4(CParams& p, int l, int tm, int tn, char* smem) {
;     ...
;     gemm_mainloop<4>(p.hbuf + (size_t)row0 * DM, DM,
;                      p.WgT + (((size_t)l * 4 + kb) * 1024 + col0) * 1024, 1024, 1024, sA, sB, acc, tid2);
	s_add_u32 m0, s56, 0x4000
	s_nop 0
	global_load_lds_dwordx4 v244, s[26:27]
	s_add_u32 m0, s56, 0x4400
	s_nop 0
	global_load_lds_dwordx4 v245, s[26:27]
	s_add_u32 m0, s56, 0x4800
	s_nop 0
	global_load_lds_dwordx4 v246, s[26:27]
	s_add_u32 m0, s56, 0x4c00
	s_nop 0
	global_load_lds_dwordx4 v247, s[26:27]
	s_add_u32 s26, s26, 128
	s_addc_u32 s27, s27, 0
	v_mfma_f32_16x16x32_bf16 v[0:3], v[216:219], v[200:203], v[0:3]
	ds_read_b128 v[168:171], v248 offset:49152
	v_mfma_f32_16x16x32_bf16 v[4:7], v[220:223], v[200:203], v[4:7]
	ds_read_b128 v[184:187], v226 offset:49152
	v_mfma_f32_16x16x32_bf16 v[8:11], v[228:231], v[200:203], v[8:11]
	ds_read_b128 v[172:175], v248 offset:51200
	v_mfma_f32_16x16x32_bf16 v[12:15], v[232:235], v[200:203], v[12:15]
	ds_read_b128 v[188:191], v226 offset:49664
	v_mfma_f32_16x16x32_bf16 v[16:19], v[216:219], v[204:207], v[16:19]
	ds_read_b128 v[176:179], v248 offset:53248
	v_mfma_f32_16x16x32_bf16 v[20:23], v[220:223], v[204:207], v[20:23]
	ds_read_b128 v[192:195], v226 offset:50176
	v_mfma_f32_16x16x32_bf16 v[24:27], v[228:231], v[204:207], v[24:27]
	ds_read_b128 v[180:183], v248 offset:55296
	v_mfma_f32_16x16x32_bf16 v[28:31], v[232:235], v[204:207], v[28:31]
	ds_read_b128 v[196:199], v226 offset:50688
	v_mfma_f32_16x16x32_bf16 v[32:35], v[216:219], v[208:211], v[32:35]
	v_mfma_f32_16x16x32_bf16 v[36:39], v[220:223], v[208:211], v[36:39]
	v_mfma_f32_16x16x32_bf16 v[40:43], v[228:231], v[208:211], v[40:43]
	v_mfma_f32_16x16x32_bf16 v[44:47], v[232:235], v[208:211], v[44:47]
	v_mfma_f32_16x16x32_bf16 v[48:51], v[216:219], v[212:215], v[48:51]
	v_mfma_f32_16x16x32_bf16 v[52:55], v[220:223], v[212:215], v[52:55]
	v_mfma_f32_16x16x32_bf16 v[56:59], v[228:231], v[212:215], v[56:59]
	v_mfma_f32_16x16x32_bf16 v[60:63], v[232:235], v[212:215], v[60:63]
	s_add_u32 m0, s56, 0x8000
	s_nop 0
	global_load_lds_dwordx4 v236, s[24:25]
	s_add_u32 m0, s56, 0x8400
	s_nop 0
	global_load_lds_dwordx4 v237, s[24:25]
	s_add_u32 m0, s56, 0x8800
	s_nop 0
	global_load_lds_dwordx4 v238, s[24:25]
	s_add_u32 m0, s56, 0x8c00
	s_nop 0
	global_load_lds_dwordx4 v239, s[24:25]
	s_add_u32 s24, s24, 128
	s_addc_u32 s25, s25, 0
	s_waitcnt lgkmcnt(0)
	v_mfma_f32_16x16x32_bf16 v[0:3], v[184:187], v[168:171], v[0:3]
	ds_read_b128 v[200:203], v249 offset:49152
	v_mfma_f32_16x16x32_bf16 v[4:7], v[188:191], v[168:171], v[4:7]
	ds_read_b128 v[216:219], v227 offset:49152
	v_mfma_f32_16x16x32_bf16 v[8:11], v[192:195], v[168:171], v[8:11]
	ds_read_b128 v[204:207], v249 offset:51200
	v_mfma_f32_16x16x32_bf16 v[12:15], v[196:199], v[168:171], v[12:15]
	ds_read_b128 v[220:223], v227 offset:49664
	v_mfma_f32_16x16x32_bf16 v[16:19], v[184:187], v[172:175], v[16:19]
	ds_read_b128 v[208:211], v249 offset:53248
	v_mfma_f32_16x16x32_bf16 v[20:23], v[188:191], v[172:175], v[20:23]
	ds_read_b128 v[228:231], v227 offset:50176
	v_mfma_f32_16x16x32_bf16 v[24:27], v[192:195], v[172:175], v[24:27]
	ds_read_b128 v[212:215], v249 offset:55296
	v_mfma_f32_16x16x32_bf16 v[28:31], v[196:199], v[172:175], v[28:31]
	ds_read_b128 v[232:235], v227 offset:50688
	v_mfma_f32_16x16x32_bf16 v[32:35], v[184:187], v[176:179], v[32:35]
	v_mfma_f32_16x16x32_bf16 v[36:39], v[188:191], v[176:179], v[36:39]
	v_mfma_f32_16x16x32_bf16 v[40:43], v[192:195], v[176:179], v[40:43]
	v_mfma_f32_16x16x32_bf16 v[44:47], v[196:199], v[176:179], v[44:47]
	v_mfma_f32_16x16x32_bf16 v[48:51], v[184:187], v[180:183], v[48:51]
	v_mfma_f32_16x16x32_bf16 v[52:55], v[188:191], v[180:183], v[52:55]
	v_mfma_f32_16x16x32_bf16 v[56:59], v[192:195], v[180:183], v[56:59]
	v_mfma_f32_16x16x32_bf16 v[60:63], v[196:199], v[180:183], v[60:63]
	s_waitcnt vmcnt(4) lgkmcnt(0)
	s_barrier
	s_add_u32 m0, s56, 0xc000
	s_nop 0
	global_load_lds_dwordx4 v244, s[26:27]
	s_add_u32 m0, s56, 0xc400
	s_nop 0
	global_load_lds_dwordx4 v245, s[26:27]
	s_add_u32 m0, s56, 0xc800
	s_nop 0
	global_load_lds_dwordx4 v246, s[26:27]
	s_add_u32 m0, s56, 0xcc00
	s_nop 0
	global_load_lds_dwordx4 v247, s[26:27]
	s_add_u32 s26, s26, 128
	s_addc_u32 s27, s27, 0
	v_mfma_f32_16x16x32_bf16 v[0:3], v[216:219], v[200:203], v[0:3]
	ds_read_b128 v[168:171], v248 offset:0
	v_mfma_f32_16x16x32_bf16 v[4:7], v[220:223], v[200:203], v[4:7]
	ds_read_b128 v[184:187], v250 offset:16384
	v_mfma_f32_16x16x32_bf16 v[8:11], v[228:231], v[200:203], v[8:11]
	ds_read_b128 v[172:175], v248 offset:2048
	v_mfma_f32_16x16x32_bf16 v[12:15], v[232:235], v[200:203], v[12:15]
	ds_read_b128 v[188:191], v250 offset:16896
	v_mfma_f32_16x16x32_bf16 v[16:19], v[216:219], v[204:207], v[16:19]
	ds_read_b128 v[176:179], v248 offset:4096
	v_mfma_f32_16x16x32_bf16 v[20:23], v[220:223], v[204:207], v[20:23]
	ds_read_b128 v[192:195], v250 offset:17408
	v_mfma_f32_16x16x32_bf16 v[24:27], v[228:231], v[204:207], v[24:27]
	ds_read_b128 v[180:183], v248 offset:6144
	v_mfma_f32_16x16x32_bf16 v[28:31], v[232:235], v[204:207], v[28:31]
	ds_read_b128 v[196:199], v250 offset:17920
	v_mfma_f32_16x16x32_bf16 v[32:35], v[216:219], v[208:211], v[32:35]
	v_mfma_f32_16x16x32_bf16 v[36:39], v[220:223], v[208:211], v[36:39]
	v_mfma_f32_16x16x32_bf16 v[40:43], v[228:231], v[208:211], v[40:43]
	v_mfma_f32_16x16x32_bf16 v[44:47], v[232:235], v[208:211], v[44:47]
	v_mfma_f32_16x16x32_bf16 v[48:51], v[216:219], v[212:215], v[48:51]
	v_mfma_f32_16x16x32_bf16 v[52:55], v[220:223], v[212:215], v[52:55]
	v_mfma_f32_16x16x32_bf16 v[56:59], v[228:231], v[212:215], v[56:59]
	v_mfma_f32_16x16x32_bf16 v[60:63], v[232:235], v[212:215], v[60:63]
	s_add_u32 m0, s56, 0x10000
	s_nop 0
	global_load_lds_dwordx4 v236, s[24:25]
	s_add_u32 m0, s56, 0x10400
	s_nop 0
	global_load_lds_dwordx4 v237, s[24:25]
	s_add_u32 m0, s56, 0x10800
	s_nop 0
	global_load_lds_dwordx4 v238, s[24:25]
	s_add_u32 m0, s56, 0x10c00
	s_nop 0
	global_load_lds_dwordx4 v239, s[24:25]
	s_add_u32 s24, s24, 128
	s_addc_u32 s25, s25, 0
	s_waitcnt lgkmcnt(0)
; template <int NI> ...
;     ...
;   G_LOAD(a0, b0, 0);
;   G_LOAD(a1, b1, 32);
;   __syncthreads();
;   G_WRITE(a0, b0, 0);
;   __syncthreads();
;   for (int kt = 0; kt < nk; kt += 2) {
;     G_LOAD(a0, b0, min((kt + 2) * 32, klast));
;     G_COMPUTE(0);
;     G_WRITE(a1, b1, 1);
;     __syncthreads();
;     G_LOAD(a1, b1, min((kt + 3) * 32, klast));
;     G_COMPUTE(1);
;     G_WRITE(a0, b0, 0);
;     __syncthreads();
;   }
; __device__ void phase_merge4(CParams& p, int l, int tm, int tn, char* smem) {
;     ...
;     gemm_mainloop<4>(p.hbuf + (size_t)row0 * DM, DM,
;                      p.WgT + (((size_t)l * 4 + kb) * 1024 + col0) * 1024, 1024, 1024, sA, sB, acc, tid2);
	v_mfma_f32_16x16x32_bf16 v[0:3], v[184:187], v[168:171], v[0:3]
	ds_read_b128 v[200:203], v249 offset:0
	v_mfma_f32_16x16x32_bf16 v[4:7], v[188:191], v[168:171], v[4:7]
	ds_read_b128 v[216:219], v251 offset:16384
	v_mfma_f32_16x16x32_bf16 v[8:11], v[192:195], v[168:171], v[8:11]
	ds_read_b128 v[204:207], v249 offset:2048
	v_mfma_f32_16x16x32_bf16 v[12:15], v[196:199], v[168:171], v[12:15]
	ds_read_b128 v[220:223], v251 offset:16896
	v_mfma_f32_16x16x32_bf16 v[16:19], v[184:187], v[172:175], v[16:19]
	ds_read_b128 v[208:211], v249 offset:4096
	v_mfma_f32_16x16x32_bf16 v[20:23], v[188:191], v[172:175], v[20:23]
	ds_read_b128 v[228:231], v251 offset:17408
	v_mfma_f32_16x16x32_bf16 v[24:27], v[192:195], v[172:175], v[24:27]
	ds_read_b128 v[212:215], v249 offset:6144
	v_mfma_f32_16x16x32_bf16 v[28:31], v[196:199], v[172:175], v[28:31]
	ds_read_b128 v[232:235], v251 offset:17920
	v_mfma_f32_16x16x32_bf16 v[32:35], v[184:187], v[176:179], v[32:35]
	v_mfma_f32_16x16x32_bf16 v[36:39], v[188:191], v[176:179], v[36:39]
	v_mfma_f32_16x16x32_bf16 v[40:43], v[192:195], v[176:179], v[40:43]
	v_mfma_f32_16x16x32_bf16 v[44:47], v[196:199], v[176:179], v[44:47]
	v_mfma_f32_16x16x32_bf16 v[48:51], v[184:187], v[180:183], v[48:51]
	v_mfma_f32_16x16x32_bf16 v[52:55], v[188:191], v[180:183], v[52:55]
	v_mfma_f32_16x16x32_bf16 v[56:59], v[192:195], v[180:183], v[56:59]
	v_mfma_f32_16x16x32_bf16 v[60:63], v[196:199], v[180:183], v[60:63]
	s_waitcnt vmcnt(4) lgkmcnt(0)
	s_barrier
	s_add_u32 m0, s56, 0x0
	s_nop 0
	global_load_lds_dwordx4 v244, s[26:27]
	s_add_u32 m0, s56, 0x400
	s_nop 0
	global_load_lds_dwordx4 v245, s[26:27]
	s_add_u32 m0, s56, 0x800
	s_nop 0
	global_load_lds_dwordx4 v246, s[26:27]
	s_add_u32 m0, s56, 0xc00
	s_nop 0
	global_load_lds_dwordx4 v247, s[26:27]
	s_add_u32 s26, s26, 128
	s_addc_u32 s27, s27, 0
	v_mfma_f32_16x16x32_bf16 v[0:3], v[216:219], v[200:203], v[0:3]
	ds_read_b128 v[168:171], v248 offset:32768
	v_mfma_f32_16x16x32_bf16 v[4:7], v[220:223], v[200:203], v[4:7]
	ds_read_b128 v[184:187], v250 offset:49152
	v_mfma_f32_16x16x32_bf16 v[8:11], v[228:231], v[200:203], v[8:11]
	ds_read_b128 v[172:175], v248 offset:34816
	v_mfma_f32_16x16x32_bf16 v[12:15], v[232:235], v[200:203], v[12:15]
	ds_read_b128 v[188:191], v250 offset:49664
	v_mfma_f32_16x16x32_bf16 v[16:19], v[216:219], v[204:207], v[16:19]
	ds_read_b128 v[176:179], v248 offset:36864
	v_mfma_f32_16x16x32_bf16 v[20:23], v[220:223], v[204:207], v[20:23]
	ds_read_b128 v[192:195], v250 offset:50176
	v_mfma_f32_16x16x32_bf16 v[24:27], v[228:231], v[204:207], v[24:27]
	ds_read_b128 v[180:183], v248 offset:38912
	v_mfma_f32_16x16x32_bf16 v[28:31], v[232:235], v[204:207], v[28:31]
	ds_read_b128 v[196:199], v250 offset:50688
	v_mfma_f32_16x16x32_bf16 v[32:35], v[216:219], v[208:211], v[32:35]
	v_mfma_f32_16x16x32_bf16 v[36:39], v[220:223], v[208:211], v[36:39]
	v_mfma_f32_16x16x32_bf16 v[40:43], v[228:231], v[208:211], v[40:43]
	v_mfma_f32_16x16x32_bf16 v[44:47], v[232:235], v[208:211], v[44:47]
	v_mfma_f32_16x16x32_bf16 v[48:51], v[216:219], v[212:215], v[48:51]
	v_mfma_f32_16x16x32_bf16 v[52:55], v[220:223], v[212:215], v[52:55]
	v_mfma_f32_16x16x32_bf16 v[56:59], v[228:231], v[212:215], v[56:59]
	v_mfma_f32_16x16x32_bf16 v[60:63], v[232:235], v[212:215], v[60:63]
	s_add_u32 m0, s56, 0x4000
	s_nop 0
	global_load_lds_dwordx4 v236, s[24:25]
	s_add_u32 m0, s56, 0x4400
	s_nop 0
	global_load_lds_dwordx4 v237, s[24:25]
	s_add_u32 m0, s56, 0x4800
	s_nop 0
	global_load_lds_dwordx4 v238, s[24:25]
	s_add_u32 m0, s56, 0x4c00
	s_nop 0
	global_load_lds_dwordx4 v239, s[24:25]
	s_add_u32 s24, s24, 128
	s_addc_u32 s25, s25, 0
	s_waitcnt lgkmcnt(0)
	v_mfma_f32_16x16x32_bf16 v[0:3], v[184:187], v[168:171], v[0:3]
	ds_read_b128 v[200:203], v249 offset:32768
	v_mfma_f32_16x16x32_bf16 v[4:7], v[188:191], v[168:171], v[4:7]
	ds_read_b128 v[216:219], v251 offset:49152
	v_mfma_f32_16x16x32_bf16 v[8:11], v[192:195], v[168:171], v[8:11]
	ds_read_b128 v[204:207], v249 offset:34816
	v_mfma_f32_16x16x32_bf16 v[12:15], v[196:199], v[168:171], v[12:15]
	ds_read_b128 v[220:223], v251 offset:49664
	v_mfma_f32_16x16x32_bf16 v[16:19], v[184:187], v[172:175], v[16:19]
	ds_read_b128 v[208:211], v249 offset:36864
	v_mfma_f32_16x16x32_bf16 v[20:23], v[188:191], v[172:175], v[20:23]
	ds_read_b128 v[228:231], v251 offset:50176
	v_mfma_f32_16x16x32_bf16 v[24:27], v[192:195], v[172:175], v[24:27]
	ds_read_b128 v[212:215], v249 offset:38912
	v_mfma_f32_16x16x32_bf16 v[28:31], v[196:199], v[172:175], v[28:31]
	ds_read_b128 v[232:235], v251 offset:50688
	v_mfma_f32_16x16x32_bf16 v[32:35], v[184:187], v[176:179], v[32:35]
	v_mfma_f32_16x16x32_bf16 v[36:39], v[188:191], v[176:179], v[36:39]
	v_mfma_f32_16x16x32_bf16 v[40:43], v[192:195], v[176:179], v[40:43]
	v_mfma_f32_16x16x32_bf16 v[44:47], v[196:199], v[176:179], v[44:47]
	v_mfma_f32_16x16x32_bf16 v[48:51], v[184:187], v[180:183], v[48:51]
	v_mfma_f32_16x16x32_bf16 v[52:55], v[188:191], v[180:183], v[52:55]
	v_mfma_f32_16x16x32_bf16 v[56:59], v[192:195], v[180:183], v[56:59]
	v_mfma_f32_16x16x32_bf16 v[60:63], v[196:199], v[180:183], v[60:63]
	s_waitcnt vmcnt(4) lgkmcnt(0)
	s_barrier
; template <int NI> ...
;     ...
;   G_LOAD(a0, b0, 0);
;   G_LOAD(a1, b1, 32);
;   __syncthreads();
;   G_WRITE(a0, b0, 0);
;   __syncthreads();
;   for (int kt = 0; kt < nk; kt += 2) {
;     G_LOAD(a0, b0, min((kt + 2) * 32, klast));
;     G_COMPUTE(0);
;     G_WRITE(a1, b1, 1);
;     __syncthreads();
;     G_LOAD(a1, b1, min((kt + 3) * 32, klast));
;     G_COMPUTE(1);
;     G_WRITE(a0, b0, 0);
;     __syncthreads();
;   }
; __device__ void phase_merge4(CParams& p, int l, int tm, int tn, char* smem) {
;     ...
;     gemm_mainloop<4>(p.hbuf + (size_t)row0 * DM, DM,
;                      p.WgT + (((size_t)l * 4 + kb) * 1024 + col0) * 1024, 1024, 1024, sA, sB, acc, tid2);
	s_add_u32 m0, s56, 0x8000
	s_nop 0
	global_load_lds_dwordx4 v244, s[26:27]
	s_add_u32 m0, s56, 0x8400
	s_nop 0
	global_load_lds_dwordx4 v245, s[26:27]
	s_add_u32 m0, s56, 0x8800
	s_nop 0
	global_load_lds_dwordx4 v246, s[26:27]
	s_add_u32 m0, s56, 0x8c00
	s_nop 0
	global_load_lds_dwordx4 v247, s[26:27]
	s_add_u32 s26, s26, 128
	s_addc_u32 s27, s27, 0
	v_mfma_f32_16x16x32_bf16 v[0:3], v[216:219], v[200:203], v[0:3]
	ds_read_b128 v[168:171], v166 offset:49152
	v_mfma_f32_16x16x32_bf16 v[4:7], v[220:223], v[200:203], v[4:7]
	ds_read_b128 v[184:187], v250 offset:0
	v_mfma_f32_16x16x32_bf16 v[8:11], v[228:231], v[200:203], v[8:11]
	ds_read_b128 v[172:175], v166 offset:51200
	v_mfma_f32_16x16x32_bf16 v[12:15], v[232:235], v[200:203], v[12:15]
	ds_read_b128 v[188:191], v250 offset:512
	v_mfma_f32_16x16x32_bf16 v[16:19], v[216:219], v[204:207], v[16:19]
	ds_read_b128 v[176:179], v166 offset:53248
	v_mfma_f32_16x16x32_bf16 v[20:23], v[220:223], v[204:207], v[20:23]
	ds_read_b128 v[192:195], v250 offset:1024
	v_mfma_f32_16x16x32_bf16 v[24:27], v[228:231], v[204:207], v[24:27]
	ds_read_b128 v[180:183], v166 offset:55296
	v_mfma_f32_16x16x32_bf16 v[28:31], v[232:235], v[204:207], v[28:31]
	ds_read_b128 v[196:199], v250 offset:1536
	v_mfma_f32_16x16x32_bf16 v[32:35], v[216:219], v[208:211], v[32:35]
	v_mfma_f32_16x16x32_bf16 v[36:39], v[220:223], v[208:211], v[36:39]
	v_mfma_f32_16x16x32_bf16 v[40:43], v[228:231], v[208:211], v[40:43]
	v_mfma_f32_16x16x32_bf16 v[44:47], v[232:235], v[208:211], v[44:47]
	v_mfma_f32_16x16x32_bf16 v[48:51], v[216:219], v[212:215], v[48:51]
	v_mfma_f32_16x16x32_bf16 v[52:55], v[220:223], v[212:215], v[52:55]
	v_mfma_f32_16x16x32_bf16 v[56:59], v[228:231], v[212:215], v[56:59]
	v_mfma_f32_16x16x32_bf16 v[60:63], v[232:235], v[212:215], v[60:63]
	s_add_u32 m0, s56, 0xc000
	s_nop 0
	global_load_lds_dwordx4 v236, s[24:25]
	s_add_u32 m0, s56, 0xc400
	s_nop 0
	global_load_lds_dwordx4 v237, s[24:25]
	s_add_u32 m0, s56, 0xc800
	s_nop 0
	global_load_lds_dwordx4 v238, s[24:25]
	s_add_u32 m0, s56, 0xcc00
	s_nop 0
	global_load_lds_dwordx4 v239, s[24:25]
	s_add_u32 s24, s24, 128
	s_addc_u32 s25, s25, 0
	s_waitcnt lgkmcnt(0)
	v_mfma_f32_16x16x32_bf16 v[0:3], v[184:187], v[168:171], v[0:3]
	ds_read_b128 v[200:203], v167 offset:49152
	v_mfma_f32_16x16x32_bf16 v[4:7], v[188:191], v[168:171], v[4:7]
	ds_read_b128 v[216:219], v251 offset:0
	v_mfma_f32_16x16x32_bf16 v[8:11], v[192:195], v[168:171], v[8:11]
	ds_read_b128 v[204:207], v167 offset:51200
	v_mfma_f32_16x16x32_bf16 v[12:15], v[196:199], v[168:171], v[12:15]
	ds_read_b128 v[220:223], v251 offset:512
	v_mfma_f32_16x16x32_bf16 v[16:19], v[184:187], v[172:175], v[16:19]
	ds_read_b128 v[208:211], v167 offset:53248
	v_mfma_f32_16x16x32_bf16 v[20:23], v[188:191], v[172:175], v[20:23]
	ds_read_b128 v[228:231], v251 offset:1024
	v_mfma_f32_16x16x32_bf16 v[24:27], v[192:195], v[172:175], v[24:27]
	ds_read_b128 v[212:215], v167 offset:55296
	v_mfma_f32_16x16x32_bf16 v[28:31], v[196:199], v[172:175], v[28:31]
	ds_read_b128 v[232:235], v251 offset:1536
	v_mfma_f32_16x16x32_bf16 v[32:35], v[184:187], v[176:179], v[32:35]
	v_mfma_f32_16x16x32_bf16 v[36:39], v[188:191], v[176:179], v[36:39]
	v_mfma_f32_16x16x32_bf16 v[40:43], v[192:195], v[176:179], v[40:43]
	v_mfma_f32_16x16x32_bf16 v[44:47], v[196:199], v[176:179], v[44:47]
	v_mfma_f32_16x16x32_bf16 v[48:51], v[184:187], v[180:183], v[48:51]
	v_mfma_f32_16x16x32_bf16 v[52:55], v[188:191], v[180:183], v[52:55]
	v_mfma_f32_16x16x32_bf16 v[56:59], v[192:195], v[180:183], v[56:59]
	v_mfma_f32_16x16x32_bf16 v[60:63], v[196:199], v[180:183], v[60:63]
	s_waitcnt vmcnt(4) lgkmcnt(0)
	s_barrier
	s_add_u32 m0, s56, 0x10000
	s_nop 0
	global_load_lds_dwordx4 v244, s[26:27]
	s_add_u32 m0, s56, 0x10400
	s_nop 0
	global_load_lds_dwordx4 v245, s[26:27]
	s_add_u32 m0, s56, 0x10800
	s_nop 0
	global_load_lds_dwordx4 v246, s[26:27]
	s_add_u32 m0, s56, 0x10c00
	s_nop 0
	global_load_lds_dwordx4 v247, s[26:27]
	s_add_u32 s26, s26, 128
	s_addc_u32 s27, s27, 0
	v_mfma_f32_16x16x32_bf16 v[0:3], v[216:219], v[200:203], v[0:3]
	ds_read_b128 v[168:171], v248 offset:16384
	v_mfma_f32_16x16x32_bf16 v[4:7], v[220:223], v[200:203], v[4:7]
	ds_read_b128 v[184:187], v250 offset:32768
	v_mfma_f32_16x16x32_bf16 v[8:11], v[228:231], v[200:203], v[8:11]
	ds_read_b128 v[172:175], v248 offset:18432
	v_mfma_f32_16x16x32_bf16 v[12:15], v[232:235], v[200:203], v[12:15]
	ds_read_b128 v[188:191], v250 offset:33280
	v_mfma_f32_16x16x32_bf16 v[16:19], v[216:219], v[204:207], v[16:19]
	ds_read_b128 v[176:179], v248 offset:20480
	v_mfma_f32_16x16x32_bf16 v[20:23], v[220:223], v[204:207], v[20:23]
	ds_read_b128 v[192:195], v250 offset:33792
	v_mfma_f32_16x16x32_bf16 v[24:27], v[228:231], v[204:207], v[24:27]
	ds_read_b128 v[180:183], v248 offset:22528
	v_mfma_f32_16x16x32_bf16 v[28:31], v[232:235], v[204:207], v[28:31]
	ds_read_b128 v[196:199], v250 offset:34304
	v_mfma_f32_16x16x32_bf16 v[32:35], v[216:219], v[208:211], v[32:35]
	v_mfma_f32_16x16x32_bf16 v[36:39], v[220:223], v[208:211], v[36:39]
	v_mfma_f32_16x16x32_bf16 v[40:43], v[228:231], v[208:211], v[40:43]
	v_mfma_f32_16x16x32_bf16 v[44:47], v[232:235], v[208:211], v[44:47]
	v_mfma_f32_16x16x32_bf16 v[48:51], v[216:219], v[212:215], v[48:51]
	v_mfma_f32_16x16x32_bf16 v[52:55], v[220:223], v[212:215], v[52:55]
	v_mfma_f32_16x16x32_bf16 v[56:59], v[228:231], v[212:215], v[56:59]
	v_mfma_f32_16x16x32_bf16 v[60:63], v[232:235], v[212:215], v[60:63]
	s_mov_b64 s[24:25], s[28:29]
	s_add_u32 m0, s56, 0x0
	s_nop 0
	global_load_lds_dwordx4 v236, s[24:25]
	s_add_u32 m0, s56, 0x400
	s_nop 0
	global_load_lds_dwordx4 v237, s[24:25]
	s_add_u32 m0, s56, 0x800
	s_nop 0
	global_load_lds_dwordx4 v238, s[24:25]
	s_add_u32 m0, s56, 0xc00
	s_nop 0
	global_load_lds_dwordx4 v239, s[24:25]
	s_add_u32 s24, s24, 128
	s_addc_u32 s25, s25, 0
	s_waitcnt lgkmcnt(0)
; template <int NI> ...
;     ...
;   G_LOAD(a0, b0, 0);
;   G_LOAD(a1, b1, 32);
;   __syncthreads();
;   G_WRITE(a0, b0, 0);
;   __syncthreads();
;   for (int kt = 0; kt < nk; kt += 2) {
;     G_LOAD(a0, b0, min((kt + 2) * 32, klast));
;     G_COMPUTE(0);
;     G_WRITE(a1, b1, 1);
;     __syncthreads();
;     G_LOAD(a1, b1, min((kt + 3) * 32, klast));
;     G_COMPUTE(1);
;     G_WRITE(a0, b0, 0);
;     __syncthreads();
	v_mfma_f32_16x16x32_bf16 v[0:3], v[184:187], v[168:171], v[0:3]
	ds_read_b128 v[200:203], v249 offset:16384
	v_mfma_f32_16x16x32_bf16 v[4:7], v[188:191], v[168:171], v[4:7]
	ds_read_b128 v[216:219], v251 offset:32768
	v_mfma_f32_16x16x32_bf16 v[8:11], v[192:195], v[168:171], v[8:11]
	ds_read_b128 v[204:207], v249 offset:18432
	v_mfma_f32_16x16x32_bf16 v[12:15], v[196:199], v[168:171], v[12:15]
	ds_read_b128 v[220:223], v251 offset:33280
	v_mfma_f32_16x16x32_bf16 v[16:19], v[184:187], v[172:175], v[16:19]
	ds_read_b128 v[208:211], v249 offset:20480
	v_mfma_f32_16x16x32_bf16 v[20:23], v[188:191], v[172:175], v[20:23]
	ds_read_b128 v[228:231], v251 offset:33792
	v_mfma_f32_16x16x32_bf16 v[24:27], v[192:195], v[172:175], v[24:27]
	ds_read_b128 v[212:215], v249 offset:22528
	v_mfma_f32_16x16x32_bf16 v[28:31], v[196:199], v[172:175], v[28:31]
	ds_read_b128 v[232:235], v251 offset:34304
	v_mfma_f32_16x16x32_bf16 v[32:35], v[184:187], v[176:179], v[32:35]
	v_mfma_f32_16x16x32_bf16 v[36:39], v[188:191], v[176:179], v[36:39]
	v_mfma_f32_16x16x32_bf16 v[40:43], v[192:195], v[176:179], v[40:43]
	v_mfma_f32_16x16x32_bf16 v[44:47], v[196:199], v[176:179], v[44:47]
	v_mfma_f32_16x16x32_bf16 v[48:51], v[184:187], v[180:183], v[48:51]
	v_mfma_f32_16x16x32_bf16 v[52:55], v[188:191], v[180:183], v[52:55]
	v_mfma_f32_16x16x32_bf16 v[56:59], v[192:195], v[180:183], v[56:59]
	v_mfma_f32_16x16x32_bf16 v[60:63], v[196:199], v[180:183], v[60:63]
	s_waitcnt vmcnt(4) lgkmcnt(0)
	s_barrier
	s_mov_b64 s[26:27], s[44:45]
	s_add_u32 m0, s56, 0x4000
	s_nop 0
	global_load_lds_dwordx4 v240, s[26:27]
	s_add_u32 m0, s56, 0x4400
	s_nop 0
	global_load_lds_dwordx4 v241, s[26:27]
	s_add_u32 m0, s56, 0x4800
	s_nop 0
	global_load_lds_dwordx4 v242, s[26:27]
	s_add_u32 m0, s56, 0x4c00
	s_nop 0
	global_load_lds_dwordx4 v243, s[26:27]
	s_add_u32 s26, s26, 128
	s_addc_u32 s27, s27, 0
	v_mfma_f32_16x16x32_bf16 v[0:3], v[216:219], v[200:203], v[0:3]
	ds_read_b128 v[168:171], v248 offset:49152
	v_mfma_f32_16x16x32_bf16 v[4:7], v[220:223], v[200:203], v[4:7]
	ds_read_b128 v[184:187], v226 offset:49152
	v_mfma_f32_16x16x32_bf16 v[8:11], v[228:231], v[200:203], v[8:11]
	ds_read_b128 v[172:175], v248 offset:51200
	v_mfma_f32_16x16x32_bf16 v[12:15], v[232:235], v[200:203], v[12:15]
	ds_read_b128 v[188:191], v226 offset:49664
	v_mfma_f32_16x16x32_bf16 v[16:19], v[216:219], v[204:207], v[16:19]
	ds_read_b128 v[176:179], v248 offset:53248
	v_mfma_f32_16x16x32_bf16 v[20:23], v[220:223], v[204:207], v[20:23]
	ds_read_b128 v[192:195], v226 offset:50176
	v_mfma_f32_16x16x32_bf16 v[24:27], v[228:231], v[204:207], v[24:27]
	ds_read_b128 v[180:183], v248 offset:55296
	v_mfma_f32_16x16x32_bf16 v[28:31], v[232:235], v[204:207], v[28:31]
	ds_read_b128 v[196:199], v226 offset:50688
	v_mfma_f32_16x16x32_bf16 v[32:35], v[216:219], v[208:211], v[32:35]
	v_mfma_f32_16x16x32_bf16 v[36:39], v[220:223], v[208:211], v[36:39]
	v_mfma_f32_16x16x32_bf16 v[40:43], v[228:231], v[208:211], v[40:43]
	v_mfma_f32_16x16x32_bf16 v[44:47], v[232:235], v[208:211], v[44:47]
	v_mfma_f32_16x16x32_bf16 v[48:51], v[216:219], v[212:215], v[48:51]
	v_mfma_f32_16x16x32_bf16 v[52:55], v[220:223], v[212:215], v[52:55]
	v_mfma_f32_16x16x32_bf16 v[56:59], v[228:231], v[212:215], v[56:59]
	v_mfma_f32_16x16x32_bf16 v[60:63], v[232:235], v[212:215], v[60:63]
	s_add_u32 m0, s56, 0x8000
	s_nop 0
	global_load_lds_dwordx4 v236, s[24:25]
	s_add_u32 m0, s56, 0x8400
	s_nop 0
	global_load_lds_dwordx4 v237, s[24:25]
	s_add_u32 m0, s56, 0x8800
	s_nop 0
	global_load_lds_dwordx4 v238, s[24:25]
	s_add_u32 m0, s56, 0x8c00
	s_nop 0
	global_load_lds_dwordx4 v239, s[24:25]
	s_add_u32 s24, s24, 128
	s_addc_u32 s25, s25, 0
	s_waitcnt lgkmcnt(0)
	v_mfma_f32_16x16x32_bf16 v[0:3], v[184:187], v[168:171], v[0:3]
	ds_read_b128 v[200:203], v249 offset:49152
	v_mfma_f32_16x16x32_bf16 v[4:7], v[188:191], v[168:171], v[4:7]
	ds_read_b128 v[216:219], v227 offset:49152
	v_mfma_f32_16x16x32_bf16 v[8:11], v[192:195], v[168:171], v[8:11]
	ds_read_b128 v[204:207], v249 offset:51200
	v_mfma_f32_16x16x32_bf16 v[12:15], v[196:199], v[168:171], v[12:15]
	ds_read_b128 v[220:223], v227 offset:49664
	v_mfma_f32_16x16x32_bf16 v[16:19], v[184:187], v[172:175], v[16:19]
	ds_read_b128 v[208:211], v249 offset:53248
	v_mfma_f32_16x16x32_bf16 v[20:23], v[188:191], v[172:175], v[20:23]
	ds_read_b128 v[228:231], v227 offset:50176
	v_mfma_f32_16x16x32_bf16 v[24:27], v[192:195], v[172:175], v[24:27]
	ds_read_b128 v[212:215], v249 offset:55296
	v_mfma_f32_16x16x32_bf16 v[28:31], v[196:199], v[172:175], v[28:31]
	ds_read_b128 v[232:235], v227 offset:50688
	v_mfma_f32_16x16x32_bf16 v[32:35], v[184:187], v[176:179], v[32:35]
	v_mfma_f32_16x16x32_bf16 v[36:39], v[188:191], v[176:179], v[36:39]
	v_mfma_f32_16x16x32_bf16 v[40:43], v[192:195], v[176:179], v[40:43]
	v_mfma_f32_16x16x32_bf16 v[44:47], v[196:199], v[176:179], v[44:47]
	v_mfma_f32_16x16x32_bf16 v[48:51], v[184:187], v[180:183], v[48:51]
	v_mfma_f32_16x16x32_bf16 v[52:55], v[188:191], v[180:183], v[52:55]
	v_mfma_f32_16x16x32_bf16 v[56:59], v[192:195], v[180:183], v[56:59]
	v_mfma_f32_16x16x32_bf16 v[60:63], v[196:199], v[180:183], v[60:63]
	s_waitcnt vmcnt(4) lgkmcnt(0)
	s_barrier
; __device__ __forceinline__ float sigmoidf_(float v) { return 1.f / (1.f + __expf(-v)); }
; template <int NI> ...
;     ...
;   G_LOAD(a0, b0, 0);
;   G_LOAD(a1, b1, 32);
;   __syncthreads();
;   G_WRITE(a0, b0, 0);
;   __syncthreads();
;   for (int kt = 0; kt < nk; kt += 2) {
;     G_LOAD(a0, b0, min((kt + 2) * 32, klast));
;     G_COMPUTE(0);
;     G_WRITE(a1, b1, 1);
;     __syncthreads();
;     G_LOAD(a1, b1, min((kt + 3) * 32, klast));
;     G_COMPUTE(1);
;     G_WRITE(a0, b0, 0);
;     __syncthreads();
; __device__ void phase_merge4(CParams& p, int l, int tm, int tn, char* smem) {
;     ...
; #pragma unroll
;     for (int mi = 0; mi < 4; mi++)
; #pragma unroll
;       for (int ni = 0; ni < 4; ni++) {
;         unsigned p0 = pk[mi][ni][0], p1 = pk[mi][ni][1], m0 = mer[mi][ni][0], m1 = mer[mi][ni][1];
;         float r0 = __uint_as_float(m0 << 16) + sigmoidf_(acc[mi][ni][0]) * __uint_as_float(p0 << 16);
;         float r1 = __uint_as_float(m0 & 0xffff0000u) + sigmoidf_(acc[mi][ni][1]) * __uint_as_float(p0 & 0xffff0000u);
;         float r2 = __uint_as_float(m1 << 16) + sigmoidf_(acc[mi][ni][2]) * __uint_as_float(p1 << 16);
;         float r3 = __uint_as_float(m1 & 0xffff0000u) + sigmoidf_(acc[mi][ni][3]) * __uint_as_float(p1 & 0xffff0000u);
;         mer[mi][ni][0] = (unsigned)f2bf(r0) | ((unsigned)f2bf(r1) << 16);
;         mer[mi][ni][1] = (unsigned)f2bf(r2) | ((unsigned)f2bf(r3) << 16);
;       }
	s_add_u32 m0, s56, 0xc000
	s_nop 0
	global_load_lds_dwordx4 v240, s[26:27]
	s_add_u32 m0, s56, 0xc400
	s_nop 0
	global_load_lds_dwordx4 v241, s[26:27]
	s_add_u32 m0, s56, 0xc800
	s_nop 0
	global_load_lds_dwordx4 v242, s[26:27]
	s_add_u32 m0, s56, 0xcc00
	s_nop 0
	global_load_lds_dwordx4 v243, s[26:27]
	s_add_u32 s26, s26, 128
	s_addc_u32 s27, s27, 0
	v_mfma_f32_16x16x32_bf16 v[0:3], v[216:219], v[200:203], v[0:3]
	ds_read_b128 v[168:171], v248 offset:0
	v_mfma_f32_16x16x32_bf16 v[4:7], v[220:223], v[200:203], v[4:7]
	ds_read_b128 v[184:187], v250 offset:16384
	v_mfma_f32_16x16x32_bf16 v[8:11], v[228:231], v[200:203], v[8:11]
	ds_read_b128 v[172:175], v248 offset:2048
	v_mfma_f32_16x16x32_bf16 v[12:15], v[232:235], v[200:203], v[12:15]
	ds_read_b128 v[188:191], v250 offset:16896
	v_mfma_f32_16x16x32_bf16 v[16:19], v[216:219], v[204:207], v[16:19]
	ds_read_b128 v[176:179], v248 offset:4096
	v_mfma_f32_16x16x32_bf16 v[20:23], v[220:223], v[204:207], v[20:23]
	ds_read_b128 v[192:195], v250 offset:17408
	v_mfma_f32_16x16x32_bf16 v[24:27], v[228:231], v[204:207], v[24:27]
	ds_read_b128 v[180:183], v248 offset:6144
	v_mfma_f32_16x16x32_bf16 v[28:31], v[232:235], v[204:207], v[28:31]
	ds_read_b128 v[196:199], v250 offset:17920
	v_mfma_f32_16x16x32_bf16 v[32:35], v[216:219], v[208:211], v[32:35]
	v_mfma_f32_16x16x32_bf16 v[36:39], v[220:223], v[208:211], v[36:39]
	v_mfma_f32_16x16x32_bf16 v[40:43], v[228:231], v[208:211], v[40:43]
	v_mfma_f32_16x16x32_bf16 v[44:47], v[232:235], v[208:211], v[44:47]
	v_mfma_f32_16x16x32_bf16 v[48:51], v[216:219], v[212:215], v[48:51]
	v_mfma_f32_16x16x32_bf16 v[52:55], v[220:223], v[212:215], v[52:55]
	v_mfma_f32_16x16x32_bf16 v[56:59], v[228:231], v[212:215], v[56:59]
	v_mfma_f32_16x16x32_bf16 v[60:63], v[232:235], v[212:215], v[60:63]
	s_nop 15
	s_nop 7
	v_mul_f32_e32 v200, 0xbfb8aa3b, v0
	v_mul_f32_e32 v201, 0xbfb8aa3b, v1
	v_mul_f32_e32 v202, 0xbfb8aa3b, v2
	v_mul_f32_e32 v203, 0xbfb8aa3b, v3
	v_mul_f32_e32 v204, 0xbfb8aa3b, v4
	v_mul_f32_e32 v205, 0xbfb8aa3b, v5
	v_mul_f32_e32 v206, 0xbfb8aa3b, v6
	v_mul_f32_e32 v207, 0xbfb8aa3b, v7
	v_exp_f32_e32 v200, v200
	v_exp_f32_e32 v201, v201
	v_exp_f32_e32 v202, v202
	v_exp_f32_e32 v203, v203
	v_exp_f32_e32 v204, v204
	v_exp_f32_e32 v205, v205
	v_exp_f32_e32 v206, v206
	v_exp_f32_e32 v207, v207
	v_add_f32_e32 v200, 1.0, v200
	v_add_f32_e32 v201, 1.0, v201
	v_add_f32_e32 v202, 1.0, v202
	v_add_f32_e32 v203, 1.0, v203
	v_add_f32_e32 v204, 1.0, v204
	v_add_f32_e32 v205, 1.0, v205
	v_add_f32_e32 v206, 1.0, v206
	v_add_f32_e32 v207, 1.0, v207
	v_rcp_f32_e32 v200, v200
	v_rcp_f32_e32 v201, v201
	v_rcp_f32_e32 v202, v202
	v_rcp_f32_e32 v203, v203
	v_rcp_f32_e32 v204, v204
	v_rcp_f32_e32 v205, v205
	v_rcp_f32_e32 v206, v206
	v_rcp_f32_e32 v207, v207
	v_lshlrev_b32_e32 v208, 16, v128
	v_and_b32_e32 v209, 0xffff0000, v128
	v_lshlrev_b32_e32 v210, 16, v129
	v_and_b32_e32 v211, 0xffff0000, v129
	v_lshlrev_b32_e32 v212, 16, v130
	v_and_b32_e32 v213, 0xffff0000, v130
	v_lshlrev_b32_e32 v214, 16, v131
	v_and_b32_e32 v215, 0xffff0000, v131
	v_fmac_f32_e32 v64, v200, v208
	v_fmac_f32_e32 v65, v201, v209
	v_fmac_f32_e32 v66, v202, v210
	v_fmac_f32_e32 v67, v203, v211
	v_fmac_f32_e32 v68, v204, v212
	v_fmac_f32_e32 v69, v205, v213
	v_fmac_f32_e32 v70, v206, v214
	v_fmac_f32_e32 v71, v207, v215
	v_mul_f32_e32 v200, 0xbfb8aa3b, v8
	v_mul_f32_e32 v201, 0xbfb8aa3b, v9
	v_mul_f32_e32 v202, 0xbfb8aa3b, v10
	v_mul_f32_e32 v203, 0xbfb8aa3b, v11
	v_mul_f32_e32 v204, 0xbfb8aa3b, v12
	v_mul_f32_e32 v205, 0xbfb8aa3b, v13
	v_mul_f32_e32 v206, 0xbfb8aa3b, v14
	v_mul_f32_e32 v207, 0xbfb8aa3b, v15
	v_exp_f32_e32 v200, v200
	v_exp_f32_e32 v201, v201
	v_exp_f32_e32 v202, v202
	v_exp_f32_e32 v203, v203
	v_exp_f32_e32 v204, v204
	v_exp_f32_e32 v205, v205
	v_exp_f32_e32 v206, v206
	v_exp_f32_e32 v207, v207
	v_add_f32_e32 v200, 1.0, v200
	v_add_f32_e32 v201, 1.0, v201
	v_add_f32_e32 v202, 1.0, v202
	v_add_f32_e32 v203, 1.0, v203
	v_add_f32_e32 v204, 1.0, v204
	v_add_f32_e32 v205, 1.0, v205
	v_add_f32_e32 v206, 1.0, v206
	v_add_f32_e32 v207, 1.0, v207
	v_rcp_f32_e32 v200, v200
	v_rcp_f32_e32 v201, v201
	v_rcp_f32_e32 v202, v202
	v_rcp_f32_e32 v203, v203
	v_rcp_f32_e32 v204, v204
	v_rcp_f32_e32 v205, v205
	v_rcp_f32_e32 v206, v206
	v_rcp_f32_e32 v207, v207
	v_lshlrev_b32_e32 v208, 16, v132
	v_and_b32_e32 v209, 0xffff0000, v132
	v_lshlrev_b32_e32 v210, 16, v133
	v_and_b32_e32 v211, 0xffff0000, v133
	v_lshlrev_b32_e32 v212, 16, v134
	v_and_b32_e32 v213, 0xffff0000, v134
	v_lshlrev_b32_e32 v214, 16, v135
	v_and_b32_e32 v215, 0xffff0000, v135
	v_fmac_f32_e32 v72, v200, v208
	v_fmac_f32_e32 v73, v201, v209
	v_fmac_f32_e32 v74, v202, v210
	v_fmac_f32_e32 v75, v203, v211
	v_fmac_f32_e32 v76, v204, v212
	v_fmac_f32_e32 v77, v205, v213
	v_fmac_f32_e32 v78, v206, v214
	v_fmac_f32_e32 v79, v207, v215
	v_mul_f32_e32 v200, 0xbfb8aa3b, v16
	v_mul_f32_e32 v201, 0xbfb8aa3b, v17
	v_mul_f32_e32 v202, 0xbfb8aa3b, v18
	v_mul_f32_e32 v203, 0xbfb8aa3b, v19
	v_mul_f32_e32 v204, 0xbfb8aa3b, v20
	v_mul_f32_e32 v205, 0xbfb8aa3b, v21
	v_mul_f32_e32 v206, 0xbfb8aa3b, v22
	v_mul_f32_e32 v207, 0xbfb8aa3b, v23
	v_exp_f32_e32 v200, v200
	v_exp_f32_e32 v201, v201
	v_exp_f32_e32 v202, v202
	v_exp_f32_e32 v203, v203
	v_exp_f32_e32 v204, v204
	v_exp_f32_e32 v205, v205
	v_exp_f32_e32 v206, v206
	v_exp_f32_e32 v207, v207
	v_add_f32_e32 v200, 1.0, v200
	v_add_f32_e32 v201, 1.0, v201
	v_add_f32_e32 v202, 1.0, v202
	v_add_f32_e32 v203, 1.0, v203
	v_add_f32_e32 v204, 1.0, v204
	v_add_f32_e32 v205, 1.0, v205
	v_add_f32_e32 v206, 1.0, v206
	v_add_f32_e32 v207, 1.0, v207
	v_rcp_f32_e32 v200, v200
	v_rcp_f32_e32 v201, v201
	v_rcp_f32_e32 v202, v202
; __device__ __forceinline__ float sigmoidf_(float v) { return 1.f / (1.f + __expf(-v)); }
; __device__ void phase_merge4(CParams& p, int l, int tm, int tn, char* smem) {
;     ...
; #pragma unroll
;     for (int mi = 0; mi < 4; mi++)
; #pragma unroll
;       for (int ni = 0; ni < 4; ni++) {
;         unsigned p0 = pk[mi][ni][0], p1 = pk[mi][ni][1], m0 = mer[mi][ni][0], m1 = mer[mi][ni][1];
;         float r0 = __uint_as_float(m0 << 16) + sigmoidf_(acc[mi][ni][0]) * __uint_as_float(p0 << 16);
;         float r1 = __uint_as_float(m0 & 0xffff0000u) + sigmoidf_(acc[mi][ni][1]) * __uint_as_float(p0 & 0xffff0000u);
;         float r2 = __uint_as_float(m1 << 16) + sigmoidf_(acc[mi][ni][2]) * __uint_as_float(p1 << 16);
;         float r3 = __uint_as_float(m1 & 0xffff0000u) + sigmoidf_(acc[mi][ni][3]) * __uint_as_float(p1 & 0xffff0000u);
;         mer[mi][ni][0] = (unsigned)f2bf(r0) | ((unsigned)f2bf(r1) << 16);
;         mer[mi][ni][1] = (unsigned)f2bf(r2) | ((unsigned)f2bf(r3) << 16);
;       }
	v_rcp_f32_e32 v203, v203
	v_rcp_f32_e32 v204, v204
	v_rcp_f32_e32 v205, v205
	v_rcp_f32_e32 v206, v206
	v_rcp_f32_e32 v207, v207
	v_lshlrev_b32_e32 v208, 16, v136
	v_and_b32_e32 v209, 0xffff0000, v136
	v_lshlrev_b32_e32 v210, 16, v137
	v_and_b32_e32 v211, 0xffff0000, v137
	v_lshlrev_b32_e32 v212, 16, v138
	v_and_b32_e32 v213, 0xffff0000, v138
	v_lshlrev_b32_e32 v214, 16, v139
	v_and_b32_e32 v215, 0xffff0000, v139
	v_fmac_f32_e32 v80, v200, v208
	v_fmac_f32_e32 v81, v201, v209
	v_fmac_f32_e32 v82, v202, v210
	v_fmac_f32_e32 v83, v203, v211
	v_fmac_f32_e32 v84, v204, v212
	v_fmac_f32_e32 v85, v205, v213
	v_fmac_f32_e32 v86, v206, v214
	v_fmac_f32_e32 v87, v207, v215
	v_mul_f32_e32 v200, 0xbfb8aa3b, v24
	v_mul_f32_e32 v201, 0xbfb8aa3b, v25
	v_mul_f32_e32 v202, 0xbfb8aa3b, v26
	v_mul_f32_e32 v203, 0xbfb8aa3b, v27
	v_mul_f32_e32 v204, 0xbfb8aa3b, v28
	v_mul_f32_e32 v205, 0xbfb8aa3b, v29
	v_mul_f32_e32 v206, 0xbfb8aa3b, v30
	v_mul_f32_e32 v207, 0xbfb8aa3b, v31
	v_exp_f32_e32 v200, v200
	v_exp_f32_e32 v201, v201
	v_exp_f32_e32 v202, v202
	v_exp_f32_e32 v203, v203
	v_exp_f32_e32 v204, v204
	v_exp_f32_e32 v205, v205
	v_exp_f32_e32 v206, v206
	v_exp_f32_e32 v207, v207
	v_add_f32_e32 v200, 1.0, v200
	v_add_f32_e32 v201, 1.0, v201
	v_add_f32_e32 v202, 1.0, v202
	v_add_f32_e32 v203, 1.0, v203
	v_add_f32_e32 v204, 1.0, v204
	v_add_f32_e32 v205, 1.0, v205
	v_add_f32_e32 v206, 1.0, v206
	v_add_f32_e32 v207, 1.0, v207
	v_rcp_f32_e32 v200, v200
	v_rcp_f32_e32 v201, v201
	v_rcp_f32_e32 v202, v202
	v_rcp_f32_e32 v203, v203
	v_rcp_f32_e32 v204, v204
	v_rcp_f32_e32 v205, v205
	v_rcp_f32_e32 v206, v206
	v_rcp_f32_e32 v207, v207
	v_lshlrev_b32_e32 v208, 16, v140
	v_and_b32_e32 v209, 0xffff0000, v140
	v_lshlrev_b32_e32 v210, 16, v141
	v_and_b32_e32 v211, 0xffff0000, v141
	v_lshlrev_b32_e32 v212, 16, v142
	v_and_b32_e32 v213, 0xffff0000, v142
	v_lshlrev_b32_e32 v214, 16, v143
	v_and_b32_e32 v215, 0xffff0000, v143
	v_fmac_f32_e32 v88, v200, v208
	v_fmac_f32_e32 v89, v201, v209
	v_fmac_f32_e32 v90, v202, v210
	v_fmac_f32_e32 v91, v203, v211
	v_fmac_f32_e32 v92, v204, v212
	v_fmac_f32_e32 v93, v205, v213
	v_fmac_f32_e32 v94, v206, v214
	v_fmac_f32_e32 v95, v207, v215
	v_mul_f32_e32 v200, 0xbfb8aa3b, v32
	v_mul_f32_e32 v201, 0xbfb8aa3b, v33
	v_mul_f32_e32 v202, 0xbfb8aa3b, v34
	v_mul_f32_e32 v203, 0xbfb8aa3b, v35
	v_mul_f32_e32 v204, 0xbfb8aa3b, v36
	v_mul_f32_e32 v205, 0xbfb8aa3b, v37
	v_mul_f32_e32 v206, 0xbfb8aa3b, v38
	v_mul_f32_e32 v207, 0xbfb8aa3b, v39
	v_exp_f32_e32 v200, v200
	v_exp_f32_e32 v201, v201
	v_exp_f32_e32 v202, v202
	v_exp_f32_e32 v203, v203
	v_exp_f32_e32 v204, v204
	v_exp_f32_e32 v205, v205
	v_exp_f32_e32 v206, v206
	v_exp_f32_e32 v207, v207
	v_add_f32_e32 v200, 1.0, v200
	v_add_f32_e32 v201, 1.0, v201
	v_add_f32_e32 v202, 1.0, v202
	v_add_f32_e32 v203, 1.0, v203
	v_add_f32_e32 v204, 1.0, v204
	v_add_f32_e32 v205, 1.0, v205
	v_add_f32_e32 v206, 1.0, v206
	v_add_f32_e32 v207, 1.0, v207
	v_rcp_f32_e32 v200, v200
	v_rcp_f32_e32 v201, v201
	v_rcp_f32_e32 v202, v202
	v_rcp_f32_e32 v203, v203
	v_rcp_f32_e32 v204, v204
	v_rcp_f32_e32 v205, v205
	v_rcp_f32_e32 v206, v206
	v_rcp_f32_e32 v207, v207
	v_lshlrev_b32_e32 v208, 16, v148
	v_and_b32_e32 v209, 0xffff0000, v148
	v_lshlrev_b32_e32 v210, 16, v149
	v_and_b32_e32 v211, 0xffff0000, v149
	v_lshlrev_b32_e32 v212, 16, v150
	v_and_b32_e32 v213, 0xffff0000, v150
	v_lshlrev_b32_e32 v214, 16, v151
	v_and_b32_e32 v215, 0xffff0000, v151
	v_fmac_f32_e32 v96, v200, v208
	v_fmac_f32_e32 v97, v201, v209
	v_fmac_f32_e32 v98, v202, v210
	v_fmac_f32_e32 v99, v203, v211
	v_fmac_f32_e32 v100, v204, v212
	v_fmac_f32_e32 v101, v205, v213
	v_fmac_f32_e32 v102, v206, v214
	v_fmac_f32_e32 v103, v207, v215
	v_mul_f32_e32 v200, 0xbfb8aa3b, v40
	v_mul_f32_e32 v201, 0xbfb8aa3b, v41
	v_mul_f32_e32 v202, 0xbfb8aa3b, v42
	v_mul_f32_e32 v203, 0xbfb8aa3b, v43
	v_mul_f32_e32 v204, 0xbfb8aa3b, v44
	v_mul_f32_e32 v205, 0xbfb8aa3b, v45
	v_mul_f32_e32 v206, 0xbfb8aa3b, v46
	v_mul_f32_e32 v207, 0xbfb8aa3b, v47
	v_exp_f32_e32 v200, v200
	v_exp_f32_e32 v201, v201
	v_exp_f32_e32 v202, v202
	v_exp_f32_e32 v203, v203
	v_exp_f32_e32 v204, v204
	v_exp_f32_e32 v205, v205
	v_exp_f32_e32 v206, v206
	v_exp_f32_e32 v207, v207
	v_add_f32_e32 v200, 1.0, v200
	v_add_f32_e32 v201, 1.0, v201
	v_add_f32_e32 v202, 1.0, v202
	v_add_f32_e32 v203, 1.0, v203
	v_add_f32_e32 v204, 1.0, v204
	v_add_f32_e32 v205, 1.0, v205
	v_add_f32_e32 v206, 1.0, v206
	v_add_f32_e32 v207, 1.0, v207
	v_rcp_f32_e32 v200, v200
	v_rcp_f32_e32 v201, v201
	v_rcp_f32_e32 v202, v202
	v_rcp_f32_e32 v203, v203
	v_rcp_f32_e32 v204, v204
	v_rcp_f32_e32 v205, v205
	v_rcp_f32_e32 v206, v206
	v_rcp_f32_e32 v207, v207
	v_lshlrev_b32_e32 v208, 16, v152
	v_and_b32_e32 v209, 0xffff0000, v152
	v_lshlrev_b32_e32 v210, 16, v153
	v_and_b32_e32 v211, 0xffff0000, v153
	v_lshlrev_b32_e32 v212, 16, v154
	v_and_b32_e32 v213, 0xffff0000, v154
	v_lshlrev_b32_e32 v214, 16, v155
	v_and_b32_e32 v215, 0xffff0000, v155
	v_fmac_f32_e32 v104, v200, v208
	v_fmac_f32_e32 v105, v201, v209
	v_fmac_f32_e32 v106, v202, v210
	v_fmac_f32_e32 v107, v203, v211
; __device__ __forceinline__ float sigmoidf_(float v) { return 1.f / (1.f + __expf(-v)); }
; __device__ void phase_merge4(CParams& p, int l, int tm, int tn, char* smem) {
;     ...
; #pragma unroll
;     for (int mi = 0; mi < 4; mi++)
; #pragma unroll
;       for (int ni = 0; ni < 4; ni++) {
;         unsigned p0 = pk[mi][ni][0], p1 = pk[mi][ni][1], m0 = mer[mi][ni][0], m1 = mer[mi][ni][1];
;         float r0 = __uint_as_float(m0 << 16) + sigmoidf_(acc[mi][ni][0]) * __uint_as_float(p0 << 16);
;         float r1 = __uint_as_float(m0 & 0xffff0000u) + sigmoidf_(acc[mi][ni][1]) * __uint_as_float(p0 & 0xffff0000u);
;         float r2 = __uint_as_float(m1 << 16) + sigmoidf_(acc[mi][ni][2]) * __uint_as_float(p1 << 16);
;         float r3 = __uint_as_float(m1 & 0xffff0000u) + sigmoidf_(acc[mi][ni][3]) * __uint_as_float(p1 & 0xffff0000u);
;         mer[mi][ni][0] = (unsigned)f2bf(r0) | ((unsigned)f2bf(r1) << 16);
;         mer[mi][ni][1] = (unsigned)f2bf(r2) | ((unsigned)f2bf(r3) << 16);
;       }
;   }
;   {
;     const int lane = tid & 63, wid = tid >> 6, wr = wid >> 1, wc = wid & 1;
; #pragma unroll
;     for (int mi = 0; mi < 4; mi++)
; #pragma unroll
;       for (int ni = 0; ni < 4; ni++)
; #pragma unroll
;         for (int j = 0; j < 4; j++) {
;           int rl = wr * 64 + mi * 16 + (lane >> 4) * 4 + j;
;           int cl = wc * 64 + ni * 16 + (lane & 15);
;           unsigned w = mer[mi][ni][j >> 1];
;           p.merged[(size_t)(row0 + rl) * 1024 + col0 + cl] = (bf16_t)((j & 1) ? (w >> 16) : (w & 0xffffu));
;         }
;   }
	v_fmac_f32_e32 v108, v204, v212
	v_fmac_f32_e32 v109, v205, v213
	v_fmac_f32_e32 v110, v206, v214
	v_fmac_f32_e32 v111, v207, v215
	v_mul_f32_e32 v200, 0xbfb8aa3b, v48
	v_mul_f32_e32 v201, 0xbfb8aa3b, v49
	v_mul_f32_e32 v202, 0xbfb8aa3b, v50
	v_mul_f32_e32 v203, 0xbfb8aa3b, v51
	v_mul_f32_e32 v204, 0xbfb8aa3b, v52
	v_mul_f32_e32 v205, 0xbfb8aa3b, v53
	v_mul_f32_e32 v206, 0xbfb8aa3b, v54
	v_mul_f32_e32 v207, 0xbfb8aa3b, v55
	v_exp_f32_e32 v200, v200
	v_exp_f32_e32 v201, v201
	v_exp_f32_e32 v202, v202
	v_exp_f32_e32 v203, v203
	v_exp_f32_e32 v204, v204
	v_exp_f32_e32 v205, v205
	v_exp_f32_e32 v206, v206
	v_exp_f32_e32 v207, v207
	v_add_f32_e32 v200, 1.0, v200
	v_add_f32_e32 v201, 1.0, v201
	v_add_f32_e32 v202, 1.0, v202
	v_add_f32_e32 v203, 1.0, v203
	v_add_f32_e32 v204, 1.0, v204
	v_add_f32_e32 v205, 1.0, v205
	v_add_f32_e32 v206, 1.0, v206
	v_add_f32_e32 v207, 1.0, v207
	v_rcp_f32_e32 v200, v200
	v_rcp_f32_e32 v201, v201
	v_rcp_f32_e32 v202, v202
	v_rcp_f32_e32 v203, v203
	v_rcp_f32_e32 v204, v204
	v_rcp_f32_e32 v205, v205
	v_rcp_f32_e32 v206, v206
	v_rcp_f32_e32 v207, v207
	v_lshlrev_b32_e32 v208, 16, v156
	v_and_b32_e32 v209, 0xffff0000, v156
	v_lshlrev_b32_e32 v210, 16, v157
	v_and_b32_e32 v211, 0xffff0000, v157
	v_lshlrev_b32_e32 v212, 16, v158
	v_and_b32_e32 v213, 0xffff0000, v158
	v_lshlrev_b32_e32 v214, 16, v159
	v_and_b32_e32 v215, 0xffff0000, v159
	v_fmac_f32_e32 v112, v200, v208
	v_fmac_f32_e32 v113, v201, v209
	v_fmac_f32_e32 v114, v202, v210
	v_fmac_f32_e32 v115, v203, v211
	v_fmac_f32_e32 v116, v204, v212
	v_fmac_f32_e32 v117, v205, v213
	v_fmac_f32_e32 v118, v206, v214
	v_fmac_f32_e32 v119, v207, v215
	v_mul_f32_e32 v200, 0xbfb8aa3b, v56
	v_mul_f32_e32 v201, 0xbfb8aa3b, v57
	v_mul_f32_e32 v202, 0xbfb8aa3b, v58
	v_mul_f32_e32 v203, 0xbfb8aa3b, v59
	v_mul_f32_e32 v204, 0xbfb8aa3b, v60
	v_mul_f32_e32 v205, 0xbfb8aa3b, v61
	v_mul_f32_e32 v206, 0xbfb8aa3b, v62
	v_mul_f32_e32 v207, 0xbfb8aa3b, v63
	v_exp_f32_e32 v200, v200
	v_exp_f32_e32 v201, v201
	v_exp_f32_e32 v202, v202
	v_exp_f32_e32 v203, v203
	v_exp_f32_e32 v204, v204
	v_exp_f32_e32 v205, v205
	v_exp_f32_e32 v206, v206
	v_exp_f32_e32 v207, v207
	v_add_f32_e32 v200, 1.0, v200
	v_add_f32_e32 v201, 1.0, v201
	v_add_f32_e32 v202, 1.0, v202
	v_add_f32_e32 v203, 1.0, v203
	v_add_f32_e32 v204, 1.0, v204
	v_add_f32_e32 v205, 1.0, v205
	v_add_f32_e32 v206, 1.0, v206
	v_add_f32_e32 v207, 1.0, v207
	v_rcp_f32_e32 v200, v200
	v_rcp_f32_e32 v201, v201
	v_rcp_f32_e32 v202, v202
	v_rcp_f32_e32 v203, v203
	v_rcp_f32_e32 v204, v204
	v_rcp_f32_e32 v205, v205
	v_rcp_f32_e32 v206, v206
	v_rcp_f32_e32 v207, v207
	v_lshlrev_b32_e32 v208, 16, v160
	v_and_b32_e32 v209, 0xffff0000, v160
	v_lshlrev_b32_e32 v210, 16, v161
	v_and_b32_e32 v211, 0xffff0000, v161
	v_lshlrev_b32_e32 v212, 16, v162
	v_and_b32_e32 v213, 0xffff0000, v162
	v_lshlrev_b32_e32 v214, 16, v163
	v_and_b32_e32 v215, 0xffff0000, v163
	v_fmac_f32_e32 v120, v200, v208
	v_fmac_f32_e32 v121, v201, v209
	v_fmac_f32_e32 v122, v202, v210
	v_fmac_f32_e32 v123, v203, v211
	v_fmac_f32_e32 v124, v204, v212
	v_fmac_f32_e32 v125, v205, v213
	v_fmac_f32_e32 v126, v206, v214
	v_fmac_f32_e32 v127, v207, v215
	s_and_b32 s63, s22, 3
	s_cmp_lg_u32 s63, 3
	s_cbranch_scc1 .Lmg4_nostore
	s_lshl_b32 s62, s23, 11
	s_lshl_b32 s92, s21, 1
	s_add_u32 s62, s62, s92
	s_add_u32 s58, s8, s62
	s_addc_u32 s59, s9, 0
	v_cvt_pk_bf16_f32 v200, v64, v65
	v_cvt_pk_bf16_f32 v201, v66, v67
	v_cvt_pk_bf16_f32 v202, v68, v69
	v_cvt_pk_bf16_f32 v203, v70, v71
	global_store_dwordx4 v144, v[200:203], s[58:59] offset:0
	v_cvt_pk_bf16_f32 v204, v72, v73
	v_cvt_pk_bf16_f32 v205, v74, v75
	v_cvt_pk_bf16_f32 v206, v76, v77
	v_cvt_pk_bf16_f32 v207, v78, v79
	global_store_dwordx4 v144, v[204:207], s[58:59] offset:16
	s_add_u32 s58, s58, 0x8000
	s_addc_u32 s59, s59, 0
	v_cvt_pk_bf16_f32 v208, v80, v81
	v_cvt_pk_bf16_f32 v209, v82, v83
	v_cvt_pk_bf16_f32 v210, v84, v85
	v_cvt_pk_bf16_f32 v211, v86, v87
	global_store_dwordx4 v144, v[208:211], s[58:59] offset:0
	v_cvt_pk_bf16_f32 v212, v88, v89
	v_cvt_pk_bf16_f32 v213, v90, v91
	v_cvt_pk_bf16_f32 v214, v92, v93
	v_cvt_pk_bf16_f32 v215, v94, v95
	global_store_dwordx4 v144, v[212:215], s[58:59] offset:16
	s_add_u32 s58, s58, 0x8000
	s_addc_u32 s59, s59, 0
	v_cvt_pk_bf16_f32 v216, v96, v97
	v_cvt_pk_bf16_f32 v217, v98, v99
	v_cvt_pk_bf16_f32 v218, v100, v101
	v_cvt_pk_bf16_f32 v219, v102, v103
	global_store_dwordx4 v144, v[216:219], s[58:59] offset:0
	v_cvt_pk_bf16_f32 v220, v104, v105
	v_cvt_pk_bf16_f32 v221, v106, v107
	v_cvt_pk_bf16_f32 v222, v108, v109
	v_cvt_pk_bf16_f32 v223, v110, v111
	global_store_dwordx4 v144, v[220:223], s[58:59] offset:16
	s_add_u32 s58, s58, 0x8000
	s_addc_u32 s59, s59, 0
	v_cvt_pk_bf16_f32 v228, v112, v113
	v_cvt_pk_bf16_f32 v229, v114, v115
	v_cvt_pk_bf16_f32 v230, v116, v117
	v_cvt_pk_bf16_f32 v231, v118, v119
	global_store_dwordx4 v144, v[228:231], s[58:59] offset:0
	v_cvt_pk_bf16_f32 v232, v120, v121
	v_cvt_pk_bf16_f32 v233, v122, v123
	v_cvt_pk_bf16_f32 v234, v124, v125
	v_cvt_pk_bf16_f32 v235, v126, v127
	global_store_dwordx4 v144, v[232:235], s[58:59] offset:16

; template <int NI> ...
;     ...
;   G_LOAD(a0, b0, 0);
;   G_LOAD(a1, b1, 32);
;   __syncthreads();
;   G_WRITE(a0, b0, 0);
;   __syncthreads();
;   for (int kt = 0; kt < nk; kt += 2) {
;     G_LOAD(a0, b0, min((kt + 2) * 32, klast));
;     G_COMPUTE(0);
;     G_WRITE(a1, b1, 1);
;     __syncthreads();
;     G_LOAD(a1, b1, min((kt + 3) * 32, klast));
;     G_COMPUTE(1);
;     G_WRITE(a0, b0, 0);
;     __syncthreads();
.Loutp_pair:
	s_cmp_eq_u32 s53, 14
	s_cselect_b64 s[8:9], s[18:19], s[8:9]
	s_add_u32 s54, s32, s93
	s_add_u32 m0, s54, 0x0
	s_nop 0
	global_load_lds_dwordx4 v236, s[8:9]
	s_add_u32 m0, s54, 0x400
	s_nop 0
	global_load_lds_dwordx4 v237, s[8:9]
	s_add_u32 m0, s54, 0x800
	s_nop 0
	global_load_lds_dwordx4 v238, s[8:9]
	s_add_u32 m0, s54, 0xc00
	s_nop 0
	global_load_lds_dwordx4 v239, s[8:9]
	s_add_u32 s8, s8, 128
	s_addc_u32 s9, s9, 0
	v_add_u32_e32 v129, s59, v249
	v_add_u32_e32 v131, s62, v251
	s_waitcnt lgkmcnt(0)
	v_mfma_f32_16x16x32_bf16 v[0:3], v[184:187], v[168:171], v[0:3]
	ds_read_b128 v[200:203], v129 offset:0
	v_mfma_f32_16x16x32_bf16 v[4:7], v[188:191], v[168:171], v[4:7]
	ds_read_b128 v[216:219], v131 offset:0
	v_mfma_f32_16x16x32_bf16 v[8:11], v[192:195], v[168:171], v[8:11]
	ds_read_b128 v[204:207], v129 offset:2048
	v_mfma_f32_16x16x32_bf16 v[12:15], v[196:199], v[168:171], v[12:15]
	ds_read_b128 v[220:223], v131 offset:2048
	v_mfma_f32_16x16x32_bf16 v[16:19], v[184:187], v[172:175], v[16:19]
	ds_read_b128 v[208:211], v129 offset:4096
	v_mfma_f32_16x16x32_bf16 v[20:23], v[188:191], v[172:175], v[20:23]
	ds_read_b128 v[228:231], v131 offset:4096
	v_mfma_f32_16x16x32_bf16 v[24:27], v[192:195], v[172:175], v[24:27]
	ds_read_b128 v[212:215], v129 offset:6144
	v_mfma_f32_16x16x32_bf16 v[28:31], v[196:199], v[172:175], v[28:31]
	ds_read_b128 v[232:235], v131 offset:6144
	v_mfma_f32_16x16x32_bf16 v[32:35], v[184:187], v[176:179], v[32:35]
	v_mfma_f32_16x16x32_bf16 v[36:39], v[188:191], v[176:179], v[36:39]
	v_mfma_f32_16x16x32_bf16 v[40:43], v[192:195], v[176:179], v[40:43]
	v_mfma_f32_16x16x32_bf16 v[44:47], v[196:199], v[176:179], v[44:47]
	v_mfma_f32_16x16x32_bf16 v[48:51], v[184:187], v[180:183], v[48:51]
	v_mfma_f32_16x16x32_bf16 v[52:55], v[188:191], v[180:183], v[52:55]
	v_mfma_f32_16x16x32_bf16 v[56:59], v[192:195], v[180:183], v[56:59]
	v_mfma_f32_16x16x32_bf16 v[60:63], v[196:199], v[180:183], v[60:63]
	s_waitcnt vmcnt(4) lgkmcnt(0)
	s_barrier
	s_cmp_eq_u32 s53, 14
	s_cselect_b64 s[12:13], s[22:23], s[12:13]
	s_add_u32 s54, s32, s59
	s_add_u32 m0, s54, 0x0
	s_nop 0
	global_load_lds_dwordx4 v240, s[12:13]
	s_add_u32 m0, s54, 0x400
	s_nop 0
	global_load_lds_dwordx4 v241, s[12:13]
	s_add_u32 m0, s54, 0x800
	s_nop 0
	global_load_lds_dwordx4 v242, s[12:13]
	s_add_u32 m0, s54, 0xc00
	s_nop 0
	global_load_lds_dwordx4 v243, s[12:13]
	s_add_u32 s12, s12, 128
	s_addc_u32 s13, s13, 0
	v_add_u32_e32 v128, s63, v248
	v_add_u32_e32 v130, s92, v250
	v_mfma_f32_16x16x32_bf16 v[0:3], v[216:219], v[200:203], v[0:3]
	ds_read_b128 v[168:171], v128 offset:0
	v_mfma_f32_16x16x32_bf16 v[4:7], v[220:223], v[200:203], v[4:7]
	ds_read_b128 v[184:187], v130 offset:0
	v_mfma_f32_16x16x32_bf16 v[8:11], v[228:231], v[200:203], v[8:11]
	ds_read_b128 v[172:175], v128 offset:2048
	v_mfma_f32_16x16x32_bf16 v[12:15], v[232:235], v[200:203], v[12:15]
	ds_read_b128 v[188:191], v130 offset:2048
	v_mfma_f32_16x16x32_bf16 v[16:19], v[216:219], v[204:207], v[16:19]
	ds_read_b128 v[176:179], v128 offset:4096
	v_mfma_f32_16x16x32_bf16 v[20:23], v[220:223], v[204:207], v[20:23]
	ds_read_b128 v[192:195], v130 offset:4096
	v_mfma_f32_16x16x32_bf16 v[24:27], v[228:231], v[204:207], v[24:27]
	ds_read_b128 v[180:183], v128 offset:6144
	v_mfma_f32_16x16x32_bf16 v[28:31], v[232:235], v[204:207], v[28:31]
	ds_read_b128 v[196:199], v130 offset:6144
	v_mfma_f32_16x16x32_bf16 v[32:35], v[216:219], v[208:211], v[32:35]
	v_mfma_f32_16x16x32_bf16 v[36:39], v[220:223], v[208:211], v[36:39]
	v_mfma_f32_16x16x32_bf16 v[40:43], v[228:231], v[208:211], v[40:43]
	v_mfma_f32_16x16x32_bf16 v[44:47], v[232:235], v[208:211], v[44:47]
	v_mfma_f32_16x16x32_bf16 v[48:51], v[216:219], v[212:215], v[48:51]
	v_mfma_f32_16x16x32_bf16 v[52:55], v[220:223], v[212:215], v[52:55]
	v_mfma_f32_16x16x32_bf16 v[56:59], v[228:231], v[212:215], v[56:59]
	v_mfma_f32_16x16x32_bf16 v[60:63], v[232:235], v[212:215], v[60:63]
	s_mov_b32 s55, s59
	s_mov_b32 s56, s62
	s_mov_b32 s59, s63
	s_mov_b32 s62, s92
	s_mov_b32 s63, s93
	s_mov_b32 s92, s55
	s_mov_b32 s93, s56
	s_add_u32 s53, s53, 1
	s_cmp_lt_u32 s53, 16
	s_cbranch_scc1 .Loutp_pair
; __device__ void phase_proj_res(CParams& p, int l, int tm, int tn, char* smem, const bf16_t* A, int K,
;                                const bf16_t* Bt, int gate_off, float gscale) {
;     ...
;   const float* md = p.mod + ((size_t)l * 3 + modvec_of_tok(row0)) * 6144 + gate_off;
;   EPI_LOOP({
;     float* xp = xrow(p, row0 + rl) + col0 + cl;
;     *xp = *xp + gscale * md[col0 + cl] * acc[mi][ni][j];
;   })
	s_nop 15
	s_nop 7
	global_load_dwordx4 v[200:203], v132, s[44:45] offset:0
	global_load_dwordx4 v[204:207], v132, s[44:45] offset:64
	global_load_dwordx4 v[208:211], v132, s[44:45] offset:128
	global_load_dwordx4 v[212:215], v132, s[44:45] offset:192
	s_mov_b64 s[44:45], s[26:27]
	global_load_dwordx4 v[64:67], v144, s[44:45] offset:0
	global_load_dwordx4 v[68:71], v144, s[44:45] offset:64
	global_load_dwordx4 v[72:75], v144, s[44:45] offset:128
	global_load_dwordx4 v[76:79], v144, s[44:45] offset:192
	s_add_u32 s44, s44, 0x10000
	s_addc_u32 s45, s45, 0
	global_load_dwordx4 v[80:83], v144, s[44:45] offset:0
	global_load_dwordx4 v[84:87], v144, s[44:45] offset:64
	global_load_dwordx4 v[88:91], v144, s[44:45] offset:128
	global_load_dwordx4 v[92:95], v144, s[44:45] offset:192
	s_add_u32 s44, s44, 0x10000
	s_addc_u32 s45, s45, 0
	global_load_dwordx4 v[96:99], v144, s[44:45] offset:0
	global_load_dwordx4 v[100:103], v144, s[44:45] offset:64
	global_load_dwordx4 v[104:107], v144, s[44:45] offset:128
	global_load_dwordx4 v[108:111], v144, s[44:45] offset:192
	s_add_u32 s44, s44, 0x10000
	s_addc_u32 s45, s45, 0
	global_load_dwordx4 v[112:115], v144, s[44:45] offset:0
	global_load_dwordx4 v[116:119], v144, s[44:45] offset:64
	global_load_dwordx4 v[120:123], v144, s[44:45] offset:128
	global_load_dwordx4 v[124:127], v144, s[44:45] offset:192
	s_waitcnt vmcnt(12)
	v_fmac_f32_e32 v64, v200, v0
	v_fmac_f32_e32 v65, v201, v1
	v_fmac_f32_e32 v66, v202, v2
	v_fmac_f32_e32 v67, v203, v3
	v_fmac_f32_e32 v68, v204, v4
	v_fmac_f32_e32 v69, v205, v5
	v_fmac_f32_e32 v70, v206, v6
	v_fmac_f32_e32 v71, v207, v7
	v_fmac_f32_e32 v72, v208, v8
	v_fmac_f32_e32 v73, v209, v9
	v_fmac_f32_e32 v74, v210, v10
	v_fmac_f32_e32 v75, v211, v11
	v_fmac_f32_e32 v76, v212, v12
	v_fmac_f32_e32 v77, v213, v13
	v_fmac_f32_e32 v78, v214, v14
	v_fmac_f32_e32 v79, v215, v15
	s_waitcnt vmcnt(8)
	v_fmac_f32_e32 v80, v200, v16
	v_fmac_f32_e32 v81, v201, v17
	v_fmac_f32_e32 v82, v202, v18
	v_fmac_f32_e32 v83, v203, v19
	v_fmac_f32_e32 v84, v204, v20
	v_fmac_f32_e32 v85, v205, v21
	v_fmac_f32_e32 v86, v206, v22
	v_fmac_f32_e32 v87, v207, v23
	v_fmac_f32_e32 v88, v208, v24
	v_fmac_f32_e32 v89, v209, v25
	v_fmac_f32_e32 v90, v210, v26
	v_fmac_f32_e32 v91, v211, v27
	v_fmac_f32_e32 v92, v212, v28
	v_fmac_f32_e32 v93, v213, v29
	v_fmac_f32_e32 v94, v214, v30
	v_fmac_f32_e32 v95, v215, v31
	s_waitcnt vmcnt(4)
	v_fmac_f32_e32 v96, v200, v32
	v_fmac_f32_e32 v97, v201, v33
	v_fmac_f32_e32 v98, v202, v34
	v_fmac_f32_e32 v99, v203, v35
	v_fmac_f32_e32 v100, v204, v36
	v_fmac_f32_e32 v101, v205, v37
	v_fmac_f32_e32 v102, v206, v38
	v_fmac_f32_e32 v103, v207, v39
	v_fmac_f32_e32 v104, v208, v40
	v_fmac_f32_e32 v105, v209, v41
	v_fmac_f32_e32 v106, v210, v42
	v_fmac_f32_e32 v107, v211, v43
	v_fmac_f32_e32 v108, v212, v44
	v_fmac_f32_e32 v109, v213, v45
	v_fmac_f32_e32 v110, v214, v46
	v_fmac_f32_e32 v111, v215, v47
	s_waitcnt vmcnt(0)
	v_fmac_f32_e32 v112, v200, v48
	v_fmac_f32_e32 v113, v201, v49
	v_fmac_f32_e32 v114, v202, v50
	v_fmac_f32_e32 v115, v203, v51
	v_fmac_f32_e32 v116, v204, v52
	v_fmac_f32_e32 v117, v205, v53
	v_fmac_f32_e32 v118, v206, v54
	v_fmac_f32_e32 v119, v207, v55
	v_fmac_f32_e32 v120, v208, v56
	v_fmac_f32_e32 v121, v209, v57
	v_fmac_f32_e32 v122, v210, v58
	v_fmac_f32_e32 v123, v211, v59
	v_fmac_f32_e32 v124, v212, v60
	v_fmac_f32_e32 v125, v213, v61
	v_fmac_f32_e32 v126, v214, v62
	v_fmac_f32_e32 v127, v215, v63
	global_store_dwordx4 v144, v[64:67], s[26:27] offset:0
	global_store_dwordx4 v144, v[68:71], s[26:27] offset:64
	global_store_dwordx4 v144, v[72:75], s[26:27] offset:128
	global_store_dwordx4 v144, v[76:79], s[26:27] offset:192
	s_add_u32 s26, s26, 0x10000
	s_addc_u32 s27, s27, 0
	global_store_dwordx4 v144, v[80:83], s[26:27] offset:0
	global_store_dwordx4 v144, v[84:87], s[26:27] offset:64
	global_store_dwordx4 v144, v[88:91], s[26:27] offset:128
	global_store_dwordx4 v144, v[92:95], s[26:27] offset:192
	s_add_u32 s26, s26, 0x10000
	s_addc_u32 s27, s27, 0
	global_store_dwordx4 v144, v[96:99], s[26:27] offset:0
	global_store_dwordx4 v144, v[100:103], s[26:27] offset:64
	global_store_dwordx4 v144, v[104:107], s[26:27] offset:128
	global_store_dwordx4 v144, v[108:111], s[26:27] offset:192
	s_add_u32 s26, s26, 0x10000
	s_addc_u32 s27, s27, 0
	global_store_dwordx4 v144, v[112:115], s[26:27] offset:0
	global_store_dwordx4 v144, v[116:119], s[26:27] offset:64
	global_store_dwordx4 v144, v[120:123], s[26:27] offset:128
	global_store_dwordx4 v144, v[124:127], s[26:27] offset:192
	v_mov_b32_e32 v0, 0
	v_mov_b32_e32 v1, 0
	v_mov_b32_e32 v2, 0
	v_mov_b32_e32 v3, 0
	v_mov_b32_e32 v4, 0
	v_mov_b32_e32 v5, 0
	v_mov_b32_e32 v6, 0
	v_mov_b32_e32 v7, 0
	v_mov_b32_e32 v8, 0
	v_mov_b32_e32 v9, 0
	v_mov_b32_e32 v10, 0
	v_mov_b32_e32 v11, 0
	v_mov_b32_e32 v12, 0
	v_mov_b32_e32 v13, 0
	v_mov_b32_e32 v14, 0
	v_mov_b32_e32 v15, 0
	v_mov_b32_e32 v16, 0
	v_mov_b32_e32 v17, 0
	v_mov_b32_e32 v18, 0
	v_mov_b32_e32 v19, 0
	v_mov_b32_e32 v20, 0
	v_mov_b32_e32 v21, 0
	v_mov_b32_e32 v22, 0
	v_mov_b32_e32 v23, 0
	v_mov_b32_e32 v24, 0
	v_mov_b32_e32 v25, 0
	v_mov_b32_e32 v26, 0
	v_mov_b32_e32 v27, 0
	v_mov_b32_e32 v28, 0
	v_mov_b32_e32 v29, 0
	v_mov_b32_e32 v30, 0
	v_mov_b32_e32 v31, 0
	v_mov_b32_e32 v32, 0
	v_mov_b32_e32 v33, 0
	v_mov_b32_e32 v34, 0
	v_mov_b32_e32 v35, 0
	v_mov_b32_e32 v36, 0
	v_mov_b32_e32 v37, 0
	v_mov_b32_e32 v38, 0
	v_mov_b32_e32 v39, 0
	v_mov_b32_e32 v40, 0
	v_mov_b32_e32 v41, 0
	v_mov_b32_e32 v42, 0
	v_mov_b32_e32 v43, 0
	v_mov_b32_e32 v44, 0
	v_mov_b32_e32 v45, 0
	v_mov_b32_e32 v46, 0
	v_mov_b32_e32 v47, 0
	v_mov_b32_e32 v48, 0
	v_mov_b32_e32 v49, 0
	v_mov_b32_e32 v50, 0
	v_mov_b32_e32 v51, 0
	v_mov_b32_e32 v52, 0
	v_mov_b32_e32 v53, 0
	v_mov_b32_e32 v54, 0
	v_mov_b32_e32 v55, 0
	v_mov_b32_e32 v56, 0
	v_mov_b32_e32 v57, 0
	v_mov_b32_e32 v58, 0
	v_mov_b32_e32 v59, 0
	v_mov_b32_e32 v60, 0
	v_mov_b32_e32 v61, 0
	v_mov_b32_e32 v62, 0
	v_mov_b32_e32 v63, 0
	s_add_u32 s52, s52, 1
	s_cmp_lt_u32 s52, 2
	s_cbranch_scc1 .Loutp_tile
	s_waitcnt vmcnt(0) lgkmcnt(0)
	s_barrier
	ds_write_b128 v145, v[252:255] offset:40960
	s_waitcnt lgkmcnt(0)
	s_barrier
	s_mov_b64 s[52:53], 0

; template <int NI> ...
;     ...
;   G_LOAD(a0, b0, 0);
;   G_LOAD(a1, b1, 32);
;   __syncthreads();
;   G_WRITE(a0, b0, 0);
;   __syncthreads();
;   for (int kt = 0; kt < nk; kt += 2) {
;     G_LOAD(a0, b0, min((kt + 2) * 32, klast));
;     G_COMPUTE(0);
;     G_WRITE(a1, b1, 1);
;     __syncthreads();
;     G_LOAD(a1, b1, min((kt + 3) * 32, klast));
;     G_COMPUTE(1);
;     G_WRITE(a0, b0, 0);
;     __syncthreads();
.Lmlp1_pair:
	s_cmp_eq_u32 s45, 14
	s_cselect_b64 s[12:13], s[24:25], s[12:13]
	s_add_u32 s50, s8, s63
	s_add_u32 m0, s50, 0x0
	s_nop 0
	global_load_lds_dwordx4 v236, s[12:13]
	s_add_u32 m0, s50, 0x400
	s_nop 0
	global_load_lds_dwordx4 v237, s[12:13]
	s_add_u32 m0, s50, 0x800
	s_nop 0
	global_load_lds_dwordx4 v238, s[12:13]
	s_add_u32 m0, s50, 0xc00
	s_nop 0
	global_load_lds_dwordx4 v239, s[12:13]
	s_add_u32 s12, s12, 128
	s_addc_u32 s13, s13, 0
	v_add_u32_e32 v129, s57, v249
	v_add_u32_e32 v131, s58, v251
	s_waitcnt lgkmcnt(0)
	v_mfma_f32_16x16x32_bf16 v[0:3], v[184:187], v[168:171], v[0:3]
	ds_read_b128 v[200:203], v129 offset:0
	v_mfma_f32_16x16x32_bf16 v[4:7], v[188:191], v[168:171], v[4:7]
	ds_read_b128 v[216:219], v131 offset:0
	v_mfma_f32_16x16x32_bf16 v[8:11], v[192:195], v[168:171], v[8:11]
	ds_read_b128 v[204:207], v129 offset:2048
	v_mfma_f32_16x16x32_bf16 v[12:15], v[196:199], v[168:171], v[12:15]
	ds_read_b128 v[220:223], v131 offset:512
	v_mfma_f32_16x16x32_bf16 v[16:19], v[184:187], v[172:175], v[16:19]
	ds_read_b128 v[208:211], v129 offset:4096
	v_mfma_f32_16x16x32_bf16 v[20:23], v[188:191], v[172:175], v[20:23]
	ds_read_b128 v[228:231], v131 offset:1024
	v_mfma_f32_16x16x32_bf16 v[24:27], v[192:195], v[172:175], v[24:27]
	ds_read_b128 v[212:215], v129 offset:6144
	v_mfma_f32_16x16x32_bf16 v[28:31], v[196:199], v[172:175], v[28:31]
	ds_read_b128 v[232:235], v131 offset:1536
	v_mfma_f32_16x16x32_bf16 v[32:35], v[184:187], v[176:179], v[32:35]
	v_mfma_f32_16x16x32_bf16 v[36:39], v[188:191], v[176:179], v[36:39]
	v_mfma_f32_16x16x32_bf16 v[40:43], v[192:195], v[176:179], v[40:43]
	v_mfma_f32_16x16x32_bf16 v[44:47], v[196:199], v[176:179], v[44:47]
	v_mfma_f32_16x16x32_bf16 v[48:51], v[184:187], v[180:183], v[48:51]
	v_mfma_f32_16x16x32_bf16 v[52:55], v[188:191], v[180:183], v[52:55]
	v_mfma_f32_16x16x32_bf16 v[56:59], v[192:195], v[180:183], v[56:59]
	v_mfma_f32_16x16x32_bf16 v[60:63], v[196:199], v[180:183], v[60:63]
	s_waitcnt vmcnt(4) lgkmcnt(0)
	s_barrier
	s_cmp_eq_u32 s45, 14
	s_cselect_b64 s[16:17], s[26:27], s[16:17]
	s_add_u32 s50, s8, s57
	s_add_u32 m0, s50, 0x0
	s_nop 0
	global_load_lds_dwordx4 v240, s[16:17]
	s_add_u32 m0, s50, 0x400
	s_nop 0
	global_load_lds_dwordx4 v241, s[16:17]
	s_add_u32 m0, s50, 0x800
	s_nop 0
	global_load_lds_dwordx4 v242, s[16:17]
	s_add_u32 m0, s50, 0xc00
	s_nop 0
	global_load_lds_dwordx4 v243, s[16:17]
	s_add_u32 s16, s16, 128
	s_addc_u32 s17, s17, 0
	v_add_u32_e32 v128, s59, v248
	v_add_u32_e32 v130, s62, v250
	v_mfma_f32_16x16x32_bf16 v[0:3], v[216:219], v[200:203], v[0:3]
	ds_read_b128 v[168:171], v128 offset:0
	v_mfma_f32_16x16x32_bf16 v[4:7], v[220:223], v[200:203], v[4:7]
	ds_read_b128 v[184:187], v130 offset:0
	v_mfma_f32_16x16x32_bf16 v[8:11], v[228:231], v[200:203], v[8:11]
	ds_read_b128 v[172:175], v128 offset:2048
	v_mfma_f32_16x16x32_bf16 v[12:15], v[232:235], v[200:203], v[12:15]
	ds_read_b128 v[188:191], v130 offset:512
	v_mfma_f32_16x16x32_bf16 v[16:19], v[216:219], v[204:207], v[16:19]
	ds_read_b128 v[176:179], v128 offset:4096
	v_mfma_f32_16x16x32_bf16 v[20:23], v[220:223], v[204:207], v[20:23]
	ds_read_b128 v[192:195], v130 offset:1024
	v_mfma_f32_16x16x32_bf16 v[24:27], v[228:231], v[204:207], v[24:27]
	ds_read_b128 v[180:183], v128 offset:6144
	v_mfma_f32_16x16x32_bf16 v[28:31], v[232:235], v[204:207], v[28:31]
	ds_read_b128 v[196:199], v130 offset:1536
	v_mfma_f32_16x16x32_bf16 v[32:35], v[216:219], v[208:211], v[32:35]
	v_mfma_f32_16x16x32_bf16 v[36:39], v[220:223], v[208:211], v[36:39]
	v_mfma_f32_16x16x32_bf16 v[40:43], v[228:231], v[208:211], v[40:43]
	v_mfma_f32_16x16x32_bf16 v[44:47], v[232:235], v[208:211], v[44:47]
	v_mfma_f32_16x16x32_bf16 v[48:51], v[216:219], v[212:215], v[48:51]
	v_mfma_f32_16x16x32_bf16 v[52:55], v[220:223], v[212:215], v[52:55]
	v_mfma_f32_16x16x32_bf16 v[56:59], v[228:231], v[212:215], v[56:59]
	v_mfma_f32_16x16x32_bf16 v[60:63], v[232:235], v[212:215], v[60:63]
	s_mov_b32 s51, s57
	s_mov_b32 s54, s58
	s_mov_b32 s57, s59
	s_mov_b32 s58, s62
	s_mov_b32 s59, s63
	s_mov_b32 s62, s51
	s_mov_b32 s63, s54
	s_add_u32 s45, s45, 1
	s_cmp_lt_u32 s45, 16
	s_cbranch_scc1 .Lmlp1_pair
; __device__ void phase_mlp1(CParams& p, int l, int tm, int tn, char* smem) {
;     ...
;   EPI_LOOP({
;     float a = fmaxf(acc[mi][ni][j], 0.f);
;     p.hidden[(size_t)(row0 + rl) * DFF + col0 + cl] = f2bf(a * a);
;   })
	s_nop 15
	s_nop 7
	v_max_f32_e32 v0, 0, v0
	v_max_f32_e32 v1, 0, v1
	v_max_f32_e32 v2, 0, v2
	v_max_f32_e32 v3, 0, v3
	v_max_f32_e32 v4, 0, v4
	v_max_f32_e32 v5, 0, v5
	v_max_f32_e32 v6, 0, v6
	v_max_f32_e32 v7, 0, v7
	v_max_f32_e32 v8, 0, v8
	v_max_f32_e32 v9, 0, v9
	v_max_f32_e32 v10, 0, v10
	v_max_f32_e32 v11, 0, v11
	v_max_f32_e32 v12, 0, v12
	v_max_f32_e32 v13, 0, v13
	v_max_f32_e32 v14, 0, v14
	v_max_f32_e32 v15, 0, v15
	v_mul_f32_e32 v0, v0, v0
	v_mul_f32_e32 v1, v1, v1
	v_mul_f32_e32 v2, v2, v2
	v_mul_f32_e32 v3, v3, v3
	v_mul_f32_e32 v4, v4, v4
	v_mul_f32_e32 v5, v5, v5
	v_mul_f32_e32 v6, v6, v6
	v_mul_f32_e32 v7, v7, v7
	v_mul_f32_e32 v8, v8, v8
	v_mul_f32_e32 v9, v9, v9
	v_mul_f32_e32 v10, v10, v10
	v_mul_f32_e32 v11, v11, v11
	v_mul_f32_e32 v12, v12, v12
	v_mul_f32_e32 v13, v13, v13
	v_mul_f32_e32 v14, v14, v14
	v_mul_f32_e32 v15, v15, v15
	v_cvt_pk_bf16_f32 v64, v0, v1
	v_cvt_pk_bf16_f32 v65, v2, v3
	v_cvt_pk_bf16_f32 v66, v4, v5
	v_cvt_pk_bf16_f32 v67, v6, v7
	global_store_dwordx4 v144, v[64:67], s[42:43] offset:0
	v_cvt_pk_bf16_f32 v68, v8, v9
	v_cvt_pk_bf16_f32 v69, v10, v11
	v_cvt_pk_bf16_f32 v70, v12, v13
	v_cvt_pk_bf16_f32 v71, v14, v15
	global_store_dwordx4 v144, v[68:71], s[42:43] offset:16
	s_add_u32 s42, s42, 0x20000
	s_addc_u32 s43, s43, 0
	v_max_f32_e32 v16, 0, v16
	v_max_f32_e32 v17, 0, v17
	v_max_f32_e32 v18, 0, v18
	v_max_f32_e32 v19, 0, v19
	v_max_f32_e32 v20, 0, v20
	v_max_f32_e32 v21, 0, v21
	v_max_f32_e32 v22, 0, v22
	v_max_f32_e32 v23, 0, v23
	v_max_f32_e32 v24, 0, v24
	v_max_f32_e32 v25, 0, v25
	v_max_f32_e32 v26, 0, v26
	v_max_f32_e32 v27, 0, v27
	v_max_f32_e32 v28, 0, v28
	v_max_f32_e32 v29, 0, v29
	v_max_f32_e32 v30, 0, v30
	v_max_f32_e32 v31, 0, v31
	v_mul_f32_e32 v16, v16, v16
	v_mul_f32_e32 v17, v17, v17
	v_mul_f32_e32 v18, v18, v18
	v_mul_f32_e32 v19, v19, v19
	v_mul_f32_e32 v20, v20, v20
	v_mul_f32_e32 v21, v21, v21
	v_mul_f32_e32 v22, v22, v22
	v_mul_f32_e32 v23, v23, v23
	v_mul_f32_e32 v24, v24, v24
	v_mul_f32_e32 v25, v25, v25
	v_mul_f32_e32 v26, v26, v26
	v_mul_f32_e32 v27, v27, v27
	v_mul_f32_e32 v28, v28, v28
	v_mul_f32_e32 v29, v29, v29
	v_mul_f32_e32 v30, v30, v30
	v_mul_f32_e32 v31, v31, v31
	v_cvt_pk_bf16_f32 v72, v16, v17
	v_cvt_pk_bf16_f32 v73, v18, v19
	v_cvt_pk_bf16_f32 v74, v20, v21
	v_cvt_pk_bf16_f32 v75, v22, v23
	global_store_dwordx4 v144, v[72:75], s[42:43] offset:0
	v_cvt_pk_bf16_f32 v76, v24, v25
	v_cvt_pk_bf16_f32 v77, v26, v27
	v_cvt_pk_bf16_f32 v78, v28, v29
	v_cvt_pk_bf16_f32 v79, v30, v31
	global_store_dwordx4 v144, v[76:79], s[42:43] offset:16
	s_add_u32 s42, s42, 0x20000
	s_addc_u32 s43, s43, 0
	v_max_f32_e32 v32, 0, v32
	v_max_f32_e32 v33, 0, v33
	v_max_f32_e32 v34, 0, v34
	v_max_f32_e32 v35, 0, v35
	v_max_f32_e32 v36, 0, v36
	v_max_f32_e32 v37, 0, v37
	v_max_f32_e32 v38, 0, v38
	v_max_f32_e32 v39, 0, v39
	v_max_f32_e32 v40, 0, v40
	v_max_f32_e32 v41, 0, v41
	v_max_f32_e32 v42, 0, v42
	v_max_f32_e32 v43, 0, v43
	v_max_f32_e32 v44, 0, v44
	v_max_f32_e32 v45, 0, v45
	v_max_f32_e32 v46, 0, v46
	v_max_f32_e32 v47, 0, v47
	v_mul_f32_e32 v32, v32, v32
	v_mul_f32_e32 v33, v33, v33
	v_mul_f32_e32 v34, v34, v34
	v_mul_f32_e32 v35, v35, v35
	v_mul_f32_e32 v36, v36, v36
	v_mul_f32_e32 v37, v37, v37
	v_mul_f32_e32 v38, v38, v38
	v_mul_f32_e32 v39, v39, v39
	v_mul_f32_e32 v40, v40, v40
	v_mul_f32_e32 v41, v41, v41
	v_mul_f32_e32 v42, v42, v42
	v_mul_f32_e32 v43, v43, v43
	v_mul_f32_e32 v44, v44, v44
	v_mul_f32_e32 v45, v45, v45
	v_mul_f32_e32 v46, v46, v46
	v_mul_f32_e32 v47, v47, v47
	v_cvt_pk_bf16_f32 v80, v32, v33
	v_cvt_pk_bf16_f32 v81, v34, v35
	v_cvt_pk_bf16_f32 v82, v36, v37
	v_cvt_pk_bf16_f32 v83, v38, v39
	global_store_dwordx4 v144, v[80:83], s[42:43] offset:0
	v_cvt_pk_bf16_f32 v84, v40, v41
	v_cvt_pk_bf16_f32 v85, v42, v43
	v_cvt_pk_bf16_f32 v86, v44, v45
	v_cvt_pk_bf16_f32 v87, v46, v47
	global_store_dwordx4 v144, v[84:87], s[42:43] offset:16
	s_add_u32 s42, s42, 0x20000
	s_addc_u32 s43, s43, 0
	v_max_f32_e32 v48, 0, v48
	v_max_f32_e32 v49, 0, v49
	v_max_f32_e32 v50, 0, v50
	v_max_f32_e32 v51, 0, v51
	v_max_f32_e32 v52, 0, v52
	v_max_f32_e32 v53, 0, v53
	v_max_f32_e32 v54, 0, v54
	v_max_f32_e32 v55, 0, v55
	v_max_f32_e32 v56, 0, v56
	v_max_f32_e32 v57, 0, v57
	v_max_f32_e32 v58, 0, v58
	v_max_f32_e32 v59, 0, v59
	v_max_f32_e32 v60, 0, v60
	v_max_f32_e32 v61, 0, v61
	v_max_f32_e32 v62, 0, v62
	v_max_f32_e32 v63, 0, v63
	v_mul_f32_e32 v48, v48, v48
	v_mul_f32_e32 v49, v49, v49
	v_mul_f32_e32 v50, v50, v50
	v_mul_f32_e32 v51, v51, v51
	v_mul_f32_e32 v52, v52, v52
	v_mul_f32_e32 v53, v53, v53
	v_mul_f32_e32 v54, v54, v54
	v_mul_f32_e32 v55, v55, v55
	v_mul_f32_e32 v56, v56, v56
	v_mul_f32_e32 v57, v57, v57
	v_mul_f32_e32 v58, v58, v58
	v_mul_f32_e32 v59, v59, v59
	v_mul_f32_e32 v60, v60, v60
	v_mul_f32_e32 v61, v61, v61
	v_mul_f32_e32 v62, v62, v62
	v_mul_f32_e32 v63, v63, v63
	v_cvt_pk_bf16_f32 v88, v48, v49
	v_cvt_pk_bf16_f32 v89, v50, v51
	v_cvt_pk_bf16_f32 v90, v52, v53
	v_cvt_pk_bf16_f32 v91, v54, v55
	global_store_dwordx4 v144, v[88:91], s[42:43] offset:0
	v_cvt_pk_bf16_f32 v92, v56, v57
	v_cvt_pk_bf16_f32 v93, v58, v59
	v_cvt_pk_bf16_f32 v94, v60, v61
	v_cvt_pk_bf16_f32 v95, v62, v63
	global_store_dwordx4 v144, v[92:95], s[42:43] offset:16
	v_mov_b32_e32 v0, 0
	v_mov_b32_e32 v1, 0
	v_mov_b32_e32 v2, 0
	v_mov_b32_e32 v3, 0
	v_mov_b32_e32 v4, 0
	v_mov_b32_e32 v5, 0
	v_mov_b32_e32 v6, 0
	v_mov_b32_e32 v7, 0
	v_mov_b32_e32 v8, 0
	v_mov_b32_e32 v9, 0
	v_mov_b32_e32 v10, 0
	v_mov_b32_e32 v11, 0
	v_mov_b32_e32 v12, 0
	v_mov_b32_e32 v13, 0
	v_mov_b32_e32 v14, 0
	v_mov_b32_e32 v15, 0
	v_mov_b32_e32 v16, 0
	v_mov_b32_e32 v17, 0
	v_mov_b32_e32 v18, 0
	v_mov_b32_e32 v19, 0
	v_mov_b32_e32 v20, 0
	v_mov_b32_e32 v21, 0
	v_mov_b32_e32 v22, 0
	v_mov_b32_e32 v23, 0
	v_mov_b32_e32 v24, 0
	v_mov_b32_e32 v25, 0
	v_mov_b32_e32 v26, 0
	v_mov_b32_e32 v27, 0
	v_mov_b32_e32 v28, 0
	v_mov_b32_e32 v29, 0
	v_mov_b32_e32 v30, 0
	v_mov_b32_e32 v31, 0
	v_mov_b32_e32 v32, 0
	v_mov_b32_e32 v33, 0
	v_mov_b32_e32 v34, 0
	v_mov_b32_e32 v35, 0
	v_mov_b32_e32 v36, 0
	v_mov_b32_e32 v37, 0
	v_mov_b32_e32 v38, 0
	v_mov_b32_e32 v39, 0
	v_mov_b32_e32 v40, 0
	v_mov_b32_e32 v41, 0
	v_mov_b32_e32 v42, 0
	v_mov_b32_e32 v43, 0
	v_mov_b32_e32 v44, 0
	v_mov_b32_e32 v45, 0
	v_mov_b32_e32 v46, 0
	v_mov_b32_e32 v47, 0
	v_mov_b32_e32 v48, 0
	v_mov_b32_e32 v49, 0
	v_mov_b32_e32 v50, 0
	v_mov_b32_e32 v51, 0
	v_mov_b32_e32 v52, 0
	v_mov_b32_e32 v53, 0
	v_mov_b32_e32 v54, 0
	v_mov_b32_e32 v55, 0
	v_mov_b32_e32 v56, 0
	v_mov_b32_e32 v57, 0
	v_mov_b32_e32 v58, 0
	v_mov_b32_e32 v59, 0
	v_mov_b32_e32 v60, 0
	v_mov_b32_e32 v61, 0
	v_mov_b32_e32 v62, 0
	v_mov_b32_e32 v63, 0
	s_add_u32 s44, s44, 1
	s_cmp_lt_u32 s44, 8
	s_cbranch_scc1 .Lmlp1_tile
	s_waitcnt vmcnt(0) lgkmcnt(0)
	s_barrier
	ds_write_b128 v145, v[252:255] offset:40960
	s_waitcnt lgkmcnt(0)
	s_barrier

; template <int NI> ...
;     ...
;   G_LOAD(a0, b0, 0);
;   G_LOAD(a1, b1, 32);
;   __syncthreads();
;   G_WRITE(a0, b0, 0);
;   __syncthreads();
;   for (int kt = 0; kt < nk; kt += 2) {
;     G_LOAD(a0, b0, min((kt + 2) * 32, klast));
;     G_COMPUTE(0);
;     G_WRITE(a1, b1, 1);
;     __syncthreads();
;     G_LOAD(a1, b1, min((kt + 3) * 32, klast));
;     G_COMPUTE(1);
;     G_WRITE(a0, b0, 0);
;     __syncthreads();
.Lmlp2_pair:
	s_cmp_eq_u32 s54, 62
	s_cselect_b64 s[16:17], s[22:23], s[16:17]
	s_add_u32 s55, s4, s98
	s_add_u32 m0, s55, 0x0
	s_nop 0
	global_load_lds_dwordx4 v236, s[16:17]
	s_add_u32 m0, s55, 0x400
	s_nop 0
	global_load_lds_dwordx4 v237, s[16:17]
	s_add_u32 m0, s55, 0x800
	s_nop 0
	global_load_lds_dwordx4 v238, s[16:17]
	s_add_u32 m0, s55, 0xc00
	s_nop 0
	global_load_lds_dwordx4 v239, s[16:17]
	s_add_u32 s16, s16, 128
	s_addc_u32 s17, s17, 0
	v_add_u32_e32 v129, s62, v249
	v_add_u32_e32 v131, s63, v251
	s_waitcnt lgkmcnt(0)
	v_mfma_f32_16x16x32_bf16 v[0:3], v[184:187], v[168:171], v[0:3]
	ds_read_b128 v[200:203], v129 offset:0
	v_mfma_f32_16x16x32_bf16 v[4:7], v[188:191], v[168:171], v[4:7]
	ds_read_b128 v[216:219], v131 offset:0
	v_mfma_f32_16x16x32_bf16 v[8:11], v[192:195], v[168:171], v[8:11]
	ds_read_b128 v[204:207], v129 offset:2048
	v_mfma_f32_16x16x32_bf16 v[12:15], v[196:199], v[168:171], v[12:15]
	ds_read_b128 v[220:223], v131 offset:2048
	v_mfma_f32_16x16x32_bf16 v[16:19], v[184:187], v[172:175], v[16:19]
	ds_read_b128 v[208:211], v129 offset:4096
	v_mfma_f32_16x16x32_bf16 v[20:23], v[188:191], v[172:175], v[20:23]
	ds_read_b128 v[228:231], v131 offset:4096
	v_mfma_f32_16x16x32_bf16 v[24:27], v[192:195], v[172:175], v[24:27]
	ds_read_b128 v[212:215], v129 offset:6144
	v_mfma_f32_16x16x32_bf16 v[28:31], v[196:199], v[172:175], v[28:31]
	ds_read_b128 v[232:235], v131 offset:6144
	v_mfma_f32_16x16x32_bf16 v[32:35], v[184:187], v[176:179], v[32:35]
	v_mfma_f32_16x16x32_bf16 v[36:39], v[188:191], v[176:179], v[36:39]
	v_mfma_f32_16x16x32_bf16 v[40:43], v[192:195], v[176:179], v[40:43]
	v_mfma_f32_16x16x32_bf16 v[44:47], v[196:199], v[176:179], v[44:47]
	v_mfma_f32_16x16x32_bf16 v[48:51], v[184:187], v[180:183], v[48:51]
	v_mfma_f32_16x16x32_bf16 v[52:55], v[188:191], v[180:183], v[52:55]
	v_mfma_f32_16x16x32_bf16 v[56:59], v[192:195], v[180:183], v[56:59]
	v_mfma_f32_16x16x32_bf16 v[60:63], v[196:199], v[180:183], v[60:63]
	s_waitcnt vmcnt(4) lgkmcnt(0)
	s_barrier
	s_cmp_eq_u32 s54, 62
	s_cselect_b64 s[18:19], s[26:27], s[18:19]
	s_add_u32 s55, s4, s62
	s_add_u32 m0, s55, 0x0
	s_nop 0
	global_load_lds_dwordx4 v240, s[18:19]
	s_add_u32 m0, s55, 0x400
	s_nop 0
	global_load_lds_dwordx4 v241, s[18:19]
	s_add_u32 m0, s55, 0x800
	s_nop 0
	global_load_lds_dwordx4 v242, s[18:19]
	s_add_u32 m0, s55, 0xc00
	s_nop 0
	global_load_lds_dwordx4 v243, s[18:19]
	s_add_u32 s18, s18, 128
	s_addc_u32 s19, s19, 0
	v_add_u32_e32 v128, s92, v248
	v_add_u32_e32 v130, s93, v250
	v_mfma_f32_16x16x32_bf16 v[0:3], v[216:219], v[200:203], v[0:3]
	ds_read_b128 v[168:171], v128 offset:0
	v_mfma_f32_16x16x32_bf16 v[4:7], v[220:223], v[200:203], v[4:7]
	ds_read_b128 v[184:187], v130 offset:0
	v_mfma_f32_16x16x32_bf16 v[8:11], v[228:231], v[200:203], v[8:11]
	ds_read_b128 v[172:175], v128 offset:2048
	v_mfma_f32_16x16x32_bf16 v[12:15], v[232:235], v[200:203], v[12:15]
	ds_read_b128 v[188:191], v130 offset:2048
	v_mfma_f32_16x16x32_bf16 v[16:19], v[216:219], v[204:207], v[16:19]
	ds_read_b128 v[176:179], v128 offset:4096
	v_mfma_f32_16x16x32_bf16 v[20:23], v[220:223], v[204:207], v[20:23]
	ds_read_b128 v[192:195], v130 offset:4096
	v_mfma_f32_16x16x32_bf16 v[24:27], v[228:231], v[204:207], v[24:27]
	ds_read_b128 v[180:183], v128 offset:6144
	v_mfma_f32_16x16x32_bf16 v[28:31], v[232:235], v[204:207], v[28:31]
	ds_read_b128 v[196:199], v130 offset:6144
	v_mfma_f32_16x16x32_bf16 v[32:35], v[216:219], v[208:211], v[32:35]
	v_mfma_f32_16x16x32_bf16 v[36:39], v[220:223], v[208:211], v[36:39]
	v_mfma_f32_16x16x32_bf16 v[40:43], v[228:231], v[208:211], v[40:43]
	v_mfma_f32_16x16x32_bf16 v[44:47], v[232:235], v[208:211], v[44:47]
	v_mfma_f32_16x16x32_bf16 v[48:51], v[216:219], v[212:215], v[48:51]
	v_mfma_f32_16x16x32_bf16 v[52:55], v[220:223], v[212:215], v[52:55]
	v_mfma_f32_16x16x32_bf16 v[56:59], v[228:231], v[212:215], v[56:59]
	v_mfma_f32_16x16x32_bf16 v[60:63], v[232:235], v[212:215], v[60:63]
	s_mov_b32 s56, s62
	s_mov_b32 s57, s63
	s_mov_b32 s62, s92
	s_mov_b32 s63, s93
	s_mov_b32 s92, s98
	s_mov_b32 s93, s56
	s_mov_b32 s98, s57
	s_add_u32 s54, s54, 1
	s_cmp_lt_u32 s54, 64
	s_cbranch_scc1 .Lmlp2_pair
; __device__ void phase_proj_res(CParams& p, int l, int tm, int tn, char* smem, const bf16_t* A, int K,
;                                const bf16_t* Bt, int gate_off, float gscale) {
;     ...
;   const float* md = p.mod + ((size_t)l * 3 + modvec_of_tok(row0)) * 6144 + gate_off;
;   EPI_LOOP({
;     float* xp = xrow(p, row0 + rl) + col0 + cl;
;     *xp = *xp + gscale * md[col0 + cl] * acc[mi][ni][j];
;   })
	s_nop 15
	s_nop 7
	global_load_dwordx4 v[200:203], v132, s[52:53] offset:0
	global_load_dwordx4 v[204:207], v132, s[52:53] offset:64
	global_load_dwordx4 v[208:211], v132, s[52:53] offset:128
	global_load_dwordx4 v[212:215], v132, s[52:53] offset:192
	s_mov_b64 s[52:53], s[40:41]
	global_load_dwordx4 v[64:67], v144, s[52:53] offset:0
	global_load_dwordx4 v[68:71], v144, s[52:53] offset:64
	global_load_dwordx4 v[72:75], v144, s[52:53] offset:128
	global_load_dwordx4 v[76:79], v144, s[52:53] offset:192
	s_add_u32 s52, s52, 0x10000
	s_addc_u32 s53, s53, 0
	global_load_dwordx4 v[80:83], v144, s[52:53] offset:0
	global_load_dwordx4 v[84:87], v144, s[52:53] offset:64
	global_load_dwordx4 v[88:91], v144, s[52:53] offset:128
	global_load_dwordx4 v[92:95], v144, s[52:53] offset:192
	s_add_u32 s52, s52, 0x10000
	s_addc_u32 s53, s53, 0
	global_load_dwordx4 v[96:99], v144, s[52:53] offset:0
	global_load_dwordx4 v[100:103], v144, s[52:53] offset:64
	global_load_dwordx4 v[104:107], v144, s[52:53] offset:128
	global_load_dwordx4 v[108:111], v144, s[52:53] offset:192
	s_add_u32 s52, s52, 0x10000
	s_addc_u32 s53, s53, 0
	global_load_dwordx4 v[112:115], v144, s[52:53] offset:0
	global_load_dwordx4 v[116:119], v144, s[52:53] offset:64
	global_load_dwordx4 v[120:123], v144, s[52:53] offset:128
	global_load_dwordx4 v[124:127], v144, s[52:53] offset:192
	s_waitcnt vmcnt(12)
	v_fmac_f32_e32 v64, v200, v0
	v_fmac_f32_e32 v65, v201, v1
	v_fmac_f32_e32 v66, v202, v2
	v_fmac_f32_e32 v67, v203, v3
	v_fmac_f32_e32 v68, v204, v4
	v_fmac_f32_e32 v69, v205, v5
	v_fmac_f32_e32 v70, v206, v6
	v_fmac_f32_e32 v71, v207, v7
	v_fmac_f32_e32 v72, v208, v8
	v_fmac_f32_e32 v73, v209, v9
	v_fmac_f32_e32 v74, v210, v10
	v_fmac_f32_e32 v75, v211, v11
	v_fmac_f32_e32 v76, v212, v12
	v_fmac_f32_e32 v77, v213, v13
	v_fmac_f32_e32 v78, v214, v14
	v_fmac_f32_e32 v79, v215, v15
	s_waitcnt vmcnt(8)
	v_fmac_f32_e32 v80, v200, v16
	v_fmac_f32_e32 v81, v201, v17
	v_fmac_f32_e32 v82, v202, v18
	v_fmac_f32_e32 v83, v203, v19
	v_fmac_f32_e32 v84, v204, v20
	v_fmac_f32_e32 v85, v205, v21
	v_fmac_f32_e32 v86, v206, v22
	v_fmac_f32_e32 v87, v207, v23
	v_fmac_f32_e32 v88, v208, v24
	v_fmac_f32_e32 v89, v209, v25
	v_fmac_f32_e32 v90, v210, v26
	v_fmac_f32_e32 v91, v211, v27
	v_fmac_f32_e32 v92, v212, v28
	v_fmac_f32_e32 v93, v213, v29
	v_fmac_f32_e32 v94, v214, v30
	v_fmac_f32_e32 v95, v215, v31
	s_waitcnt vmcnt(4)
	v_fmac_f32_e32 v96, v200, v32
	v_fmac_f32_e32 v97, v201, v33
	v_fmac_f32_e32 v98, v202, v34
	v_fmac_f32_e32 v99, v203, v35
	v_fmac_f32_e32 v100, v204, v36
	v_fmac_f32_e32 v101, v205, v37
	v_fmac_f32_e32 v102, v206, v38
	v_fmac_f32_e32 v103, v207, v39
	v_fmac_f32_e32 v104, v208, v40
	v_fmac_f32_e32 v105, v209, v41
	v_fmac_f32_e32 v106, v210, v42
	v_fmac_f32_e32 v107, v211, v43
	v_fmac_f32_e32 v108, v212, v44
	v_fmac_f32_e32 v109, v213, v45
	v_fmac_f32_e32 v110, v214, v46
	v_fmac_f32_e32 v111, v215, v47
	s_waitcnt vmcnt(0)
	v_fmac_f32_e32 v112, v200, v48
	v_fmac_f32_e32 v113, v201, v49
	v_fmac_f32_e32 v114, v202, v50
	v_fmac_f32_e32 v115, v203, v51
	v_fmac_f32_e32 v116, v204, v52
	v_fmac_f32_e32 v117, v205, v53
	v_fmac_f32_e32 v118, v206, v54
	v_fmac_f32_e32 v119, v207, v55
	v_fmac_f32_e32 v120, v208, v56
	v_fmac_f32_e32 v121, v209, v57
	v_fmac_f32_e32 v122, v210, v58
	v_fmac_f32_e32 v123, v211, v59
	v_fmac_f32_e32 v124, v212, v60
	v_fmac_f32_e32 v125, v213, v61
	v_fmac_f32_e32 v126, v214, v62
	v_fmac_f32_e32 v127, v215, v63
	global_store_dwordx4 v144, v[64:67], s[40:41] offset:0
	global_store_dwordx4 v144, v[68:71], s[40:41] offset:64
	global_store_dwordx4 v144, v[72:75], s[40:41] offset:128
	global_store_dwordx4 v144, v[76:79], s[40:41] offset:192
	s_add_u32 s40, s40, 0x10000
	s_addc_u32 s41, s41, 0
	global_store_dwordx4 v144, v[80:83], s[40:41] offset:0
	global_store_dwordx4 v144, v[84:87], s[40:41] offset:64
	global_store_dwordx4 v144, v[88:91], s[40:41] offset:128
	global_store_dwordx4 v144, v[92:95], s[40:41] offset:192
	s_add_u32 s40, s40, 0x10000
	s_addc_u32 s41, s41, 0
	global_store_dwordx4 v144, v[96:99], s[40:41] offset:0
	global_store_dwordx4 v144, v[100:103], s[40:41] offset:64
	global_store_dwordx4 v144, v[104:107], s[40:41] offset:128
	global_store_dwordx4 v144, v[108:111], s[40:41] offset:192
	s_add_u32 s40, s40, 0x10000
	s_addc_u32 s41, s41, 0
	global_store_dwordx4 v144, v[112:115], s[40:41] offset:0
	global_store_dwordx4 v144, v[116:119], s[40:41] offset:64
	global_store_dwordx4 v144, v[120:123], s[40:41] offset:128
	global_store_dwordx4 v144, v[124:127], s[40:41] offset:192
	v_mov_b32_e32 v0, 0
	v_mov_b32_e32 v1, 0
	v_mov_b32_e32 v2, 0
	v_mov_b32_e32 v3, 0
	v_mov_b32_e32 v4, 0
	v_mov_b32_e32 v5, 0
	v_mov_b32_e32 v6, 0
	v_mov_b32_e32 v7, 0
	v_mov_b32_e32 v8, 0
	v_mov_b32_e32 v9, 0
	v_mov_b32_e32 v10, 0
	v_mov_b32_e32 v11, 0
	v_mov_b32_e32 v12, 0
	v_mov_b32_e32 v13, 0
	v_mov_b32_e32 v14, 0
	v_mov_b32_e32 v15, 0
	v_mov_b32_e32 v16, 0
	v_mov_b32_e32 v17, 0
	v_mov_b32_e32 v18, 0
	v_mov_b32_e32 v19, 0
	v_mov_b32_e32 v20, 0
	v_mov_b32_e32 v21, 0
	v_mov_b32_e32 v22, 0
	v_mov_b32_e32 v23, 0
	v_mov_b32_e32 v24, 0
	v_mov_b32_e32 v25, 0
	v_mov_b32_e32 v26, 0
	v_mov_b32_e32 v27, 0
	v_mov_b32_e32 v28, 0
	v_mov_b32_e32 v29, 0
	v_mov_b32_e32 v30, 0
	v_mov_b32_e32 v31, 0
	v_mov_b32_e32 v32, 0
	v_mov_b32_e32 v33, 0
	v_mov_b32_e32 v34, 0
	v_mov_b32_e32 v35, 0
	v_mov_b32_e32 v36, 0
	v_mov_b32_e32 v37, 0
	v_mov_b32_e32 v38, 0
	v_mov_b32_e32 v39, 0
	v_mov_b32_e32 v40, 0
	v_mov_b32_e32 v41, 0
	v_mov_b32_e32 v42, 0
	v_mov_b32_e32 v43, 0
	v_mov_b32_e32 v44, 0
	v_mov_b32_e32 v45, 0
	v_mov_b32_e32 v46, 0
	v_mov_b32_e32 v47, 0
	v_mov_b32_e32 v48, 0
	v_mov_b32_e32 v49, 0
	v_mov_b32_e32 v50, 0
	v_mov_b32_e32 v51, 0
	v_mov_b32_e32 v52, 0
	v_mov_b32_e32 v53, 0
	v_mov_b32_e32 v54, 0
	v_mov_b32_e32 v55, 0
	v_mov_b32_e32 v56, 0
	v_mov_b32_e32 v57, 0
	v_mov_b32_e32 v58, 0
	v_mov_b32_e32 v59, 0
	v_mov_b32_e32 v60, 0
	v_mov_b32_e32 v61, 0
	v_mov_b32_e32 v62, 0
	v_mov_b32_e32 v63, 0
	s_add_u32 s32, s32, 1
	s_cmp_lt_u32 s32, 2
	s_cbranch_scc1 .Lmlp2_tile
	s_waitcnt vmcnt(0) lgkmcnt(0)
	s_barrier
	ds_write_b128 v145, v[252:255] offset:40960
	s_waitcnt lgkmcnt(0)
	s_barrier
	s_mov_b64 s[50:51], 0
